# packed fp32 ops no longer read SGPR pairs: NSA ALiBi-init pk_fma takes its constants from VGPR pairs set at the unit head, scan_precompute wave-sum pk_add issued as two v_add
# speedup vs baseline: 1.0139x; 1.0127x over previous
; #define LAS __attribute__((address_space(3)))
; __device__ __forceinline__ unsigned pk2(float lo, float hi) { f32x2 v = {lo, hi}; bf16x2_t b = __builtin_convertvector(v, bf16x2_t); return __builtin_bit_cast(unsigned, b); }
; __device__ __forceinline__ float wsum64(float x) {
;     x = allred16(x);
;     const float t0 = __int_as_float(__builtin_amdgcn_readlane(__float_as_int(x), 0)), t1 = __int_as_float(__builtin_amdgcn_readlane(__float_as_int(x), 16));
;     const float t2 = __int_as_float(__builtin_amdgcn_readlane(__float_as_int(x), 32)), t3 = __int_as_float(__builtin_amdgcn_readlane(__float_as_int(x), 48));
;     return (t0 + t1) + (t2 + t3); }
; __device__ __forceinline__ void s2_produce(LAS unsigned char* CB, LAS unsigned char* PSb, LAS unsigned char* APTp, const unsigned (&rw)[16][5], const unsigned (&pv3)[3], int lane,
;         float mur, float muk, float muv, float w0v, float a0v, float kkv, float kav) {
;     ...
;     for (int t = 0; t < 16; ++t) {
;         const float cr = __uint_as_float(rw[t][0] << 16), ck = __uint_as_float(rw[t][1] << 16), cv = __uint_as_float(rw[t][2] << 16);
;         const float lw = __uint_as_float(rw[t][3] << 16), la = __uint_as_float(rw[t][4] << 16);
;         const float r = cr + (pr - cr) * mur, k = ck + (pk - ck) * muk, v = cv + (pv - cv) * muv;
;         pr = cr; pk = ck; pv = cv;
;         const float aic = sigm(a0v + la);
;         const float lam = -0.6065306597126334f * __builtin_amdgcn_rcpf(1.f + __expf(-(w0v + lw)));
;         const float kk = k * kkv; const float ss = wsum64(kk * kk);
;         const float kn = kk * rsqrtf(fmaxf(ss, 1e-24f));
;         const float k2 = k * (1.f + (aic - 1.f) * kav);
;         Lam += lam;
;         const float eL = __expf(Lam), eLm = __builtin_amdgcn_rcpf(eL);
;         const float at = -kn * eP, rt = r * eL, bt = kn * aic * eLm, kt = k2 * eLm;
;         eP = eL;
;         *(LAS bf16_t*)(PSb + S2_AT + t * 144 + lane * 2) = f2bf(at);
;         *(LAS bf16_t*)(PSb + S2_BT + t * 144 + lane * 2) = f2bf(bt);
;         *(LAS bf16_t*)(PSb + S2_KT + t * 144 + lane * 2) = f2bf(kt);
;         *(LAS bf16_t*)(CB + S2_RT + t * 144 + lane * 2) = f2bf(rt);
;         btv[t] = bt; ktv[t] = kt;
;         if (t & 1) { atp[t >> 1] = pk2(hold_a, at); vtp[t >> 1] = pk2(hold_v, v); } else { hold_a = at; hold_v = v; }
;     }
.LBB0_785:
	v_lshlrev_b32_e32 v79, 16, v85
	s_waitcnt vmcnt(3)
	v_add_f32_e32 v79, v142, v79
	v_mul_f32_e32 v79, 0xbfb8aa3b, v79
	v_exp_f32_e32 v79, v79
	v_lshlrev_b32_e32 v78, 16, v80
	v_lshlrev_b32_e32 v80, 16, v84
	v_lshlrev_b32_e32 v84, 16, v76
	v_lshlrev_b32_e32 v76, 16, v109
	v_add_f32_e32 v76, v142, v76
	v_mul_f32_e32 v76, 0xbfb8aa3b, v76
	v_add_f32_e32 v79, 1.0, v79
	v_exp_f32_e32 v76, v76
	v_lshlrev_b32_e32 v83, 16, v82
	v_lshlrev_b32_e32 v82, 16, v81
	v_lshlrev_b32_e32 v81, 16, v117
	v_rcp_f32_e32 v79, v79
	v_lshlrev_b32_e32 v117, 16, v75
	v_lshlrev_b32_e32 v75, 16, v98
	v_add_f32_e32 v75, v142, v75
	v_mul_f32_e32 v75, 0xbfb8aa3b, v75
	s_mov_b32 s20, 0xbf1b4598
	v_add_f32_e32 v76, 1.0, v76
	v_exp_f32_e32 v75, v75
	v_fma_f32 v218, v79, s20, 0
	v_rcp_f32_e32 v76, v76
	v_mul_f32_e32 v79, 0x3fb8aa3b, v218
	v_exp_f32_e32 v217, v79
	v_lshlrev_b32_e32 v85, 16, v77
	v_lshlrev_b32_e32 v77, 16, v108
	v_add_f32_e32 v75, 1.0, v75
	v_sub_f32_e32 v78, v78, v81
	s_waitcnt vmcnt(2)
	v_add_f32_e32 v77, v141, v77
	v_fmac_f32_e32 v218, 0xbf1b4598, v76
	v_rcp_f32_e32 v75, v75
	v_fma_f32 v79, v78, v137, v81
	v_mul_f32_e32 v77, 0xbfb8aa3b, v77
	v_mul_f32_e32 v76, 0x3fb8aa3b, v218
	v_mul_f32_e32 v79, v79, v217
	v_exp_f32_e32 v77, v77
	v_exp_f32_e32 v108, v76
	v_cvt_pk_bf16_f32 v79, v79, s0
	v_lshlrev_b32_e32 v128, 16, v116
	ds_write_b16 v5, v79
	v_sub_f32_e32 v79, v81, v128
	v_fmac_f32_e32 v218, 0xbf1b4598, v75
	v_fma_f32 v76, v79, v137, v128
	v_mul_f32_e32 v75, 0x3fb8aa3b, v218
	v_add_f32_e32 v77, 1.0, v77
	v_mul_f32_e32 v76, v76, v108
	v_exp_f32_e32 v109, v75
	v_rcp_f32_e32 v81, v77
	v_cvt_pk_bf16_f32 v76, v76, s0
	v_lshlrev_b32_e32 v77, 16, v99
	ds_write_b16 v5, v76 offset:144
	v_sub_f32_e32 v76, v128, v77
	v_fma_f32 v75, v76, v137, v77
	v_mul_f32_e32 v75, v75, v109
	v_cvt_pk_bf16_f32 v75, v75, s0
	ds_write_b16 v5, v75 offset:288
	v_lshlrev_b32_e32 v75, 16, v87
	v_add_f32_e32 v75, v142, v75
	v_mul_f32_e32 v75, 0xbfb8aa3b, v75
	v_exp_f32_e32 v75, v75
	v_lshlrev_b32_e32 v129, 16, v96
	v_lshlrev_b32_e32 v116, 16, v74
	v_lshlrev_b32_e32 v86, 16, v86
	v_add_f32_e32 v75, 1.0, v75
	v_rcp_f32_e32 v75, v75
	v_sub_f32_e32 v77, v77, v129
	v_fma_f32 v219, v77, v137, v129
	v_add_f32_e32 v77, v141, v86
	v_pk_add_f32 v[86:87], v[84:85], v[116:117] neg_lo:[0,1] neg_hi:[0,1]
	v_lshlrev_b32_e32 v74, 16, v97
	v_pk_fma_f32 v[86:87], v[86:87], v[2:3], v[116:117] op_sel_hi:[1,0,1]
	v_fmac_f32_e32 v218, 0xbf1b4598, v75
	s_waitcnt vmcnt(1)
	v_pk_mul_f32 v[96:97], v[6:7], v[86:87] op_sel_hi:[0,1]
	v_mul_f32_e32 v75, 0x3fb8aa3b, v218
	v_pk_mul_f32 v[98:99], v[96:97], v[96:97]
	v_exp_f32_e32 v128, v75
	v_add_f32_e32 v74, v141, v74
	v_add_f32_dpp v75, v98, v98 quad_perm:[1,0,3,2] row_mask:0xf bank_mask:0xf bound_ctrl:1
	v_mul_f32_e32 v74, 0xbfb8aa3b, v74
	v_exp_f32_e32 v74, v74
	v_add_f32_dpp v75, v75, v75 quad_perm:[2,3,0,1] row_mask:0xf bank_mask:0xf bound_ctrl:1
	v_rcp_f32_e32 v79, v108
	v_mul_f32_e32 v77, 0xbfb8aa3b, v77
	v_add_f32_dpp v75, v75, v75 row_half_mirror row_mask:0xf bank_mask:0xf bound_ctrl:1
	v_add_f32_e32 v74, 1.0, v74
	v_rcp_f32_e32 v76, v74
	v_add_f32_dpp v75, v75, v75 row_mirror row_mask:0xf bank_mask:0xf bound_ctrl:1
	v_rcp_f32_e32 v74, v109
	v_readlane_b32 s20, v75, 16
	v_readlane_b32 s60, v75, 48
	v_readlane_b32 s58, v75, 0
	v_readlane_b32 s59, v75, 32
	v_mov_b32_e32 v134, s20
	v_mov_b32_e32 v135, s60
	v_add_f32 v134, s58, v134
	v_add_f32 v135, s59, v135
	v_exp_f32_e32 v77, v77
	v_add_f32_e32 v75, v134, v135
	v_max_f32_e32 v75, 0x179abe15, v75
	v_rsq_f32_e32 v98, v75
	v_lshlrev_b32_e32 v89, 16, v89
	v_add_f32_dpp v75, v99, v99 quad_perm:[1,0,3,2] row_mask:0xf bank_mask:0xf bound_ctrl:1
	v_add_f32_e32 v89, v141, v89
	v_mul_f32_e32 v89, 0xbfb8aa3b, v89
	v_add_f32_dpp v75, v75, v75 quad_perm:[2,3,0,1] row_mask:0xf bank_mask:0xf bound_ctrl:1
	v_exp_f32_e32 v89, v89
	v_lshlrev_b32_e32 v93, 16, v93
	v_add_f32_dpp v75, v75, v75 row_half_mirror row_mask:0xf bank_mask:0xf bound_ctrl:1
	v_add_f32_e32 v93, v141, v93
	v_mul_f32_e32 v93, 0xbfb8aa3b, v93
	v_add_f32_dpp v75, v75, v75 row_mirror row_mask:0xf bank_mask:0xf bound_ctrl:1
	v_exp_f32_e32 v93, v93
	v_readlane_b32 s20, v75, 16
	v_readlane_b32 s60, v75, 48
	v_readlane_b32 s58, v75, 0
	v_readlane_b32 s59, v75, 32
	v_mov_b32_e32 v134, s20
	v_mov_b32_e32 v135, s60
	v_add_f32 v134, s58, v134
	v_add_f32 v135, s59, v135
	v_lshlrev_b32_e32 v101, 16, v101
	v_add_f32_e32 v75, v134, v135
	v_lshlrev_b32_e32 v135, 16, v73
	v_lshlrev_b32_e32 v73, 16, v104
	v_add_f32_e32 v73, v142, v73
	v_mul_f32_e32 v73, 0xbfb8aa3b, v73
	v_max_f32_e32 v75, 0x179abe15, v75
	v_exp_f32_e32 v73, v73
	v_rsq_f32_e32 v99, v75
	v_lshlrev_b32_e32 v134, 16, v72
	v_lshlrev_b32_e32 v72, 16, v88
	v_add_f32_e32 v73, 1.0, v73
	v_pk_mul_f32 v[96:97], v[96:97], v[98:99]
	v_rcp_f32_e32 v73, v73
	v_pk_mul_f32 v[98:99], v[108:109], v[96:97] neg_lo:[0,1] neg_hi:[0,1]
	v_add_f32_e32 v72, v141, v72
	v_cvt_pk_bf16_f32 v85, v98, s0
	ds_write_b16 v5, v85 offset:10528
	v_mul_f32_e32 v85, v219, v128
	v_cvt_pk_bf16_f32 v85, v85, s0
	v_fmac_f32_e32 v218, 0xbf1b4598, v73
	ds_write_b16 v5, v85 offset:432
	v_lshlrev_b32_e32 v85, 16, v105
	v_mul_f32_e32 v73, 0x3fb8aa3b, v218
	v_sub_f32_e32 v88, v129, v85
	v_exp_f32_e32 v129, v73
	v_fma_f32 v73, v88, v137, v85
	v_lshlrev_b32_e32 v219, 16, v91
	v_cvt_pk_bf16_f32 v108, v99, s0
	v_mul_f32_e32 v73, v73, v129
	v_cvt_pk_bf16_f32 v73, v73, s0
	ds_write_b16 v5, v73 offset:576
	v_lshlrev_b32_e32 v73, 16, v90
	v_add_f32_e32 v73, v142, v73
	v_mul_f32_e32 v73, 0xbfb8aa3b, v73
	v_exp_f32_e32 v73, v73
	ds_write_b16 v5, v108 offset:10672
	v_mul_f32_e32 v72, 0xbfb8aa3b, v72
	v_exp_f32_e32 v72, v72
	v_add_f32_e32 v73, 1.0, v73
; #define LAS __attribute__((address_space(3)))
; __device__ __forceinline__ unsigned pk2(float lo, float hi) { f32x2 v = {lo, hi}; bf16x2_t b = __builtin_convertvector(v, bf16x2_t); return __builtin_bit_cast(unsigned, b); }
; __device__ __forceinline__ float wsum64(float x) {
;     x = allred16(x);
;     const float t0 = __int_as_float(__builtin_amdgcn_readlane(__float_as_int(x), 0)), t1 = __int_as_float(__builtin_amdgcn_readlane(__float_as_int(x), 16));
;     const float t2 = __int_as_float(__builtin_amdgcn_readlane(__float_as_int(x), 32)), t3 = __int_as_float(__builtin_amdgcn_readlane(__float_as_int(x), 48));
;     return (t0 + t1) + (t2 + t3); }
; __device__ __forceinline__ void s2_produce(LAS unsigned char* CB, LAS unsigned char* PSb, LAS unsigned char* APTp, const unsigned (&rw)[16][5], const unsigned (&pv3)[3], int lane,
;         float mur, float muk, float muv, float w0v, float a0v, float kkv, float kav) {
;     ...
;     for (int t = 0; t < 16; ++t) {
;         const float cr = __uint_as_float(rw[t][0] << 16), ck = __uint_as_float(rw[t][1] << 16), cv = __uint_as_float(rw[t][2] << 16);
;         const float lw = __uint_as_float(rw[t][3] << 16), la = __uint_as_float(rw[t][4] << 16);
;         const float r = cr + (pr - cr) * mur, k = ck + (pk - ck) * muk, v = cv + (pv - cv) * muv;
;         pr = cr; pk = ck; pv = cv;
;         const float aic = sigm(a0v + la);
;         const float lam = -0.6065306597126334f * __builtin_amdgcn_rcpf(1.f + __expf(-(w0v + lw)));
;         const float kk = k * kkv; const float ss = wsum64(kk * kk);
;         const float kn = kk * rsqrtf(fmaxf(ss, 1e-24f));
;         const float k2 = k * (1.f + (aic - 1.f) * kav);
;         Lam += lam;
;         const float eL = __expf(Lam), eLm = __builtin_amdgcn_rcpf(eL);
;         const float at = -kn * eP, rt = r * eL, bt = kn * aic * eLm, kt = k2 * eLm;
;         eP = eL;
;         *(LAS bf16_t*)(PSb + S2_AT + t * 144 + lane * 2) = f2bf(at);
;         *(LAS bf16_t*)(PSb + S2_BT + t * 144 + lane * 2) = f2bf(bt);
;         *(LAS bf16_t*)(PSb + S2_KT + t * 144 + lane * 2) = f2bf(kt);
;         *(LAS bf16_t*)(CB + S2_RT + t * 144 + lane * 2) = f2bf(rt);
;         btv[t] = bt; ktv[t] = kt;
;         if (t & 1) { atp[t >> 1] = pk2(hold_a, at); vtp[t >> 1] = pk2(hold_v, v); } else { hold_a = at; hold_v = v; }
;     }
	v_rcp_f32_e32 v73, v73
	v_sub_f32_e32 v85, v85, v219
	v_add_f32_e32 v72, 1.0, v72
	v_rcp_f32_e32 v88, v72
	v_fmac_f32_e32 v218, 0xbf1b4598, v73
	v_mul_f32_e32 v73, 0x3fb8aa3b, v218
	v_exp_f32_e32 v116, v73
	v_rcp_f32_e32 v72, v129
	v_fma_f32 v85, v85, v137, v219
	v_add_f32_e32 v75, 1.0, v77
	v_pk_mov_b32 v[90:91], v[116:117], v[134:135] op_sel:[1,0]
	v_mul_f32_e32 v85, v85, v116
	v_pk_add_f32 v[90:91], v[90:91], v[134:135] neg_lo:[0,1] neg_hi:[0,1]
	v_cvt_pk_bf16_f32 v85, v85, s0
	v_pk_fma_f32 v[90:91], v[90:91], v[2:3], v[134:135] op_sel_hi:[1,0,1]
	ds_write_b16 v5, v85 offset:720
	v_pk_mul_f32 v[104:105], v[6:7], v[90:91] op_sel_hi:[0,1]
	v_pk_mul_f32 v[108:109], v[104:105], v[104:105]
	v_lshlrev_b32_e32 v85, 16, v111
	v_rcp_f32_e32 v77, v75
	v_add_f32_dpp v73, v108, v108 quad_perm:[1,0,3,2] row_mask:0xf bank_mask:0xf bound_ctrl:1
	v_rcp_f32_e32 v75, v128
	v_add_f32_e32 v101, v141, v101
	v_add_f32_dpp v73, v73, v73 quad_perm:[2,3,0,1] row_mask:0xf bank_mask:0xf bound_ctrl:1
	v_mul_f32_e32 v101, 0xbfb8aa3b, v101
	v_exp_f32_e32 v101, v101
	v_add_f32_dpp v73, v73, v73 row_half_mirror row_mask:0xf bank_mask:0xf bound_ctrl:1
	v_lshlrev_b32_e32 v107, 16, v107
	v_add_f32_e32 v107, v141, v107
	v_add_f32_dpp v73, v73, v73 row_mirror row_mask:0xf bank_mask:0xf bound_ctrl:1
	v_mul_f32_e32 v107, 0xbfb8aa3b, v107
	v_readlane_b32 s20, v73, 16
	v_readlane_b32 s60, v73, 48
	v_readlane_b32 s58, v73, 0
	v_readlane_b32 s59, v73, 32
	v_mov_b32_e32 v220, s20
	v_mov_b32_e32 v221, s60
	v_add_f32 v220, s58, v220
	v_add_f32 v221, s59, v221
	v_exp_f32_e32 v107, v107
	v_add_f32_e32 v73, v220, v221
	v_max_f32_e32 v73, 0x179abe15, v73
	v_rsq_f32_e32 v108, v73
	v_lshlrev_b32_e32 v115, 16, v115
	v_add_f32_dpp v73, v109, v109 quad_perm:[1,0,3,2] row_mask:0xf bank_mask:0xf bound_ctrl:1
	v_add_f32_e32 v115, v141, v115
	v_mul_f32_e32 v115, 0xbfb8aa3b, v115
	v_add_f32_dpp v73, v73, v73 quad_perm:[2,3,0,1] row_mask:0xf bank_mask:0xf bound_ctrl:1
	v_exp_f32_e32 v115, v115
	v_lshlrev_b32_e32 v123, 16, v123
	v_add_f32_dpp v73, v73, v73 row_half_mirror row_mask:0xf bank_mask:0xf bound_ctrl:1
	v_lshlrev_b32_e32 v36, 16, v36
	v_lshlrev_b32_e32 v37, 16, v37
	v_add_f32_dpp v73, v73, v73 row_mirror row_mask:0xf bank_mask:0xf bound_ctrl:1
	v_lshlrev_b32_e32 v57, 16, v57
	v_readlane_b32 s20, v73, 16
	v_readlane_b32 s60, v73, 48
	v_readlane_b32 s58, v73, 0
	v_readlane_b32 s59, v73, 32
	v_mov_b32_e32 v220, s20
	v_mov_b32_e32 v221, s60
	v_add_f32 v220, s58, v220
	v_add_f32 v221, s59, v221
	v_lshlrev_b32_e32 v56, 16, v56
	v_add_f32_e32 v73, v220, v221
	v_max_f32_e32 v73, 0x179abe15, v73
	v_rsq_f32_e32 v109, v73
	v_add_f32_e32 v73, 1.0, v89
	v_rcp_f32_e32 v89, v73
	v_rcp_f32_e32 v73, v116
	v_pk_mul_f32 v[104:105], v[104:105], v[108:109]
	v_lshlrev_b32_e32 v61, 16, v61
	v_pk_mul_f32 v[108:109], v[128:129], v[104:105] neg_lo:[0,1] neg_hi:[0,1]
	v_lshlrev_b32_e32 v129, 16, v71
	v_lshlrev_b32_e32 v71, 16, v110
	v_add_f32_e32 v71, v142, v71
	v_mul_f32_e32 v71, 0xbfb8aa3b, v71
	v_exp_f32_e32 v71, v71
	v_cvt_pk_bf16_f32 v117, v108, s0
	ds_write_b16 v5, v117 offset:10816
	v_cvt_pk_bf16_f32 v117, v109, s0
	v_add_f32_e32 v71, 1.0, v71
	v_rcp_f32_e32 v71, v71
	ds_write_b16 v5, v117 offset:10960
	v_lshlrev_b32_e32 v128, 16, v70
	v_lshlrev_b32_e32 v70, 16, v92
	v_fmac_f32_e32 v218, 0xbf1b4598, v71
	v_mul_f32_e32 v71, 0x3fb8aa3b, v218
	v_exp_f32_e32 v117, v71
	v_sub_f32_e32 v92, v219, v85
	v_fma_f32 v71, v92, v137, v85
	v_lshlrev_b32_e32 v219, 16, v95
	v_mul_f32_e32 v71, v71, v117
	v_cvt_pk_bf16_f32 v71, v71, s0
	ds_write_b16 v5, v71 offset:864
	v_lshlrev_b32_e32 v71, 16, v94
	v_add_f32_e32 v71, v142, v71
	v_mul_f32_e32 v71, 0xbfb8aa3b, v71
	v_exp_f32_e32 v71, v71
	v_pk_mov_b32 v[94:95], v[134:135], v[128:129] op_sel:[1,0]
	v_add_f32_e32 v70, v141, v70
	v_pk_add_f32 v[94:95], v[94:95], v[128:129] neg_lo:[0,1] neg_hi:[0,1]
	v_add_f32_e32 v71, 1.0, v71
	v_rcp_f32_e32 v71, v71
	v_pk_fma_f32 v[94:95], v[94:95], v[2:3], v[128:129] op_sel_hi:[1,0,1]
	v_mul_f32_e32 v70, 0xbfb8aa3b, v70
	v_pk_mul_f32 v[110:111], v[6:7], v[94:95] op_sel_hi:[0,1]
	v_fmac_f32_e32 v218, 0xbf1b4598, v71
	v_mul_f32_e32 v71, 0x3fb8aa3b, v218
	v_pk_mul_f32 v[134:135], v[110:111], v[110:111]
	v_exp_f32_e32 v220, v71
	v_exp_f32_e32 v70, v70
	v_add_f32_dpp v71, v134, v134 quad_perm:[1,0,3,2] row_mask:0xf bank_mask:0xf bound_ctrl:1
	v_sub_f32_e32 v85, v85, v219
	v_fma_f32 v85, v85, v137, v219
	v_add_f32_dpp v71, v71, v71 quad_perm:[2,3,0,1] row_mask:0xf bank_mask:0xf bound_ctrl:1
	v_add_f32_e32 v70, 1.0, v70
	v_rcp_f32_e32 v92, v70
	v_add_f32_dpp v71, v71, v71 row_half_mirror row_mask:0xf bank_mask:0xf bound_ctrl:1
	v_rcp_f32_e32 v70, v117
	v_mul_f32_e32 v85, v85, v220
	v_add_f32_dpp v71, v71, v71 row_mirror row_mask:0xf bank_mask:0xf bound_ctrl:1
	v_cvt_pk_bf16_f32 v85, v85, s0
	v_readlane_b32 s20, v71, 16
	v_readlane_b32 s60, v71, 48
	v_readlane_b32 s58, v71, 0
	v_readlane_b32 s59, v71, 32
	v_mov_b32_e32 v222, s20
	v_mov_b32_e32 v223, s60
	v_add_f32 v222, s58, v222
	v_add_f32 v223, s59, v223
	ds_write_b16 v5, v85 offset:1008
	v_add_f32_e32 v71, v222, v223
	v_max_f32_e32 v71, 0x179abe15, v71
	v_rsq_f32_e32 v134, v71
	v_lshlrev_b32_e32 v85, 16, v119
	v_add_f32_dpp v71, v135, v135 quad_perm:[1,0,3,2] row_mask:0xf bank_mask:0xf bound_ctrl:1
	v_lshlrev_b32_e32 v60, 16, v60
	v_lshlrev_b32_e32 v27, 16, v27
	v_add_f32_dpp v71, v71, v71 quad_perm:[2,3,0,1] row_mask:0xf bank_mask:0xf bound_ctrl:1
	v_lshlrev_b32_e32 v26, 16, v26
	v_pk_add_f32 v[26:27], v[26:27], v[60:61] neg_lo:[0,1] neg_hi:[0,1]
	v_add_f32_dpp v71, v71, v71 row_half_mirror row_mask:0xf bank_mask:0xf bound_ctrl:1
	v_pk_fma_f32 v[26:27], v[26:27], v[4:5], v[60:61] op_sel_hi:[1,0,1]
; #define LAS __attribute__((address_space(3)))
; __device__ __forceinline__ unsigned pk2(float lo, float hi) { f32x2 v = {lo, hi}; bf16x2_t b = __builtin_convertvector(v, bf16x2_t); return __builtin_bit_cast(unsigned, b); }
; __device__ __forceinline__ float wsum64(float x) {
;     x = allred16(x);
;     const float t0 = __int_as_float(__builtin_amdgcn_readlane(__float_as_int(x), 0)), t1 = __int_as_float(__builtin_amdgcn_readlane(__float_as_int(x), 16));
;     const float t2 = __int_as_float(__builtin_amdgcn_readlane(__float_as_int(x), 32)), t3 = __int_as_float(__builtin_amdgcn_readlane(__float_as_int(x), 48));
;     return (t0 + t1) + (t2 + t3); }
; __device__ __forceinline__ void s2_produce(LAS unsigned char* CB, LAS unsigned char* PSb, LAS unsigned char* APTp, const unsigned (&rw)[16][5], const unsigned (&pv3)[3], int lane,
;         float mur, float muk, float muv, float w0v, float a0v, float kkv, float kav) {
;     ...
;     for (int t = 0; t < 16; ++t) {
;         const float cr = __uint_as_float(rw[t][0] << 16), ck = __uint_as_float(rw[t][1] << 16), cv = __uint_as_float(rw[t][2] << 16);
;         const float lw = __uint_as_float(rw[t][3] << 16), la = __uint_as_float(rw[t][4] << 16);
;         const float r = cr + (pr - cr) * mur, k = ck + (pk - ck) * muk, v = cv + (pv - cv) * muv;
;         pr = cr; pk = ck; pv = cv;
;         const float aic = sigm(a0v + la);
;         const float lam = -0.6065306597126334f * __builtin_amdgcn_rcpf(1.f + __expf(-(w0v + lw)));
;         const float kk = k * kkv; const float ss = wsum64(kk * kk);
;         const float kn = kk * rsqrtf(fmaxf(ss, 1e-24f));
;         const float k2 = k * (1.f + (aic - 1.f) * kav);
;         Lam += lam;
;         const float eL = __expf(Lam), eLm = __builtin_amdgcn_rcpf(eL);
;         const float at = -kn * eP, rt = r * eL, bt = kn * aic * eLm, kt = k2 * eLm;
;         eP = eL;
;         *(LAS bf16_t*)(PSb + S2_AT + t * 144 + lane * 2) = f2bf(at);
;         *(LAS bf16_t*)(PSb + S2_BT + t * 144 + lane * 2) = f2bf(bt);
;         *(LAS bf16_t*)(PSb + S2_KT + t * 144 + lane * 2) = f2bf(kt);
;         *(LAS bf16_t*)(CB + S2_RT + t * 144 + lane * 2) = f2bf(rt);
;         btv[t] = bt; ktv[t] = kt;
;         if (t & 1) { atp[t >> 1] = pk2(hold_a, at); vtp[t >> 1] = pk2(hold_v, v); } else { hold_a = at; hold_v = v; }
;     }
	v_add_f32_e32 v80, v141, v80
	v_add_f32_dpp v71, v71, v71 row_mirror row_mask:0xf bank_mask:0xf bound_ctrl:1
	v_mul_f32_e32 v80, 0xbfb8aa3b, v80
	v_readlane_b32 s20, v71, 16
	v_readlane_b32 s60, v71, 48
	v_readlane_b32 s58, v71, 0
	v_readlane_b32 s59, v71, 32
	v_mov_b32_e32 v222, s20
	v_mov_b32_e32 v223, s60
	v_add_f32 v222, s58, v222
	v_add_f32 v223, s59, v223
	v_exp_f32_e32 v80, v80
	v_add_f32_e32 v71, v222, v223
	v_max_f32_e32 v71, 0x179abe15, v71
	v_rsq_f32_e32 v135, v71
	v_add_f32_e32 v71, 1.0, v93
	v_rcp_f32_e32 v93, v71
	v_rcp_f32_e32 v71, v220
	v_pk_mul_f32 v[110:111], v[110:111], v[134:135]
	v_lshlrev_b32_e32 v135, 16, v69
	v_lshlrev_b32_e32 v69, 16, v118
	v_add_f32_e32 v69, v142, v69
	v_mul_f32_e32 v69, 0xbfb8aa3b, v69
	v_exp_f32_e32 v69, v69
	v_pk_mul_f32 v[116:117], v[116:117], v[110:111] neg_lo:[0,1] neg_hi:[0,1]
	v_add_f32_e32 v78, 1.0, v80
	v_cvt_pk_bf16_f32 v134, v116, s0
	v_add_f32_e32 v69, 1.0, v69
	v_rcp_f32_e32 v69, v69
	ds_write_b16 v5, v134 offset:11104
	v_cvt_pk_bf16_f32 v134, v117, s0
	ds_write_b16 v5, v134 offset:11248
	v_fmac_f32_e32 v218, 0xbf1b4598, v69
	v_mul_f32_e32 v69, 0x3fb8aa3b, v218
	v_exp_f32_e32 v221, v69
	v_lshlrev_b32_e32 v134, 16, v68
	v_lshlrev_b32_e32 v68, 16, v100
	v_sub_f32_e32 v100, v219, v85
	v_fma_f32 v69, v100, v137, v85
	v_mul_f32_e32 v69, v69, v221
	v_cvt_pk_bf16_f32 v69, v69, s0
	ds_write_b16 v5, v69 offset:1152
	v_lshlrev_b32_e32 v69, 16, v102
	v_add_f32_e32 v69, v142, v69
	v_mul_f32_e32 v69, 0xbfb8aa3b, v69
	v_exp_f32_e32 v69, v69
	v_lshlrev_b32_e32 v219, 16, v103
	v_pk_mov_b32 v[102:103], v[128:129], v[134:135] op_sel:[1,0]
	v_add_f32_e32 v68, v141, v68
	v_add_f32_e32 v69, 1.0, v69
	v_rcp_f32_e32 v69, v69
	v_pk_add_f32 v[102:103], v[102:103], v[134:135] neg_lo:[0,1] neg_hi:[0,1]
	v_mul_f32_e32 v68, 0xbfb8aa3b, v68
	v_pk_fma_f32 v[102:103], v[102:103], v[2:3], v[134:135] op_sel_hi:[1,0,1]
	v_fmac_f32_e32 v218, 0xbf1b4598, v69
	v_pk_mul_f32 v[118:119], v[6:7], v[102:103] op_sel_hi:[0,1]
	v_mul_f32_e32 v69, 0x3fb8aa3b, v218
	v_pk_mul_f32 v[128:129], v[118:119], v[118:119]
	v_exp_f32_e32 v222, v69
	v_exp_f32_e32 v68, v68
	v_add_f32_dpp v69, v128, v128 quad_perm:[1,0,3,2] row_mask:0xf bank_mask:0xf bound_ctrl:1
	v_sub_f32_e32 v85, v85, v219
	v_fma_f32 v85, v85, v137, v219
	v_add_f32_dpp v69, v69, v69 quad_perm:[2,3,0,1] row_mask:0xf bank_mask:0xf bound_ctrl:1
	v_add_f32_e32 v68, 1.0, v68
	v_rcp_f32_e32 v100, v68
	v_add_f32_dpp v69, v69, v69 row_half_mirror row_mask:0xf bank_mask:0xf bound_ctrl:1
	v_rcp_f32_e32 v68, v221
	v_mul_f32_e32 v85, v85, v222
	v_add_f32_dpp v69, v69, v69 row_mirror row_mask:0xf bank_mask:0xf bound_ctrl:1
	v_cvt_pk_bf16_f32 v85, v85, s0
	v_readlane_b32 s20, v69, 16
	v_readlane_b32 s60, v69, 48
	v_readlane_b32 s58, v69, 0
	v_readlane_b32 s59, v69, 32
	v_mov_b32_e32 v224, s20
	v_mov_b32_e32 v225, s60
	v_add_f32 v224, s58, v224
	v_add_f32 v225, s59, v225
	ds_write_b16 v5, v85 offset:1296
	v_add_f32_e32 v69, v224, v225
	v_max_f32_e32 v69, 0x179abe15, v69
	v_rsq_f32_e32 v128, v69
	v_lshlrev_b32_e32 v85, 16, v127
	v_add_f32_dpp v69, v129, v129 quad_perm:[1,0,3,2] row_mask:0xf bank_mask:0xf bound_ctrl:1
	v_rcp_f32_e32 v80, v78
	v_rcp_f32_e32 v78, v217
	v_add_f32_dpp v69, v69, v69 quad_perm:[2,3,0,1] row_mask:0xf bank_mask:0xf bound_ctrl:1
	v_mov_b32_e32 v16, v15
	s_cmpk_gt_i32 s67, 0x29ca
	v_add_f32_dpp v69, v69, v69 row_half_mirror row_mask:0xf bank_mask:0xf bound_ctrl:1
	s_mov_b64 s[62:63], -1
	s_nop 0
	v_add_f32_dpp v69, v69, v69 row_mirror row_mask:0xf bank_mask:0xf bound_ctrl:1
	s_nop 0
	v_readlane_b32 s20, v69, 16
	v_readlane_b32 s60, v69, 48
	v_readlane_b32 s58, v69, 0
	v_readlane_b32 s59, v69, 32
	v_mov_b32_e32 v224, s20
	v_mov_b32_e32 v225, s60
	v_add_f32 v224, s58, v224
	v_add_f32 v225, s59, v225
	s_nop 0
	v_add_f32_e32 v69, v224, v225
	v_max_f32_e32 v69, 0x179abe15, v69
	v_rsq_f32_e32 v129, v69
	v_add_f32_e32 v69, 1.0, v101
	v_rcp_f32_e32 v101, v69
	v_rcp_f32_e32 v69, v222
	v_pk_mul_f32 v[118:119], v[118:119], v[128:129]
	s_nop 0
	v_pk_mul_f32 v[128:129], v[220:221], v[118:119] neg_lo:[0,1] neg_hi:[0,1]
	v_lshlrev_b32_e32 v221, 16, v67
	v_lshlrev_b32_e32 v67, 16, v126
	v_add_f32_e32 v67, v142, v67
	v_mul_f32_e32 v67, 0xbfb8aa3b, v67
	v_exp_f32_e32 v67, v67
	v_cvt_pk_bf16_f32 v220, v128, s0
	ds_write_b16 v5, v220 offset:11392
	v_cvt_pk_bf16_f32 v220, v129, s0
	v_add_f32_e32 v67, 1.0, v67
	v_rcp_f32_e32 v67, v67
	ds_write_b16 v5, v220 offset:11536
	v_lshlrev_b32_e32 v220, 16, v66
	v_lshlrev_b32_e32 v66, 16, v106
	v_fmac_f32_e32 v218, 0xbf1b4598, v67
	v_mul_f32_e32 v67, 0x3fb8aa3b, v218
	v_exp_f32_e32 v223, v67
	v_sub_f32_e32 v106, v219, v85
	v_fma_f32 v67, v106, v137, v85
	v_lshlrev_b32_e32 v219, 16, v113
	v_mul_f32_e32 v67, v67, v223
	v_cvt_pk_bf16_f32 v67, v67, s0
	ds_write_b16 v5, v67 offset:1440
	v_lshlrev_b32_e32 v67, 16, v112
	v_add_f32_e32 v67, v142, v67
	v_mul_f32_e32 v67, 0xbfb8aa3b, v67
	v_exp_f32_e32 v67, v67
	v_pk_mov_b32 v[112:113], v[134:135], v[220:221] op_sel:[1,0]
	v_add_f32_e32 v66, v141, v66
	v_pk_add_f32 v[112:113], v[112:113], v[220:221] neg_lo:[0,1] neg_hi:[0,1]
	v_add_f32_e32 v67, 1.0, v67
	v_rcp_f32_e32 v67, v67
	v_pk_fma_f32 v[112:113], v[112:113], v[2:3], v[220:221] op_sel_hi:[1,0,1]
	v_mul_f32_e32 v66, 0xbfb8aa3b, v66
	v_pk_mul_f32 v[126:127], v[6:7], v[112:113] op_sel_hi:[0,1]
	v_fmac_f32_e32 v218, 0xbf1b4598, v67
	v_mul_f32_e32 v67, 0x3fb8aa3b, v218
	v_pk_mul_f32 v[134:135], v[126:127], v[126:127]
	v_exp_f32_e32 v224, v67
	v_exp_f32_e32 v66, v66
	v_add_f32_dpp v67, v134, v134 quad_perm:[1,0,3,2] row_mask:0xf bank_mask:0xf bound_ctrl:1
	v_sub_f32_e32 v85, v85, v219
	v_fma_f32 v85, v85, v137, v219
; #define LAS __attribute__((address_space(3)))
; __device__ __forceinline__ unsigned pk2(float lo, float hi) { f32x2 v = {lo, hi}; bf16x2_t b = __builtin_convertvector(v, bf16x2_t); return __builtin_bit_cast(unsigned, b); }
; __device__ __forceinline__ float wsum64(float x) {
;     x = allred16(x);
;     const float t0 = __int_as_float(__builtin_amdgcn_readlane(__float_as_int(x), 0)), t1 = __int_as_float(__builtin_amdgcn_readlane(__float_as_int(x), 16));
;     const float t2 = __int_as_float(__builtin_amdgcn_readlane(__float_as_int(x), 32)), t3 = __int_as_float(__builtin_amdgcn_readlane(__float_as_int(x), 48));
;     return (t0 + t1) + (t2 + t3); }
; __device__ __forceinline__ void s2_produce(LAS unsigned char* CB, LAS unsigned char* PSb, LAS unsigned char* APTp, const unsigned (&rw)[16][5], const unsigned (&pv3)[3], int lane,
;         float mur, float muk, float muv, float w0v, float a0v, float kkv, float kav) {
;     ...
;     for (int t = 0; t < 16; ++t) {
;         const float cr = __uint_as_float(rw[t][0] << 16), ck = __uint_as_float(rw[t][1] << 16), cv = __uint_as_float(rw[t][2] << 16);
;         const float lw = __uint_as_float(rw[t][3] << 16), la = __uint_as_float(rw[t][4] << 16);
;         const float r = cr + (pr - cr) * mur, k = ck + (pk - ck) * muk, v = cv + (pv - cv) * muv;
;         pr = cr; pk = ck; pv = cv;
;         const float aic = sigm(a0v + la);
;         const float lam = -0.6065306597126334f * __builtin_amdgcn_rcpf(1.f + __expf(-(w0v + lw)));
;         const float kk = k * kkv; const float ss = wsum64(kk * kk);
;         const float kn = kk * rsqrtf(fmaxf(ss, 1e-24f));
;         const float k2 = k * (1.f + (aic - 1.f) * kav);
;         Lam += lam;
;         const float eL = __expf(Lam), eLm = __builtin_amdgcn_rcpf(eL);
;         const float at = -kn * eP, rt = r * eL, bt = kn * aic * eLm, kt = k2 * eLm;
;         eP = eL;
;         *(LAS bf16_t*)(PSb + S2_AT + t * 144 + lane * 2) = f2bf(at);
;         *(LAS bf16_t*)(PSb + S2_BT + t * 144 + lane * 2) = f2bf(bt);
;         *(LAS bf16_t*)(PSb + S2_KT + t * 144 + lane * 2) = f2bf(kt);
;         *(LAS bf16_t*)(CB + S2_RT + t * 144 + lane * 2) = f2bf(rt);
;         btv[t] = bt; ktv[t] = kt;
;         if (t & 1) { atp[t >> 1] = pk2(hold_a, at); vtp[t >> 1] = pk2(hold_v, v); } else { hold_a = at; hold_v = v; }
;     }
	v_add_f32_dpp v67, v67, v67 quad_perm:[2,3,0,1] row_mask:0xf bank_mask:0xf bound_ctrl:1
	v_add_f32_e32 v66, 1.0, v66
	v_rcp_f32_e32 v106, v66
	v_add_f32_dpp v67, v67, v67 row_half_mirror row_mask:0xf bank_mask:0xf bound_ctrl:1
	v_rcp_f32_e32 v66, v223
	v_mul_f32_e32 v85, v85, v224
	v_add_f32_dpp v67, v67, v67 row_mirror row_mask:0xf bank_mask:0xf bound_ctrl:1
	v_cvt_pk_bf16_f32 v85, v85, s0
	v_readlane_b32 s20, v67, 16
	v_readlane_b32 s60, v67, 48
	v_readlane_b32 s58, v67, 0
	v_readlane_b32 s59, v67, 32
	v_mov_b32_e32 v226, s20
	v_mov_b32_e32 v227, s60
	v_add_f32 v226, s58, v226
	v_add_f32 v227, s59, v227
	ds_write_b16 v5, v85 offset:1584
	v_add_f32_e32 v67, v226, v227
	v_max_f32_e32 v67, 0x179abe15, v67
	v_rsq_f32_e32 v134, v67
	v_lshlrev_b32_e32 v85, 16, v133
	v_add_f32_dpp v67, v135, v135 quad_perm:[1,0,3,2] row_mask:0xf bank_mask:0xf bound_ctrl:1
	s_nop 1
	v_add_f32_dpp v67, v67, v67 quad_perm:[2,3,0,1] row_mask:0xf bank_mask:0xf bound_ctrl:1
	s_nop 1
	v_add_f32_dpp v67, v67, v67 row_half_mirror row_mask:0xf bank_mask:0xf bound_ctrl:1
	s_nop 1
	v_add_f32_dpp v67, v67, v67 row_mirror row_mask:0xf bank_mask:0xf bound_ctrl:1
	s_nop 0
	v_readlane_b32 s20, v67, 16
	v_readlane_b32 s60, v67, 48
	v_readlane_b32 s58, v67, 0
	v_readlane_b32 s59, v67, 32
	v_mov_b32_e32 v226, s20
	v_mov_b32_e32 v227, s60
	v_add_f32 v226, s58, v226
	v_add_f32 v227, s59, v227
	s_nop 0
	v_add_f32_e32 v67, v226, v227
	v_max_f32_e32 v67, 0x179abe15, v67
	v_rsq_f32_e32 v135, v67
	v_add_f32_e32 v67, 1.0, v107
	v_rcp_f32_e32 v107, v67
	v_rcp_f32_e32 v67, v224
	v_pk_mul_f32 v[126:127], v[126:127], v[134:135]
	s_nop 0
	v_pk_mul_f32 v[134:135], v[222:223], v[126:127] neg_lo:[0,1] neg_hi:[0,1]
	v_lshlrev_b32_e32 v223, 16, v65
	v_lshlrev_b32_e32 v65, 16, v132
	v_add_f32_e32 v65, v142, v65
	v_mul_f32_e32 v65, 0xbfb8aa3b, v65
	v_exp_f32_e32 v65, v65
	v_cvt_pk_bf16_f32 v222, v134, s0
	ds_write_b16 v5, v222 offset:11680
	v_cvt_pk_bf16_f32 v222, v135, s0
	v_add_f32_e32 v65, 1.0, v65
	v_rcp_f32_e32 v65, v65
	ds_write_b16 v5, v222 offset:11824
	v_lshlrev_b32_e32 v222, 16, v64
	v_lshlrev_b32_e32 v64, 16, v114
	v_fmac_f32_e32 v218, 0xbf1b4598, v65
	v_mul_f32_e32 v65, 0x3fb8aa3b, v218
	v_exp_f32_e32 v225, v65
	v_sub_f32_e32 v114, v219, v85
	v_fma_f32 v65, v114, v137, v85
	v_lshlrev_b32_e32 v219, 16, v121
	v_mul_f32_e32 v65, v65, v225
	v_cvt_pk_bf16_f32 v65, v65, s0
	ds_write_b16 v5, v65 offset:1728
	v_lshlrev_b32_e32 v65, 16, v120
	v_add_f32_e32 v65, v142, v65
	v_mul_f32_e32 v65, 0xbfb8aa3b, v65
	v_exp_f32_e32 v65, v65
	v_pk_mov_b32 v[120:121], v[220:221], v[222:223] op_sel:[1,0]
	v_add_f32_e32 v64, v141, v64
	v_pk_add_f32 v[120:121], v[120:121], v[222:223] neg_lo:[0,1] neg_hi:[0,1]
	v_add_f32_e32 v65, 1.0, v65
	v_rcp_f32_e32 v65, v65
	v_pk_fma_f32 v[120:121], v[120:121], v[2:3], v[222:223] op_sel_hi:[1,0,1]
	v_mul_f32_e32 v64, 0xbfb8aa3b, v64
	v_pk_mul_f32 v[132:133], v[6:7], v[120:121] op_sel_hi:[0,1]
	v_fmac_f32_e32 v218, 0xbf1b4598, v65
	v_mul_f32_e32 v65, 0x3fb8aa3b, v218
	v_pk_mul_f32 v[220:221], v[132:133], v[132:133]
	v_exp_f32_e32 v226, v65
	v_exp_f32_e32 v64, v64
	v_add_f32_dpp v65, v220, v220 quad_perm:[1,0,3,2] row_mask:0xf bank_mask:0xf bound_ctrl:1
	v_sub_f32_e32 v85, v85, v219
	v_fma_f32 v85, v85, v137, v219
	v_add_f32_dpp v65, v65, v65 quad_perm:[2,3,0,1] row_mask:0xf bank_mask:0xf bound_ctrl:1
	v_add_f32_e32 v64, 1.0, v64
	v_rcp_f32_e32 v114, v64
	v_add_f32_dpp v65, v65, v65 row_half_mirror row_mask:0xf bank_mask:0xf bound_ctrl:1
	v_rcp_f32_e32 v64, v225
	v_mul_f32_e32 v85, v85, v226
	v_add_f32_dpp v65, v65, v65 row_mirror row_mask:0xf bank_mask:0xf bound_ctrl:1
	v_cvt_pk_bf16_f32 v85, v85, s0
	v_readlane_b32 s20, v65, 16
	v_readlane_b32 s60, v65, 48
	v_readlane_b32 s58, v65, 0
	v_readlane_b32 s59, v65, 32
	v_mov_b32_e32 v228, s20
	v_mov_b32_e32 v229, s60
	v_add_f32 v228, s58, v228
	v_add_f32 v229, s59, v229
	ds_write_b16 v5, v85 offset:1872
	v_add_f32_e32 v65, v228, v229
	v_max_f32_e32 v65, 0x179abe15, v65
	v_rsq_f32_e32 v220, v65
	v_lshlrev_b32_e32 v85, 16, v216
	v_add_f32_dpp v65, v221, v221 quad_perm:[1,0,3,2] row_mask:0xf bank_mask:0xf bound_ctrl:1
	v_lshlrev_b32_e32 v216, 16, v130
	s_nop 0
	v_add_f32_dpp v65, v65, v65 quad_perm:[2,3,0,1] row_mask:0xf bank_mask:0xf bound_ctrl:1
	s_nop 1
	v_add_f32_dpp v65, v65, v65 row_half_mirror row_mask:0xf bank_mask:0xf bound_ctrl:1
	s_nop 1
	v_add_f32_dpp v65, v65, v65 row_mirror row_mask:0xf bank_mask:0xf bound_ctrl:1
	s_nop 0
	v_readlane_b32 s20, v65, 16
	v_readlane_b32 s60, v65, 48
	v_readlane_b32 s58, v65, 0
	v_readlane_b32 s59, v65, 32
	v_mov_b32_e32 v228, s20
	v_mov_b32_e32 v229, s60
	v_add_f32 v228, s58, v228
	v_add_f32 v229, s59, v229
	s_nop 0
	v_add_f32_e32 v65, v228, v229
	v_max_f32_e32 v65, 0x179abe15, v65
	v_rsq_f32_e32 v221, v65
	v_add_f32_e32 v65, 1.0, v115
	v_rcp_f32_e32 v115, v65
	v_rcp_f32_e32 v65, v226
	v_pk_mul_f32 v[132:133], v[132:133], v[220:221]
	v_lshlrev_b32_e32 v221, 16, v63
	v_pk_mul_f32 v[224:225], v[224:225], v[132:133] neg_lo:[0,1] neg_hi:[0,1]
	v_lshlrev_b32_e32 v63, 16, v122
	v_cvt_pk_bf16_f32 v220, v224, s0
	ds_write_b16 v5, v220 offset:11968
	v_cvt_pk_bf16_f32 v220, v225, s0
	ds_write_b16 v5, v220 offset:12112
	v_lshlrev_b32_e32 v220, 16, v62
	v_lshlrev_b32_e32 v62, 16, v131
	v_add_f32_e32 v62, v142, v62
	v_mul_f32_e32 v62, 0xbfb8aa3b, v62
	v_exp_f32_e32 v62, v62
	v_add_f32_e32 v63, v141, v63
	v_mul_f32_e32 v63, 0xbfb8aa3b, v63
	v_exp_f32_e32 v63, v63
	v_add_f32_e32 v62, 1.0, v62
	v_rcp_f32_e32 v62, v62
	v_sub_f32_e32 v122, v219, v85
	v_fma_f32 v131, v122, v137, v85
	v_sub_f32_e32 v85, v85, v216
	v_fmac_f32_e32 v218, 0xbf1b4598, v62
	v_mul_f32_e32 v62, 0x3fb8aa3b, v218
	v_exp_f32_e32 v227, v62
; #define LAS __attribute__((address_space(3)))
; __device__ __forceinline__ void s2_produce(LAS unsigned char* CB, LAS unsigned char* PSb, LAS unsigned char* APTp, const unsigned (&rw)[16][5], const unsigned (&pv3)[3], int lane,
;         float mur, float muk, float muv, float w0v, float a0v, float kkv, float kav) {
;     ...
;     for (int t = 0; t < 16; ++t) {
;         const float cr = __uint_as_float(rw[t][0] << 16), ck = __uint_as_float(rw[t][1] << 16), cv = __uint_as_float(rw[t][2] << 16);
;         const float lw = __uint_as_float(rw[t][3] << 16), la = __uint_as_float(rw[t][4] << 16);
;         const float r = cr + (pr - cr) * mur, k = ck + (pk - ck) * muk, v = cv + (pv - cv) * muv;
;         pr = cr; pk = ck; pv = cv;
;         const float aic = sigm(a0v + la);
;         const float lam = -0.6065306597126334f * __builtin_amdgcn_rcpf(1.f + __expf(-(w0v + lw)));
;         const float kk = k * kkv; const float ss = wsum64(kk * kk);
;         const float kn = kk * rsqrtf(fmaxf(ss, 1e-24f));
;         const float k2 = k * (1.f + (aic - 1.f) * kav);
;         Lam += lam;
;         const float eL = __expf(Lam), eLm = __builtin_amdgcn_rcpf(eL);
;         const float at = -kn * eP, rt = r * eL, bt = kn * aic * eLm, kt = k2 * eLm;
;         eP = eL;
;         *(LAS bf16_t*)(PSb + S2_AT + t * 144 + lane * 2) = f2bf(at);
;         *(LAS bf16_t*)(PSb + S2_BT + t * 144 + lane * 2) = f2bf(bt);
;         *(LAS bf16_t*)(PSb + S2_KT + t * 144 + lane * 2) = f2bf(kt);
;         *(LAS bf16_t*)(CB + S2_RT + t * 144 + lane * 2) = f2bf(rt);
;         btv[t] = bt; ktv[t] = kt;
;         if (t & 1) { atp[t >> 1] = pk2(hold_a, at); vtp[t >> 1] = pk2(hold_v, v); } else { hold_a = at; hold_v = v; }
;     }
;     const float gC = eP;
;     *(LAS float*)(CB + S2_GC + lane * 4) = gC;
;     { u32x4 w0 = {atp[0], atp[1], atp[2], atp[3]}, w1 = {atp[4], atp[5], atp[6], atp[7]};
;       *(LAS u32x4*)(PSb + S2_ATT + lane * 32) = w0; *(LAS u32x4*)(PSb + S2_ATT + lane * 32 + 16) = w1;
;       u32x4 v0 = {vtp[0], vtp[1], vtp[2], vtp[3]}, v1 = {vtp[4], vtp[5], vtp[6], vtp[7]};
;       *(LAS u32x4*)(CB + S2_VT + lane * 32) = v0; *(LAS u32x4*)(CB + S2_VT + lane * 32 + 16) = v1;
;       u32x4 b0, b1, k0, k1;
;       b0.x = pk2(btv[0] * gC, btv[1] * gC); b0.y = pk2(btv[2] * gC, btv[3] * gC); b0.z = pk2(btv[4] * gC, btv[5] * gC); b0.w = pk2(btv[6] * gC, btv[7] * gC);
	v_add_f32_e32 v62, 1.0, v63
	v_fmac_f32_e32 v216, v85, v137
	v_add_f32_e32 v85, v141, v123
	v_mul_f32_e32 v63, v131, v227
	v_cvt_pk_bf16_f32 v63, v63, s0
	ds_write_b16 v5, v63 offset:2016
	v_lshlrev_b32_e32 v63, 16, v124
	v_add_f32_e32 v63, v142, v63
	v_mul_f32_e32 v63, 0xbfb8aa3b, v63
	v_exp_f32_e32 v63, v63
	v_pk_mov_b32 v[130:131], v[222:223], v[220:221] op_sel:[1,0]
	v_mul_f32_e32 v85, 0xbfb8aa3b, v85
	v_pk_add_f32 v[130:131], v[130:131], v[220:221] neg_lo:[0,1] neg_hi:[0,1]
	v_add_f32_e32 v63, 1.0, v63
	v_rcp_f32_e32 v63, v63
	v_pk_fma_f32 v[130:131], v[130:131], v[2:3], v[220:221] op_sel_hi:[1,0,1]
	v_exp_f32_e32 v85, v85
	v_rcp_f32_e32 v122, v62
	v_fmac_f32_e32 v218, 0xbf1b4598, v63
	v_mul_f32_e32 v63, 0x3fb8aa3b, v218
	v_pk_mul_f32 v[218:219], v[6:7], v[130:131] op_sel_hi:[0,1]
	v_pk_mul_f32 v[220:221], v[218:219], v[218:219]
	v_exp_f32_e32 v124, v63
	v_rcp_f32_e32 v62, v227
	v_add_f32_dpp v63, v220, v220 quad_perm:[1,0,3,2] row_mask:0xf bank_mask:0xf bound_ctrl:1
	v_lshlrev_b32_e32 v229, 16, v49
	v_lshlrev_b32_e32 v228, 16, v48
	v_add_f32_dpp v63, v63, v63 quad_perm:[2,3,0,1] row_mask:0xf bank_mask:0xf bound_ctrl:1
	v_cvt_pk_bf16_f32 v49, v116, v117
	v_lshlrev_b32_e32 v117, 16, v59
	v_add_f32_dpp v63, v63, v63 row_half_mirror row_mask:0xf bank_mask:0xf bound_ctrl:1
	v_lshlrev_b32_e32 v116, 16, v58
	v_cvt_pk_bf16_f32 v48, v108, v109
	v_add_f32_dpp v63, v63, v63 row_mirror row_mask:0xf bank_mask:0xf bound_ctrl:1
	s_nop 0
	v_readlane_b32 s20, v63, 16
	v_readlane_b32 s60, v63, 48
	v_readlane_b32 s58, v63, 0
	v_readlane_b32 s59, v63, 32
	v_mov_b32_e32 v222, s20
	v_mov_b32_e32 v223, s60
	v_add_f32 v222, s58, v222
	v_add_f32 v223, s59, v223
	s_nop 0
	v_add_f32_e32 v63, v222, v223
	v_max_f32_e32 v63, 0x179abe15, v63
	v_rsq_f32_e32 v220, v63
	s_nop 0
	v_add_f32_dpp v63, v221, v221 quad_perm:[1,0,3,2] row_mask:0xf bank_mask:0xf bound_ctrl:1
	s_nop 1
	v_add_f32_dpp v63, v63, v63 quad_perm:[2,3,0,1] row_mask:0xf bank_mask:0xf bound_ctrl:1
	s_nop 1
	v_add_f32_dpp v63, v63, v63 row_half_mirror row_mask:0xf bank_mask:0xf bound_ctrl:1
	s_nop 1
	v_add_f32_dpp v63, v63, v63 row_mirror row_mask:0xf bank_mask:0xf bound_ctrl:1
	s_nop 0
	v_readlane_b32 s20, v63, 16
	v_readlane_b32 s60, v63, 48
	v_readlane_b32 s58, v63, 0
	v_readlane_b32 s59, v63, 32
	v_mov_b32_e32 v222, s20
	v_mov_b32_e32 v223, s60
	v_add_f32 v222, s58, v222
	v_add_f32 v223, s59, v223
	s_nop 0
	v_add_f32_e32 v63, v222, v223
	v_max_f32_e32 v63, 0x179abe15, v63
	v_rsq_f32_e32 v221, v63
	v_add_f32_e32 v63, 1.0, v85
	v_rcp_f32_e32 v123, v63
	v_rcp_f32_e32 v63, v124
	v_pk_mul_f32 v[222:223], v[218:219], v[220:221]
	v_cvt_pk_bf16_f32 v220, v224, v225
	v_pk_mul_f32 v[218:219], v[226:227], v[222:223] neg_lo:[0,1] neg_hi:[0,1]
	v_lshlrev_b32_e32 v227, 16, v47
	v_lshlrev_b32_e32 v226, 16, v46
	v_lshlrev_b32_e32 v225, 16, v53
	v_lshlrev_b32_e32 v224, 16, v52
	v_pk_mov_b32 v[52:53], v[226:227], v[36:37] op_sel:[1,0]
	v_cvt_pk_bf16_f32 v85, v218, s0
	v_pk_add_f32 v[52:53], v[52:53], v[36:37] neg_lo:[0,1] neg_hi:[0,1]
	ds_write_b16 v5, v85 offset:12256
	v_pk_fma_f32 v[36:37], v[52:53], v[4:5], v[36:37] op_sel_hi:[1,0,1]
	v_mul_f32_e32 v85, v216, v124
	v_cvt_pk_bf16_f32 v216, v219, s0
	v_cvt_pk_bf16_f32 v221, v218, v219
	v_cvt_pk_bf16_f32 v219, v134, v135
	v_lshlrev_b32_e32 v135, 16, v55
	v_cvt_pk_bf16_f32 v55, v36, v37
	v_pk_mov_b32 v[36:37], v[228:229], v[226:227] op_sel:[1,0]
	v_lshlrev_b32_e32 v134, 16, v54
	v_pk_add_f32 v[36:37], v[36:37], v[226:227] neg_lo:[0,1] neg_hi:[0,1]
	v_cvt_pk_bf16_f32 v85, v85, s0
	v_pk_fma_f32 v[36:37], v[36:37], v[4:5], v[226:227] op_sel_hi:[1,0,1]
	ds_write_b16 v5, v216 offset:12400
	v_cvt_pk_bf16_f32 v54, v36, v37
	v_pk_mov_b32 v[36:37], v[224:225], v[228:229] op_sel:[1,0]
	ds_write_b16 v5, v85 offset:2160
	v_pk_add_f32 v[36:37], v[36:37], v[228:229] neg_lo:[0,1] neg_hi:[0,1]
	v_cvt_pk_bf16_f32 v218, v128, v129
	v_pk_fma_f32 v[36:37], v[36:37], v[4:5], v[228:229] op_sel_hi:[1,0,1]
	v_cvt_pk_bf16_f32 v47, v98, v99
	v_cvt_pk_bf16_f32 v53, v36, v37
	v_pk_mov_b32 v[36:37], v[134:135], v[224:225] op_sel:[1,0]
	s_nop 0
	v_pk_add_f32 v[36:37], v[36:37], v[224:225] neg_lo:[0,1] neg_hi:[0,1]
	s_nop 0
	v_pk_fma_f32 v[36:37], v[36:37], v[4:5], v[224:225] op_sel_hi:[1,0,1]
	s_nop 0
	v_cvt_pk_bf16_f32 v52, v36, v37
	v_pk_mov_b32 v[36:37], v[56:57], v[134:135] op_sel:[1,0]
	s_nop 0
	v_pk_add_f32 v[36:37], v[36:37], v[134:135] neg_lo:[0,1] neg_hi:[0,1]
	s_nop 0
	v_pk_fma_f32 v[36:37], v[36:37], v[4:5], v[134:135] op_sel_hi:[1,0,1]
	s_nop 0
	v_cvt_pk_bf16_f32 v59, v36, v37
	v_pk_mov_b32 v[36:37], v[116:117], v[56:57] op_sel:[1,0]
	s_nop 0
	v_pk_add_f32 v[36:37], v[36:37], v[56:57] neg_lo:[0,1] neg_hi:[0,1]
	s_nop 0
	v_pk_fma_f32 v[36:37], v[36:37], v[4:5], v[56:57] op_sel_hi:[1,0,1]
	v_cvt_pk_bf16_f32 v56, v26, v27
	v_cvt_pk_bf16_f32 v58, v36, v37
	v_pk_mov_b32 v[36:37], v[60:61], v[116:117] op_sel:[1,0]
	v_pk_mul_f32 v[26:27], v[76:77], v[96:97]
	v_pk_add_f32 v[36:37], v[36:37], v[116:117] neg_lo:[0,1] neg_hi:[0,1]
	v_pk_mul_f32 v[26:27], v[74:75], v[26:27]
	v_pk_fma_f32 v[36:37], v[36:37], v[4:5], v[116:117] op_sel_hi:[1,0,1]
	s_nop 0
	v_cvt_pk_bf16_f32 v57, v36, v37
	v_cvt_pk_bf16_f32 v36, v26, s0
	ds_write_b32 v143, v124 offset:9984
	ds_write_b128 v144, v[218:221] offset:17168
	ds_write_b128 v144, v[56:59] offset:7936
	ds_write_b128 v144, v[52:55] offset:7952
	ds_write_b16 v5, v36 offset:12832
	v_cvt_pk_bf16_f32 v36, v27, s0
	v_pk_mul_f32 v[26:27], v[124:125], v[26:27] op_sel_hi:[0,1]
	v_cvt_pk_bf16_f32 v53, v26, v27
	v_pk_mul_f32 v[26:27], v[88:89], v[104:105]
	ds_write_b16 v5, v36 offset:12976
	v_pk_mul_f32 v[26:27], v[72:73], v[26:27]
	s_nop 0
	v_cvt_pk_bf16_f32 v36, v26, s0
; #define LAS __attribute__((address_space(3)))
; __device__ __forceinline__ void s2_produce(LAS unsigned char* CB, LAS unsigned char* PSb, LAS unsigned char* APTp, const unsigned (&rw)[16][5], const unsigned (&pv3)[3], int lane,
;         float mur, float muk, float muv, float w0v, float a0v, float kkv, float kav) {
;     ...
;         const float cr = __uint_as_float(rw[t][0] << 16), ck = __uint_as_float(rw[t][1] << 16), cv = __uint_as_float(rw[t][2] << 16);
;         const float lw = __uint_as_float(rw[t][3] << 16), la = __uint_as_float(rw[t][4] << 16);
;         const float r = cr + (pr - cr) * mur, k = ck + (pk - ck) * muk, v = cv + (pv - cv) * muv;
;         pr = cr; pk = ck; pv = cv;
;         const float aic = sigm(a0v + la);
;         const float lam = -0.6065306597126334f * __builtin_amdgcn_rcpf(1.f + __expf(-(w0v + lw)));
;         const float kk = k * kkv; const float ss = wsum64(kk * kk);
;         const float kn = kk * rsqrtf(fmaxf(ss, 1e-24f));
;         const float k2 = k * (1.f + (aic - 1.f) * kav);
;         Lam += lam;
;         const float eL = __expf(Lam), eLm = __builtin_amdgcn_rcpf(eL);
;         const float at = -kn * eP, rt = r * eL, bt = kn * aic * eLm, kt = k2 * eLm;
;         eP = eL;
;         *(LAS bf16_t*)(PSb + S2_AT + t * 144 + lane * 2) = f2bf(at);
;         *(LAS bf16_t*)(PSb + S2_BT + t * 144 + lane * 2) = f2bf(bt);
;         *(LAS bf16_t*)(PSb + S2_KT + t * 144 + lane * 2) = f2bf(kt);
;         *(LAS bf16_t*)(CB + S2_RT + t * 144 + lane * 2) = f2bf(rt);
;         btv[t] = bt; ktv[t] = kt;
;         if (t & 1) { atp[t >> 1] = pk2(hold_a, at); vtp[t >> 1] = pk2(hold_v, v); } else { hold_a = at; hold_v = v; }
;     }
;     const float gC = eP;
;     *(LAS float*)(CB + S2_GC + lane * 4) = gC;
;     { u32x4 w0 = {atp[0], atp[1], atp[2], atp[3]}, w1 = {atp[4], atp[5], atp[6], atp[7]};
;       *(LAS u32x4*)(PSb + S2_ATT + lane * 32) = w0; *(LAS u32x4*)(PSb + S2_ATT + lane * 32 + 16) = w1;
;       u32x4 v0 = {vtp[0], vtp[1], vtp[2], vtp[3]}, v1 = {vtp[4], vtp[5], vtp[6], vtp[7]};
;       *(LAS u32x4*)(CB + S2_VT + lane * 32) = v0; *(LAS u32x4*)(CB + S2_VT + lane * 32 + 16) = v1;
;       u32x4 b0, b1, k0, k1;
;       b0.x = pk2(btv[0] * gC, btv[1] * gC); b0.y = pk2(btv[2] * gC, btv[3] * gC); b0.z = pk2(btv[4] * gC, btv[5] * gC); b0.w = pk2(btv[6] * gC, btv[7] * gC);
	ds_write_b16 v5, v36 offset:13120
	v_cvt_pk_bf16_f32 v36, v27, s0
	v_pk_mul_f32 v[26:27], v[124:125], v[26:27] op_sel_hi:[0,1]
	v_cvt_pk_bf16_f32 v54, v26, v27
	v_pk_mul_f32 v[26:27], v[92:93], v[110:111]
	ds_write_b16 v5, v36 offset:13264
	v_pk_mul_f32 v[26:27], v[70:71], v[26:27]
	s_nop 0
	v_cvt_pk_bf16_f32 v36, v26, s0
	ds_write_b16 v5, v36 offset:13408
	v_cvt_pk_bf16_f32 v36, v27, s0
	v_pk_mul_f32 v[26:27], v[124:125], v[26:27] op_sel_hi:[0,1]
	v_cvt_pk_bf16_f32 v55, v26, v27
	v_pk_mul_f32 v[26:27], v[100:101], v[118:119]
	ds_write_b16 v5, v36 offset:13552
	v_pk_mul_f32 v[26:27], v[68:69], v[26:27]
	s_nop 0
	v_cvt_pk_bf16_f32 v36, v26, s0
	ds_write_b16 v5, v36 offset:13696
	v_cvt_pk_bf16_f32 v36, v27, s0
	v_pk_mul_f32 v[26:27], v[124:125], v[26:27] op_sel_hi:[0,1]
	v_cvt_pk_bf16_f32 v56, v26, v27
	v_pk_mul_f32 v[26:27], v[106:107], v[126:127]
	ds_write_b16 v5, v36 offset:13840
	v_pk_mul_f32 v[26:27], v[66:67], v[26:27]
	s_nop 0
	v_cvt_pk_bf16_f32 v36, v26, s0
	ds_write_b16 v5, v36 offset:13984
	v_cvt_pk_bf16_f32 v36, v27, s0
	v_pk_mul_f32 v[26:27], v[124:125], v[26:27] op_sel_hi:[0,1]
	v_cvt_pk_bf16_f32 v57, v26, v27
	v_pk_mul_f32 v[26:27], v[114:115], v[132:133]
	ds_write_b16 v5, v36 offset:14128
	v_pk_mul_f32 v[26:27], v[64:65], v[26:27]
	s_nop 0
	v_cvt_pk_bf16_f32 v36, v26, s0
	ds_write_b16 v5, v36 offset:14272
	v_cvt_pk_bf16_f32 v36, v27, s0
	v_pk_mul_f32 v[26:27], v[124:125], v[26:27] op_sel_hi:[0,1]
	v_cvt_pk_bf16_f32 v58, v26, v27
	v_pk_mul_f32 v[26:27], v[122:123], v[222:223]
	ds_write_b16 v5, v36 offset:14416
	v_pk_mul_f32 v[26:27], v[62:63], v[26:27]
	s_nop 0
	v_cvt_pk_bf16_f32 v36, v26, s0
	ds_write_b16 v5, v36 offset:14560
	v_cvt_pk_bf16_f32 v36, v27, s0
	v_pk_mul_f32 v[26:27], v[124:125], v[26:27] op_sel_hi:[0,1]
	v_cvt_pk_bf16_f32 v59, v26, v27
	v_pk_mov_b32 v[26:27], v[82:83], v[84:85] op_sel:[1,0]
	ds_write_b16 v5, v36 offset:14704
	v_pk_add_f32 v[36:37], v[82:83], v[26:27] neg_lo:[0,1] neg_hi:[0,1]
	s_nop 0
	v_pk_fma_f32 v[26:27], v[36:37], v[2:3], v[26:27] op_sel_hi:[1,0,1]
	v_pk_add_f32 v[36:37], v[80:81], -1.0 op_sel_hi:[1,0]
	s_waitcnt vmcnt(0)
	v_pk_fma_f32 v[36:37], v[8:9], v[36:37], 1.0 op_sel_hi:[0,1,0]
	v_pk_mul_f32 v[36:37], v[26:27], v[36:37]
	v_pk_mul_f32 v[26:27], v[6:7], v[26:27] op_sel_hi:[0,1]
	v_pk_mul_f32 v[60:61], v[26:27], v[26:27]
	v_pk_mul_f32 v[36:37], v[36:37], v[78:79]
	s_nop 0
	v_add_f32_dpp v52, v60, v60 quad_perm:[1,0,3,2] row_mask:0xf bank_mask:0xf bound_ctrl:1
	v_cvt_pk_bf16_f32 v46, v36, s0
	ds_write_b16 v5, v46 offset:14848
	v_add_f32_dpp v52, v52, v52 quad_perm:[2,3,0,1] row_mask:0xf bank_mask:0xf bound_ctrl:1
	v_cvt_pk_bf16_f32 v46, v37, s0
	ds_write_b16 v5, v46 offset:14992
	v_add_f32_dpp v52, v52, v52 row_half_mirror row_mask:0xf bank_mask:0xf bound_ctrl:1
	s_nop 1
	v_add_f32_dpp v52, v52, v52 row_mirror row_mask:0xf bank_mask:0xf bound_ctrl:1
	s_nop 0
	v_readlane_b32 s20, v52, 16
	v_readlane_b32 s60, v52, 48
	v_readlane_b32 s58, v52, 0
	v_readlane_b32 s59, v52, 32
	v_mov_b32_e32 v82, s20
	v_mov_b32_e32 v83, s60
	v_add_f32 v82, s58, v82
	v_add_f32 v83, s59, v83
	s_nop 0
	v_add_f32_e32 v52, v82, v83
	v_max_f32_e32 v52, 0x179abe15, v52
	v_rsq_f32_e32 v60, v52
	s_nop 0
	v_add_f32_dpp v52, v61, v61 quad_perm:[1,0,3,2] row_mask:0xf bank_mask:0xf bound_ctrl:1
	s_nop 1
	v_add_f32_dpp v52, v52, v52 quad_perm:[2,3,0,1] row_mask:0xf bank_mask:0xf bound_ctrl:1
	s_nop 1
	v_add_f32_dpp v52, v52, v52 row_half_mirror row_mask:0xf bank_mask:0xf bound_ctrl:1
	s_nop 1
	v_add_f32_dpp v52, v52, v52 row_mirror row_mask:0xf bank_mask:0xf bound_ctrl:1
	s_nop 0
	v_readlane_b32 s20, v52, 16
	v_readlane_b32 s60, v52, 48
	v_readlane_b32 s58, v52, 0
	v_readlane_b32 s59, v52, 32
	v_mov_b32_e32 v82, s20
	v_mov_b32_e32 v83, s60
	v_add_f32 v82, s58, v82
	v_add_f32 v83, s59, v83
	s_nop 0
	v_add_f32_e32 v52, v82, v83
	v_max_f32_e32 v52, 0x179abe15, v52
	v_rsq_f32_e32 v61, v52
	s_nop 0
	v_pk_mul_f32 v[26:27], v[26:27], v[60:61]
	s_nop 0
	v_pk_mul_f32 v[60:61], v[80:81], v[26:27]
	v_xor_b32_e32 v46, 0x80000000, v26
	v_pk_mul_f32 v[60:61], v[78:79], v[60:61]
	v_cvt_pk_bf16_f32 v52, -v26, s0
	v_cvt_pk_bf16_f32 v26, v60, s0
	ds_write_b16 v5, v26 offset:12544
	v_mul_f32_e64 v26, v217, -v27
	v_cvt_pk_bf16_f32 v27, v26, s0
	ds_write_b16 v5, v27 offset:10384
	v_cvt_pk_bf16_f32 v27, v61, s0
	ds_write_b16 v5, v27 offset:12688
	v_cvt_pk_bf16_f32 v46, v46, v26
	v_pk_mul_f32 v[26:27], v[124:125], v[60:61] op_sel_hi:[0,1]
	ds_write_b16 v5, v52 offset:10240
	v_cvt_pk_bf16_f32 v52, v26, v27
	v_pk_mul_f32 v[26:27], v[36:37], v[124:125] op_sel_hi:[1,0]
	ds_write_b128 v144, v[46:49] offset:17152
	v_cvt_pk_bf16_f32 v46, v26, v27
	v_pk_add_f32 v[26:27], v[76:77], -1.0 op_sel_hi:[1,0]
	s_nop 0
	v_pk_fma_f32 v[26:27], v[8:9], v[26:27], 1.0 op_sel_hi:[0,1,0]
	v_pk_mul_f32 v[26:27], v[86:87], v[26:27]
	s_nop 0
	v_pk_mul_f32 v[26:27], v[26:27], v[74:75]
	s_nop 0
	v_cvt_pk_bf16_f32 v36, v26, s0
	ds_write_b16 v5, v36 offset:15136
	v_cvt_pk_bf16_f32 v36, v27, s0
	v_pk_mul_f32 v[26:27], v[26:27], v[124:125] op_sel_hi:[1,0]
	ds_write_b16 v5, v36 offset:15280
	v_cvt_pk_bf16_f32 v47, v26, v27
	v_pk_add_f32 v[26:27], v[88:89], -1.0 op_sel_hi:[1,0]
	s_nop 0
	v_pk_fma_f32 v[26:27], v[8:9], v[26:27], 1.0 op_sel_hi:[0,1,0]
	v_pk_mul_f32 v[26:27], v[90:91], v[26:27]
	s_nop 0
	v_pk_mul_f32 v[26:27], v[26:27], v[72:73]
	s_nop 0
	v_cvt_pk_bf16_f32 v36, v26, s0
	ds_write_b16 v5, v36 offset:15424
	v_cvt_pk_bf16_f32 v36, v27, s0
	v_pk_mul_f32 v[26:27], v[26:27], v[124:125] op_sel_hi:[1,0]
	ds_write_b16 v5, v36 offset:15568
	v_cvt_pk_bf16_f32 v48, v26, v27
	v_pk_add_f32 v[26:27], v[92:93], -1.0 op_sel_hi:[1,0]
	s_nop 0
	v_pk_fma_f32 v[26:27], v[8:9], v[26:27], 1.0 op_sel_hi:[0,1,0]
; #define LAS __attribute__((address_space(3)))
; __device__ __forceinline__ void s2_produce(LAS unsigned char* CB, LAS unsigned char* PSb, LAS unsigned char* APTp, const unsigned (&rw)[16][5], const unsigned (&pv3)[3], int lane,
;         float mur, float muk, float muv, float w0v, float a0v, float kkv, float kav) {
;     ...
;       b0.x = pk2(btv[0] * gC, btv[1] * gC); b0.y = pk2(btv[2] * gC, btv[3] * gC); b0.z = pk2(btv[4] * gC, btv[5] * gC); b0.w = pk2(btv[6] * gC, btv[7] * gC);
;       b1.x = pk2(btv[8] * gC, btv[9] * gC); b1.y = pk2(btv[10] * gC, btv[11] * gC); b1.z = pk2(btv[12] * gC, btv[13] * gC); b1.w = pk2(btv[14] * gC, btv[15] * gC);
;       k0.x = pk2(ktv[0] * gC, ktv[1] * gC); k0.y = pk2(ktv[2] * gC, ktv[3] * gC); k0.z = pk2(ktv[4] * gC, ktv[5] * gC); k0.w = pk2(ktv[6] * gC, ktv[7] * gC);
;       k1.x = pk2(ktv[8] * gC, ktv[9] * gC); k1.y = pk2(ktv[10] * gC, ktv[11] * gC); k1.z = pk2(ktv[12] * gC, ktv[13] * gC); k1.w = pk2(ktv[14] * gC, ktv[15] * gC);
;       *(LAS u32x4*)(CB + S2_B2T + lane * 32) = b0; *(LAS u32x4*)(CB + S2_B2T + lane * 32 + 16) = b1;
;       *(LAS u32x4*)(CB + S2_K2T + lane * 32) = k0; *(LAS u32x4*)(CB + S2_K2T + lane * 32 + 16) = k1; }
;     asm volatile("" ::: "memory");
;     const f32x4 z4 = {0.f, 0.f, 0.f, 0.f};
;     f32x4 dN = mm64(PSb + S2_BT, PSb + S2_AT, z4, l15, g4);
;     f32x4 dAak = mm64(PSb + S2_KT, PSb + S2_AT, z4, l15, g4);
;     f32x4 dBr = mm64(PSb + S2_BT, CB + S2_RT, z4, l15, g4);
;     f32x4 dKr = mm64(PSb + S2_KT, CB + S2_RT, z4, l15, g4);
;     f32x4 P;
; #pragma unroll
;     for (int i = 0; i < 4; ++i) { const int sidx = 4 * g4 + i;
;         dN[i] = (sidx < l15) ? dN[i] : 0.f; dAak[i] = (sidx < l15) ? dAak[i] : 0.f;
;         dBr[i] = (sidx <= l15) ? dBr[i] : 0.f; dKr[i] = (sidx <= l15) ? dKr[i] : 0.f;
;         P[i] = dN[i] + ((sidx == l15) ? 1.f : 0.f); }
;     asm volatile("s_waitcnt lgkmcnt(0)" ::: "memory");
;     st_RM(PSb + S2_N, dN, l15, g4); st_T(PSb + S2_NT, 32, dN, l15, g4); st_RM(PSb + S2_AAK, dAak, l15, g4);
;     st_T(CB + S2_BRT, 32, dBr, l15, g4); st_T(CB + S2_KRT, 32, dKr, l15, g4);
;     st_RM(PSb + S2_P, P, l15, g4);
;     asm volatile("" ::: "memory");
;     const f32x4 n2 = mm16(PSb + S2_N, PSb + S2_NT, z4, l15, g4);
	v_pk_mul_f32 v[26:27], v[94:95], v[26:27]
	s_nop 0
	v_pk_mul_f32 v[26:27], v[26:27], v[70:71]
	s_nop 0
	v_cvt_pk_bf16_f32 v36, v26, s0
	ds_write_b16 v5, v36 offset:15712
	v_cvt_pk_bf16_f32 v36, v27, s0
	v_pk_mul_f32 v[26:27], v[26:27], v[124:125] op_sel_hi:[1,0]
	ds_write_b16 v5, v36 offset:15856
	v_cvt_pk_bf16_f32 v49, v26, v27
	v_pk_add_f32 v[26:27], v[100:101], -1.0 op_sel_hi:[1,0]
	s_nop 0
	v_pk_fma_f32 v[26:27], v[8:9], v[26:27], 1.0 op_sel_hi:[0,1,0]
	v_pk_mul_f32 v[26:27], v[102:103], v[26:27]
	s_nop 0
	v_pk_mul_f32 v[26:27], v[26:27], v[68:69]
	s_nop 0
	v_cvt_pk_bf16_f32 v36, v26, s0
	ds_write_b16 v5, v36 offset:16000
	v_cvt_pk_bf16_f32 v36, v27, s0
	v_pk_mul_f32 v[26:27], v[26:27], v[124:125] op_sel_hi:[1,0]
	ds_write_b16 v5, v36 offset:16144
	v_cvt_pk_bf16_f32 v68, v26, v27
	v_pk_add_f32 v[26:27], v[106:107], -1.0 op_sel_hi:[1,0]
	s_nop 0
	v_pk_fma_f32 v[26:27], v[8:9], v[26:27], 1.0 op_sel_hi:[0,1,0]
	v_pk_mul_f32 v[26:27], v[112:113], v[26:27]
	s_nop 0
	v_pk_mul_f32 v[26:27], v[26:27], v[66:67]
	s_nop 0
	v_cvt_pk_bf16_f32 v36, v26, s0
	ds_write_b16 v5, v36 offset:16288
	v_cvt_pk_bf16_f32 v36, v27, s0
	v_pk_mul_f32 v[26:27], v[26:27], v[124:125] op_sel_hi:[1,0]
	ds_write_b16 v5, v36 offset:16432
	v_cvt_pk_bf16_f32 v69, v26, v27
	v_pk_add_f32 v[26:27], v[114:115], -1.0 op_sel_hi:[1,0]
	s_nop 0
	v_pk_fma_f32 v[26:27], v[8:9], v[26:27], 1.0 op_sel_hi:[0,1,0]
	v_pk_mul_f32 v[26:27], v[120:121], v[26:27]
	s_nop 0
	v_pk_mul_f32 v[26:27], v[26:27], v[64:65]
	s_nop 0
	v_cvt_pk_bf16_f32 v36, v26, s0
	ds_write_b16 v5, v36 offset:16576
	v_cvt_pk_bf16_f32 v36, v27, s0
	v_pk_mul_f32 v[26:27], v[26:27], v[124:125] op_sel_hi:[1,0]
	ds_write_b16 v5, v36 offset:16720
	v_cvt_pk_bf16_f32 v70, v26, v27
	v_pk_add_f32 v[26:27], v[122:123], -1.0 op_sel_hi:[1,0]
	s_nop 0
	v_pk_fma_f32 v[26:27], v[8:9], v[26:27], 1.0 op_sel_hi:[0,1,0]
	v_pk_mul_f32 v[26:27], v[130:131], v[26:27]
	s_nop 0
	v_pk_mul_f32 v[26:27], v[26:27], v[62:63]
	s_nop 0
	v_cvt_pk_bf16_f32 v36, v26, s0
	ds_write_b16 v5, v36 offset:16864
	v_cvt_pk_bf16_f32 v36, v27, s0
	v_pk_mul_f32 v[26:27], v[124:125], v[26:27] op_sel_hi:[0,1]
	ds_write_b16 v5, v36 offset:17008
	v_cvt_pk_bf16_f32 v71, v26, v27
	ds_write_b128 v144, v[52:55] offset:3840
	ds_write_b128 v144, v[56:59] offset:3856
	ds_write_b128 v144, v[46:49] offset:5888
	ds_write_b128 v144, v[68:71] offset:5904
	ds_read_b128 v[46:49], v145 offset:12544
	ds_read_b128 v[52:55], v145 offset:12608
	ds_read_b128 v[56:59], v145 offset:10240
	ds_read_b128 v[60:63], v145 offset:10304
	ds_read_b128 v[68:71], v145 offset:14848
	ds_read_b128 v[72:75], v145 offset:14912
	s_waitcnt lgkmcnt(3)
	v_mfma_f32_16x16x32_bf16 v[64:67], v[46:49], v[56:59], 0
	s_waitcnt lgkmcnt(1)
	v_mfma_f32_16x16x32_bf16 v[56:59], v[68:71], v[56:59], 0
	v_mfma_f32_16x16x32_bf16 v[64:67], v[52:55], v[60:63], v[64:67]
	s_waitcnt lgkmcnt(0)
	v_mfma_f32_16x16x32_bf16 v[56:59], v[72:75], v[60:63], v[56:59]
	ds_read_b128 v[60:63], v145
	ds_read_b128 v[76:79], v145 offset:64
	s_nop 3
	v_cndmask_b32_e64 v26, 0, v64, s[4:5]
	v_cndmask_b32_e64 v27, 0, v65, s[8:9]
	s_waitcnt lgkmcnt(1)
	v_mfma_f32_16x16x32_bf16 v[46:49], v[46:49], v[60:63], 0
	v_cvt_pk_bf16_f32 v64, v26, s0
	s_waitcnt lgkmcnt(0)
	ds_write_b16 v146, v64 offset:10240
	s_waitcnt lgkmcnt(1)
	v_mfma_f32_16x16x32_bf16 v[46:49], v[52:55], v[76:79], v[46:49]
	v_cvt_pk_bf16_f32 v64, v27, s0
	ds_write_b16 v146, v64 offset:10272
	v_mfma_f32_16x16x32_bf16 v[52:55], v[68:71], v[60:63], 0
	v_cndmask_b32_e64 v60, 0, v66, s[10:11]
	v_cndmask_b32_e64 v62, 0, v67, s[14:15]
	s_nop 2
	v_cndmask_b32_e64 v36, v46, 0, s[6:7]
	v_mfma_f32_16x16x32_bf16 v[52:55], v[72:75], v[76:79], v[52:55]
	v_add_f32_e32 v46, v9, v26
	v_cvt_pk_bf16_f32 v26, v26, v27
	v_cndmask_b32_e64 v61, v48, 0, s[12:13]
	v_cndmask_b32_e64 v63, v49, 0, s[16:17]
	v_add_f32_e32 v48, v136, v60
	s_nop 2
	v_cndmask_b32_e64 v37, v52, 0, s[6:7]
	v_cndmask_b32_e64 v52, 0, v47, s[4:5]
	v_add_f32_e32 v47, v125, v27
	v_cvt_pk_bf16_f32 v27, v60, v62
	ds_write_b64 v147, v[26:27] offset:10752
	v_cvt_pk_bf16_f32 v26, v56, s0
	v_cndmask_b32_e64 v26, 0, v26, s[4:5]
	ds_write_b16 v146, v26 offset:14336
	v_cvt_pk_bf16_f32 v26, v57, s0
	v_cndmask_b32_e64 v26, 0, v26, s[8:9]
	ds_write_b16 v146, v26 offset:14368
	v_cvt_pk_bf16_f32 v26, v58, s0
	v_cndmask_b32_e64 v26, 0, v26, s[10:11]
	ds_write_b16 v146, v26 offset:14400
	v_cvt_pk_bf16_f32 v26, v59, s0
	v_cndmask_b32_e64 v53, 0, v53, s[4:5]
	v_cndmask_b32_e64 v54, v54, 0, s[12:13]
	v_cndmask_b32_e64 v55, v55, 0, s[16:17]
	v_cndmask_b32_e64 v26, 0, v26, s[14:15]
	ds_write_b16 v146, v26 offset:14432
	v_cvt_pk_bf16_f32 v26, v36, v52
	v_cvt_pk_bf16_f32 v27, v61, v63
	v_cvt_pk_bf16_f32 v36, v37, v53
	v_cvt_pk_bf16_f32 v37, v54, v55
	v_add_u32_e32 v52, 0x100, v147
	ds_write2st64_b64 v52, v[26:27], v[36:37] offset0:5 offset1:6
	v_cvt_pk_bf16_f32 v26, v46, s0
	ds_write_b16 v146, v26 offset:13824
	v_cvt_pk_bf16_f32 v26, v47, s0
	v_add_f32_e32 v49, v138, v62
	v_cvt_pk_bf16_f32 v64, v60, s0
	ds_write_b16 v146, v26 offset:13856
	v_cvt_pk_bf16_f32 v26, v48, s0
	ds_write_b16 v146, v64 offset:10304
	v_cvt_pk_bf16_f32 v64, v62, s0
	ds_write_b16 v146, v26 offset:13888
	v_cvt_pk_bf16_f32 v26, v49, s0
	ds_write_b16 v146, v64 offset:10336
	ds_write_b16 v146, v26 offset:13920
	ds_read2st64_b64 v[52:55], v147 offset0:20 offset1:21
	s_waitcnt lgkmcnt(0)
; __device__ __forceinline__ void s2_produce(LAS unsigned char* CB, LAS unsigned char* PSb, LAS unsigned char* APTp, const unsigned (&rw)[16][5], const unsigned (&pv3)[3], int lane,
;         float mur, float muk, float muv, float w0v, float a0v, float kkv, float kav) {
;     ...
;     const f32x4 n2 = mm16(PSb + S2_N, PSb + S2_NT, z4, l15, g4);
;     asm volatile("" ::: "memory");
;     st_RM(PSb + S2_N2, n2, l15, g4); st_T(PSb + S2_N2T, 32, n2, l15, g4);
;     asm volatile("" ::: "memory");
;     P = mm16(PSb + S2_P, PSb + S2_N2T, P, l15, g4);
;     asm volatile("s_waitcnt lgkmcnt(0)" ::: "memory");
;     st_RM(PSb + S2_P, P, l15, g4);
;     asm volatile("" ::: "memory");
;     const f32x4 n4 = mm16(PSb + S2_N2, PSb + S2_N2T, z4, l15, g4);
;     asm volatile("" ::: "memory");
;     st_RM(PSb + S2_N4, n4, l15, g4); st_T(PSb + S2_N4T, 32, n4, l15, g4);
;     asm volatile("" ::: "memory");
;     P = mm16(PSb + S2_P, PSb + S2_N4T, P, l15, g4);
;     asm volatile("s_waitcnt lgkmcnt(0)" ::: "memory");
;     st_RM(PSb + S2_P, P, l15, g4);
;     asm volatile("" ::: "memory");
;     const f32x4 n8 = mm16(PSb + S2_N4, PSb + S2_N4T, z4, l15, g4);
;     asm volatile("" ::: "memory");
;     st_T(PSb + S2_N8T, 32, n8, l15, g4);
;     asm volatile("" ::: "memory");
;     const f32x4 Tm = mm16(PSb + S2_P, PSb + S2_N8T, P, l15, g4);
;     asm volatile("" ::: "memory");
;     st_T(PSb + S2_TT, 32, Tm, l15, g4);
;     asm volatile("" ::: "memory");
;     const f32x4 W = mm16(PSb + S2_AAK, PSb + S2_TT, z4, l15, g4);
;     asm volatile("" ::: "memory");
;     st_T(CB + S2_WT, 32, W, l15, g4);
; #pragma unroll
;     for (int kt = 0; kt < 4; ++kt) {
;         const f32x4 ap = mm16(PSb + S2_ATT + kt * 512, PSb + S2_TT, z4, l15, g4);
;         st_T(APTp + kt * 32, 144, ap, l15, g4);
;     }
; }
; __device__ __forceinline__ unsigned char* s2_block(unsigned char* ws, float* out, int c) {
;     if (c < 10699) return ws + WS_RC + (size_t)c * S2_CHB;
;     c -= 10699; if (c < 8024) return ws + WS_RA + (size_t)416 * MiB + (size_t)c * S2_CHB;
;     c -= 8024; if (c < 5349) return (unsigned char*)out + (size_t)192 * MiB + (size_t)c * S2_CHB;
;     c -= 5349; if (c < 2674) return ws + WS_LORAA + (size_t)c * S2_CHB;
;     c -= 2674; return ws + WS_END + (size_t)c * S2_CHB;
; }
	v_mfma_f32_16x16x16_bf16 v[52:55], v[52:53], v[54:55], 0
	v_add_u32_e32 v56, v7, v139
	s_nop 6
	v_cvt_pk_bf16_f32 v26, v52, s0
	ds_write_b16 v146, v26 offset:11264
	v_cvt_pk_bf16_f32 v26, v53, s0
	ds_write_b16 v146, v26 offset:11296
	v_cvt_pk_bf16_f32 v26, v54, s0
	ds_write_b16 v146, v26 offset:11328
	v_cvt_pk_bf16_f32 v26, v55, s0
	ds_write_b16 v146, v26 offset:11360
	v_cvt_pk_bf16_f32 v26, v52, v53
	v_cvt_pk_bf16_f32 v27, v54, v55
	ds_write_b64 v147, v[26:27] offset:11776
	ds_read2st64_b64 v[52:55], v147 offset0:23 offset1:27
	s_waitcnt lgkmcnt(0)
	v_mfma_f32_16x16x16_bf16 v[46:49], v[54:55], v[52:53], v[46:49]
	s_waitcnt lgkmcnt(0)
	s_nop 7
	v_cvt_pk_bf16_f32 v26, v46, s0
	ds_write_b16 v146, v26 offset:13824
	v_cvt_pk_bf16_f32 v26, v47, s0
	ds_write_b16 v146, v26 offset:13856
	v_cvt_pk_bf16_f32 v26, v48, s0
	ds_write_b16 v146, v26 offset:13888
	v_cvt_pk_bf16_f32 v26, v49, s0
	ds_write_b16 v146, v26 offset:13920
	ds_read2st64_b64 v[52:55], v147 offset0:22 offset1:23
	s_waitcnt lgkmcnt(0)
	v_mfma_f32_16x16x16_bf16 v[52:55], v[52:53], v[54:55], 0
	s_nop 7
	v_cvt_pk_bf16_f32 v26, v52, s0
	ds_write_b16 v146, v26 offset:12288
	v_cvt_pk_bf16_f32 v26, v53, s0
	ds_write_b16 v146, v26 offset:12320
	v_cvt_pk_bf16_f32 v26, v54, s0
	ds_write_b16 v146, v26 offset:12352
	v_cvt_pk_bf16_f32 v26, v55, s0
	ds_write_b16 v146, v26 offset:12384
	v_cvt_pk_bf16_f32 v26, v52, v53
	v_cvt_pk_bf16_f32 v27, v54, v55
	ds_write_b64 v147, v[26:27] offset:12800
	ds_read2st64_b64 v[52:55], v147 offset0:25 offset1:27
	s_waitcnt lgkmcnt(0)
	v_mfma_f32_16x16x16_bf16 v[46:49], v[54:55], v[52:53], v[46:49]
	s_waitcnt lgkmcnt(0)
	s_nop 7
	v_cvt_pk_bf16_f32 v26, v46, s0
	ds_write_b16 v146, v26 offset:13824
	v_cvt_pk_bf16_f32 v26, v47, s0
	ds_write_b16 v146, v26 offset:13856
	v_cvt_pk_bf16_f32 v26, v48, s0
	ds_write_b16 v146, v26 offset:13888
	v_cvt_pk_bf16_f32 v26, v49, s0
	ds_write_b16 v146, v26 offset:13920
	ds_read2st64_b64 v[52:55], v147 offset0:24 offset1:25
	s_waitcnt lgkmcnt(0)
	v_mfma_f32_16x16x16_bf16 v[52:55], v[52:53], v[54:55], 0
	s_nop 7
	v_cvt_pk_bf16_f32 v26, v52, v53
	v_cvt_pk_bf16_f32 v27, v54, v55
	ds_write_b64 v147, v[26:27] offset:13312
	ds_read2st64_b64 v[52:55], v147 offset0:26 offset1:27
	s_waitcnt lgkmcnt(0)
	v_mfma_f32_16x16x16_bf16 v[46:49], v[54:55], v[52:53], v[46:49]
	s_nop 7
	v_cvt_pk_bf16_f32 v26, v46, v47
	v_cvt_pk_bf16_f32 v27, v48, v49
	ds_write_b64 v147, v[26:27] offset:14848
	ds_read2st64_b64 v[46:49], v147 offset0:28 offset1:29
	ds_read_b64 v[26:27], v147 offset:17152
	ds_read_b64 v[36:37], v147 offset:14848
	s_waitcnt lgkmcnt(0)
	v_mfma_f32_16x16x16_bf16 v[52:55], v[26:27], v[36:37], 0
	v_mfma_f32_16x16x16_bf16 v[46:49], v[46:47], v[48:49], 0
	s_nop 6
	v_cvt_pk_bf16_f32 v26, v52, v53
	v_cvt_pk_bf16_f32 v27, v54, v55
	ds_write_b64 v56, v[26:27] offset:10240
	ds_read_b64 v[26:27], v147 offset:17664
	s_waitcnt lgkmcnt(0)
	v_mfma_f32_16x16x16_bf16 v[52:55], v[26:27], v[36:37], 0
	v_cvt_pk_bf16_f32 v46, v46, v47
	v_cvt_pk_bf16_f32 v47, v48, v49
	ds_write_b64 v147, v[46:47] offset:2304
	s_nop 4
	v_cvt_pk_bf16_f32 v26, v52, v53
	v_cvt_pk_bf16_f32 v27, v54, v55
	ds_write_b64 v56, v[26:27] offset:10272
	ds_read_b64 v[26:27], v147 offset:18176
	s_waitcnt lgkmcnt(0)
	v_mfma_f32_16x16x16_bf16 v[52:55], v[26:27], v[36:37], 0
	s_nop 7
	v_cvt_pk_bf16_f32 v26, v52, v53
	v_cvt_pk_bf16_f32 v27, v54, v55
	ds_write_b64 v56, v[26:27] offset:10304
	ds_read_b64 v[26:27], v147 offset:18688
	s_waitcnt lgkmcnt(0)
	v_mfma_f32_16x16x16_bf16 v[46:49], v[26:27], v[36:37], 0
	s_nop 7
	v_cvt_pk_bf16_f32 v26, v46, v47
	v_cvt_pk_bf16_f32 v27, v48, v49
	ds_write_b64 v56, v[26:27] offset:10336
	s_waitcnt lgkmcnt(0)
	s_cbranch_scc0 .LBB0_799
	s_cmpk_gt_u32 s67, 0x4922
	s_cbranch_scc0 .LBB0_796
	s_cmpk_gt_u32 s67, 0x5e07
	s_cbranch_scc0 .LBB0_793
	s_cmpk_gt_u32 s67, 0x6879
	s_mov_b64 s[60:61], -1
	s_cbranch_scc0 .LBB0_790
	s_add_i32 s20, s67, 0xffff9786
	s_mov_b64 s[60:61], 0
	s_mov_b64 s[58:59], s[20:21]

; __device__ __forceinline__ void nsa_phase(LAS unsigned char* lds, const Args& a, const bf16_t* z, const bf16_t* KC, const bf16_t* VCT, const bf16_t* VST, const bf16_t* VWT, bf16_t* A2, int ldo, bool merged) {
;     ...
;         const int bg = unit & 31, qt = ((unit >> 8) & 1) ? ((unit >> 5) ^ 7) : (unit >> 5), b = bg >> 1, g = bg & 1, t0 = qt * 64, cur = qt;
;         const int hq = g * 4 + hr;
;         const float slope = exp2f(-(float)(hq + 1)) * 1.4426950408889634f;
;         const size_t row0 = (size_t)b * SEQ + t0;
;         int l15 = l15_, g4 = g4_; asm volatile("" : "+v"(l15), "+v"(g4));
;         int tidv = tid; asm volatile("" : "+v"(tidv));
;         unsigned kt_off = NS_KT + l15 * 144 + g4 * 16, vt_off = NS_VT + l15 * 144 + g4 * 8;
;         unsigned kcl_off = NS_KCL + l15 * 144 + g4 * 16, vcl_off = NS_VCL + l15 * 528 + g4 * 8;
;         asm volatile("" : "+v"(kcl_off), "+v"(vcl_off));
;         __syncthreads();
;         if (!kc_resident) {
; #pragma unroll
;             for (int it = 0; it < 4; ++it) {
;                 const int row = it * 64 + (tid >> 3), ch = tid & 7;
;                 *(LAS u32x4*)(lds + NS_KCL + row * 144 + ch * 16) = *(const u32x4*)(KC + ((size_t)bg * 256 + row) * 256 + ch * 8);
;                 const int dim = tid >> 3, c16 = (tid & 7) + 8 * it;
;                 *(LAS u32x4*)(lds + NS_VCL + dim * 528 + c16 * 16) = *(const u32x4*)(VCT + ((size_t)bg * 64 + dim) * 256 + c16 * 8);
;             }
;         }
;         if (tid == 0) { UNI[0] = 0u; UNI[1] = 0u; }
;         bf16x8 Qf[2][2]; int tq[2]; float gate[2][3];
; #pragma unroll
;         for (int qs = 0; qs < 2; ++qs) {
;             const int ql = qh * 32 + qs * 16 + l15; tq[qs] = t0 + ql;
;             const bf16_t* zr = z + (row0 + ql) * ZLD;
;             Qf[qs][0] = *(const bf16x8*)(zr + ZQ + hq * 64 + g4 * 8);
;             Qf[qs][1] = *(const bf16x8*)(zr + ZQ + hq * 64 + 32 + g4 * 8);
; #pragma unroll
;             for (int br = 0; br < 3; ++br) gate[qs][br] = sigm(bf2f(zr[ZGT + hq * 3 + br]) + gbias[hq * 3 + br]);
;     ...
;             for (int tl = 0; tl < 4; ++tl) {
;                 if (tl <= tlmax) {
; #pragma unroll
;                     for (int s = 0; s < 4; ++s) {
;                         const LAS unsigned char* kp = lds + kcl_off + (tl * 64 + s * 16) * 144;
;                         const bf16x8 k0 = *(const LAS bf16x8*)kp, k1 = *(const LAS bf16x8*)(kp + 64);
.LBB0_913:
	v_mov_b32_e32 v228, s56
	v_mov_b32_e32 v229, s57
	v_mov_b32_e32 v232, s88
	v_mov_b32_e32 v233, s89
	v_mov_b32_e32 v236, s20
	v_mov_b32_e32 v237, s21
	v_mov_b32_e32 v238, s54
	v_mov_b32_e32 v239, s55
	v_mov_b32_e32 v240, s80
	v_mov_b32_e32 v241, s81
	v_mov_b32_e32 v242, s44
	v_mov_b32_e32 v243, s45
	v_mov_b32_e32 v244, s40
	v_mov_b32_e32 v245, s41
	v_mov_b32_e32 v248, s90
	v_mov_b32_e32 v249, s91
	v_mov_b32_e32 v250, s58
	v_mov_b32_e32 v251, s59
	v_mov_b32_e32 v170, v157
	v_mov_b32_e32 v136, v159
	s_movk_i32 s0, 0x210
	v_mul_lo_u32 v134, v170, s83
	v_lshl_add_u32 v135, v136, 4, v134
	v_lshlrev_b32_e32 v112, 3, v136
	v_mul_lo_u32 v1, v170, s0
	s_mov_b32 s0, 0x9000
	v_mov_b32_e32 v130, v156
	v_add3_u32 v119, v1, v112, s0
	v_mov_b32_e32 v1, v135
	s_waitcnt lgkmcnt(0)
	s_barrier
	s_mov_b64 s[0:1], exec
	v_readlane_b32 s6, v247, 1
	v_readlane_b32 s7, v247, 2
	s_and_b64 s[6:7], s[0:1], s[6:7]
	s_mov_b64 exec, s[6:7]
	v_mov_b32_e32 v2, s82
	ds_write_b64 v2, v[168:169]
	s_or_b64 exec, exec, s[0:1]
	s_lshl_b32 s0, s62, 8
	s_cmp_lt_u32 s62, 8
	s_cselect_b32 s0, s0, 0x680
	s_add_i32 s0, s0, s2
	s_and_b32 s1, s0, 0x100
	s_bfe_u32 s0, s0, 0x60005
	s_xor_b32 s6, s0, 7
	s_cmp_eq_u32 s1, 0
	s_cselect_b32 s63, s0, s6
	s_lshl_b32 s22, s63, 6
	v_add_u32_e32 v2, s95, v170
	s_or_b32 s68, s22, s34
	s_mov_b32 s69, s61
	v_ashrrev_i32_e32 v3, 31, v2
	v_lshl_add_u64 v[4:5], s[68:69], 0, v[2:3]
	v_mad_u64_u32 v[12:13], s[0:1], v4, s3, v[166:167]
	v_ashrrev_i32_e32 v113, 31, v112
	v_mad_i32_i24 v13, v5, s3, v13
	s_mov_b32 s77, s61
	v_lshl_add_u64 v[4:5], v[12:13], 0, s[76:77]
	v_lshlrev_b64 v[14:15], 1, v[112:113]
	v_lshl_add_u64 v[8:9], v[4:5], 0, v[14:15]
	v_add_u32_e32 v96, 16, v2
	global_load_dwordx4 v[4:7], v[8:9], off
	s_nop 0
	global_load_dwordx4 v[8:11], v[8:9], off offset:64
	v_readlane_b32 s0, v246, 16
	v_ashrrev_i32_e32 v97, 31, v96
	v_readlane_b32 s1, v246, 17
	v_lshl_add_u64 v[16:17], s[68:69], 0, v[96:97]
	s_mov_b32 s79, s61
	v_lshl_add_u64 v[12:13], v[12:13], 0, s[78:79]
	v_add_u32_e32 v97, 0, v1
	v_lshlrev_b32_e32 v116, 6, v136
	global_load_dwordx3 v[52:54], v0, s[0:1]
	v_mad_u64_u32 v[18:19], s[0:1], v16, s3, v[166:167]
	v_mad_i32_i24 v19, v17, s3, v19
	v_lshl_add_u64 v[16:17], v[18:19], 0, s[76:77]
	v_lshl_add_u64 v[16:17], v[16:17], 0, v[14:15]
	global_load_dword v58, v[12:13], off
	global_load_ushort v57, v[12:13], off offset:4
	s_nop 0
	global_load_dwordx4 v[12:15], v[16:17], off
	v_lshl_add_u64 v[20:21], v[18:19], 0, s[78:79]
	global_load_dwordx4 v[16:19], v[16:17], off offset:64
	s_nop 0
	global_load_dword v56, v[20:21], off
	global_load_ushort v55, v[20:21], off offset:4
	s_waitcnt lgkmcnt(0)
	s_barrier
	ds_read_b128 v[20:23], v97
	ds_read_b128 v[24:27], v97 offset:64
	v_add_u32_e32 v138, s22, v2
	v_or_b32_e32 v117, 31, v116
	v_sub_u32_e32 v2, v117, v138
	v_cvt_f32_i32_e32 v1, v2
	s_cmp_lt_u32 s63, 17
	s_cselect_b64 s[0:1], -1, 0
	s_cmp_gt_u32 s63, 16
	v_mul_f32_e32 v28, v160, v1
	v_pk_fma_f32 v[30:31], v[162:163], v[248:249], v[28:29] op_sel_hi:[1,1,0]
	v_pk_fma_f32 v[28:29], v[164:165], v[250:251], v[28:29] op_sel_hi:[1,1,0]
	v_sub_u32_e32 v1, v138, v116
	s_waitcnt vmcnt(8) lgkmcnt(1)
	v_mfma_f32_16x16x32_bf16 v[20:23], v[20:23], v[4:7], v[28:31]
	s_waitcnt vmcnt(7) lgkmcnt(0)
	v_mfma_f32_16x16x32_bf16 v[20:23], v[24:27], v[8:11], v[20:23]
	s_cbranch_scc1 .LBB0_917
	v_subrev_u32_e32 v3, 31, v1
	v_cmp_lt_i32_e32 vcc, -1, v3
	v_subrev_u32_e32 v3, 47, v1
	s_nop 3
	v_cndmask_b32_e32 v20, v194, v20, vcc
	v_cmp_lt_i32_e32 vcc, -1, v3
	v_subrev_u32_e32 v3, 63, v1
	s_nop 0
	v_cndmask_b32_e32 v21, v194, v21, vcc
	v_cmp_lt_i32_e32 vcc, -1, v3
	v_add_u32_e32 v3, 0xffffffb1, v1
	s_nop 0
	v_cndmask_b32_e32 v22, v194, v22, vcc
	v_cmp_lt_i32_e32 vcc, -1, v3
	s_nop 1
	v_cndmask_b32_e32 v23, v194, v23, vcc
.LBB0_917:
	ds_read_b128 v[24:27], v97 offset:2304
	ds_read_b128 v[28:31], v97 offset:2368
	v_add_u32_e32 v3, 0x100, v2
	v_cvt_f32_i32_e32 v3, v3
	v_mov_b32_e32 v161, v160
	s_andn2_b64 vcc, exec, s[0:1]
	v_mul_f32_e32 v32, v160, v3
	v_pk_fma_f32 v[34:35], v[160:161], v[248:249], v[32:33] op_sel_hi:[1,1,0]
	v_pk_fma_f32 v[32:33], v[164:165], v[250:251], v[32:33] op_sel_hi:[1,1,0]
	v_cndmask_b32_e64 v3, 0, 1, s[0:1]
	v_cmp_ne_u32_e64 s[16:17], 1, v3
	s_waitcnt lgkmcnt(1)
	v_mfma_f32_16x16x32_bf16 v[24:27], v[24:27], v[4:7], v[32:35]
	s_waitcnt lgkmcnt(0)
	v_mfma_f32_16x16x32_bf16 v[24:27], v[28:31], v[8:11], v[24:27]
	s_cbranch_vccnz .LBB0_919
	v_add_u32_e32 v3, 0xfffffee1, v1
	v_cmp_lt_i32_e32 vcc, -1, v3
	v_add_u32_e32 v3, 0xfffffed1, v1
	s_nop 3
	v_cndmask_b32_e32 v24, v194, v24, vcc
	v_cmp_lt_i32_e32 vcc, -1, v3
	v_add_u32_e32 v3, 0xfffffec1, v1
	s_nop 0
	v_cndmask_b32_e32 v25, v194, v25, vcc
	v_cmp_lt_i32_e32 vcc, -1, v3
	v_add_u32_e32 v3, 0xfffffeb1, v1
	s_nop 0
	v_cndmask_b32_e32 v26, v194, v26, vcc
	v_cmp_lt_i32_e32 vcc, -1, v3
	s_nop 1
	v_cndmask_b32_e32 v27, v194, v27, vcc
.LBB0_919:
	ds_read_b128 v[28:31], v97 offset:4608
	v_add_u32_e32 v3, 0x200, v2
	v_cvt_f32_i32_e32 v3, v3
	s_and_b64 vcc, exec, s[16:17]
	v_mul_f32_e32 v32, v160, v3
	v_pk_fma_f32 v[34:35], v[160:161], v[248:249], v[32:33] op_sel_hi:[1,1,0]
	v_pk_fma_f32 v[32:33], v[164:165], v[250:251], v[32:33] op_sel_hi:[1,1,0]
	s_waitcnt lgkmcnt(0)
	s_nop 0
	v_mfma_f32_16x16x32_bf16 v[28:31], v[28:31], v[4:7], v[32:35]
	s_nop 2
	ds_read_b128 v[32:35], v97 offset:4672
	s_waitcnt lgkmcnt(0)
	v_mfma_f32_16x16x32_bf16 v[28:31], v[32:35], v[8:11], v[28:31]
	s_cbranch_vccnz .LBB0_921
	v_add_u32_e32 v3, 0xfffffde1, v1
	v_cmp_lt_i32_e32 vcc, -1, v3
	v_add_u32_e32 v3, 0xfffffdd1, v1
	s_nop 3
	v_cndmask_b32_e32 v28, v194, v28, vcc
	v_cmp_lt_i32_e32 vcc, -1, v3
	v_add_u32_e32 v3, 0xfffffdc1, v1
	s_nop 0
	v_cndmask_b32_e32 v29, v194, v29, vcc
	v_cmp_lt_i32_e32 vcc, -1, v3
	v_add_u32_e32 v3, 0xfffffdb1, v1
	s_nop 0
	v_cndmask_b32_e32 v30, v194, v30, vcc
	v_cmp_lt_i32_e32 vcc, -1, v3
	s_nop 1
	v_cndmask_b32_e32 v31, v194, v31, vcc
; #define LAS __attribute__((address_space(3)))
; #define MFMA16(a, b, c) __builtin_amdgcn_mfma_f32_16x16x32_bf16(a, b, c, 0, 0, 0)
; __device__ __forceinline__ void nsa_phase(LAS unsigned char* lds, const Args& a, const bf16_t* z, const bf16_t* KC, const bf16_t* VCT, const bf16_t* VST, const bf16_t* VWT, bf16_t* A2, int ldo, bool merged) {
;     ...
;             for (int tl = 0; tl < 4; ++tl) {
;                 if (tl <= tlmax) {
; #pragma unroll
;                     for (int s = 0; s < 4; ++s) {
;                         const LAS unsigned char* kp = lds + kcl_off + (tl * 64 + s * 16) * 144;
;                         const bf16x8 k0 = *(const LAS bf16x8*)kp, k1 = *(const LAS bf16x8*)(kp + 64);
;                         const float cb = slope * (float)((tl * 1024 + s * 256 + 64 * g4 + 31) - tq[qs]);
;                         f32x4 zz;
; #pragma unroll
;                         for (int i = 0; i < 4; ++i) zz[i] = fmaf(slope, 16.f * (float)i, cb);
;                         zz = MFMA16(k0, Qf[qs][0], zz);
;                         zz = MFMA16(k1, Qf[qs][1], zz);
;                         if (!((64 * (tl + 1) - 1) <= (4 * qt - 2))) {
; #pragma unroll
;                             for (int i = 0; i < 4; ++i) {
;                                 const int dist = (tq[qs] - 31 - 64 * g4) - (tl * 1024 + s * 256 + 16 * i);
;                                 const bool ok = (dist >= 0) && !(tl == 3 && s == 3 && i == 3 && g4 == 3);
;                                 zz[i] = ok ? zz[i] : -1e30f;
;                             }
;                         }
; #pragma unroll
;                         for (int i = 0; i < 4; ++i) mx = fmaxf(mx, zz[i]);
;                         sc[tl][s] = zz;
;                         __builtin_amdgcn_sched_barrier(0);
;                     }
.LBB0_921:
	ds_read_b128 v[32:35], v97 offset:6912
	v_add_u32_e32 v3, 0x300, v2
	v_cvt_f32_i32_e32 v3, v3
	v_mov_b32_e32 v161, v160
	s_and_b64 vcc, exec, s[16:17]
	v_mul_f32_e32 v36, v160, v3
	v_pk_fma_f32 v[38:39], v[160:161], v[248:249], v[36:37] op_sel_hi:[1,1,0]
	v_pk_fma_f32 v[36:37], v[164:165], v[250:251], v[36:37] op_sel_hi:[1,1,0]
	s_waitcnt lgkmcnt(0)
	s_nop 0
	v_mfma_f32_16x16x32_bf16 v[32:35], v[32:35], v[4:7], v[36:39]
	s_nop 2
	ds_read_b128 v[36:39], v97 offset:6976
	s_waitcnt lgkmcnt(0)
	v_mfma_f32_16x16x32_bf16 v[32:35], v[36:39], v[8:11], v[32:35]
	s_cbranch_vccnz .LBB0_923
	v_add_u32_e32 v3, 0xfffffce1, v1
	v_cmp_lt_i32_e32 vcc, -1, v3
	v_add_u32_e32 v3, 0xfffffcd1, v1
	s_nop 3
	v_cndmask_b32_e32 v32, v194, v32, vcc
	v_cmp_lt_i32_e32 vcc, -1, v3
	v_add_u32_e32 v3, 0xfffffcc1, v1
	s_nop 0
	v_cndmask_b32_e32 v33, v194, v33, vcc
	v_cmp_lt_i32_e32 vcc, -1, v3
	v_add_u32_e32 v3, 0xfffffcb1, v1
	s_nop 0
	v_cndmask_b32_e32 v34, v194, v34, vcc
	v_cmp_lt_i32_e32 vcc, -1, v3
	s_nop 1
	v_cndmask_b32_e32 v35, v194, v35, vcc
.LBB0_923:
	v_mov_b32_e32 v39, 0xf149f2ca
	v_max3_f32 v3, v20, v39, v21
	v_max3_f32 v3, v3, v22, v23
	v_max3_f32 v3, v3, v24, v25
	v_max3_f32 v3, v3, v26, v27
	v_max3_f32 v3, v3, v28, v29
	v_max3_f32 v3, v3, v30, v31
	v_max3_f32 v3, v3, v32, v33
	v_max3_f32 v3, v3, v34, v35
	s_cmp_gt_u32 s63, 15
	s_cselect_b64 s[6:7], -1, 0
	s_cmp_lt_u32 s63, 16
	s_cbranch_scc1 .LBB0_933
	ds_read_b128 v[36:39], v97 offset:9216
	v_add_u32_e32 v40, 0x400, v2
	v_cvt_f32_i32_e32 v44, v40
	ds_read_b128 v[40:43], v97 offset:9280
	v_mov_b32_e32 v161, v160
	s_cmp_lt_u32 s63, 33
	v_mul_f32_e32 v44, v160, v44
	v_pk_fma_f32 v[46:47], v[160:161], v[248:249], v[44:45] op_sel_hi:[1,1,0]
	v_pk_fma_f32 v[44:45], v[164:165], v[250:251], v[44:45] op_sel_hi:[1,1,0]
	s_cselect_b64 s[8:9], -1, 0
	s_cmp_gt_u32 s63, 32
	s_waitcnt lgkmcnt(1)
	v_mfma_f32_16x16x32_bf16 v[36:39], v[36:39], v[4:7], v[44:47]
	s_waitcnt lgkmcnt(0)
	v_mfma_f32_16x16x32_bf16 v[36:39], v[40:43], v[8:11], v[36:39]
	s_cbranch_scc1 .LBB0_926
	v_add_u32_e32 v40, 0xfffffbe1, v1
	v_cmp_lt_i32_e32 vcc, -1, v40
	v_add_u32_e32 v40, 0xfffffbd1, v1
	s_nop 3
	v_cndmask_b32_e32 v36, v194, v36, vcc
	v_cmp_lt_i32_e32 vcc, -1, v40
	v_add_u32_e32 v40, 0xfffffbc1, v1
	s_nop 0
	v_cndmask_b32_e32 v37, v194, v37, vcc
	v_cmp_lt_i32_e32 vcc, -1, v40
	v_add_u32_e32 v40, 0xfffffbb1, v1
	s_nop 0
	v_cndmask_b32_e32 v38, v194, v38, vcc
	v_cmp_lt_i32_e32 vcc, -1, v40
	s_nop 1
	v_cndmask_b32_e32 v39, v194, v39, vcc
.LBB0_926:
	ds_read_b128 v[40:43], v97 offset:11520
	v_add_u32_e32 v44, 0x500, v2
	v_cvt_f32_i32_e32 v48, v44
	ds_read_b128 v[44:47], v97 offset:11584
	s_andn2_b64 vcc, exec, s[8:9]
	v_mul_f32_e32 v48, v160, v48
	v_pk_fma_f32 v[50:51], v[160:161], v[248:249], v[48:49] op_sel_hi:[1,1,0]
	v_pk_fma_f32 v[48:49], v[164:165], v[250:251], v[48:49] op_sel_hi:[1,1,0]
	s_waitcnt lgkmcnt(1)
	s_nop 0
	v_mfma_f32_16x16x32_bf16 v[40:43], v[40:43], v[4:7], v[48:51]
	s_waitcnt lgkmcnt(0)
	v_mfma_f32_16x16x32_bf16 v[40:43], v[44:47], v[8:11], v[40:43]
	s_nop 0
	v_cndmask_b32_e64 v48, 0, 1, s[8:9]
	v_cmp_ne_u32_e64 s[0:1], 1, v48
	s_cbranch_vccnz .LBB0_928
	v_add_u32_e32 v44, 0xfffffae1, v1
	v_cmp_lt_i32_e32 vcc, -1, v44
	v_add_u32_e32 v44, 0xfffffad1, v1
	s_nop 0
	v_cndmask_b32_e32 v40, v194, v40, vcc
	v_cmp_lt_i32_e32 vcc, -1, v44
	v_add_u32_e32 v44, 0xfffffac1, v1
	s_nop 0
	v_cndmask_b32_e32 v41, v194, v41, vcc
	v_cmp_lt_i32_e32 vcc, -1, v44
	v_add_u32_e32 v44, 0xfffffab1, v1
	s_nop 0
	v_cndmask_b32_e32 v42, v194, v42, vcc
	v_cmp_lt_i32_e32 vcc, -1, v44
	s_nop 1
	v_cndmask_b32_e32 v43, v194, v43, vcc
.LBB0_928:
	ds_read_b128 v[44:47], v97 offset:13824
	v_add_u32_e32 v48, 0x600, v2
	v_cvt_f32_i32_e32 v48, v48
	v_mov_b32_e32 v161, v160
	s_and_b64 vcc, exec, s[0:1]
	v_mul_f32_e32 v48, v160, v48
	v_pk_fma_f32 v[50:51], v[160:161], v[248:249], v[48:49] op_sel_hi:[1,1,0]
	v_pk_fma_f32 v[48:49], v[164:165], v[250:251], v[48:49] op_sel_hi:[1,1,0]
	s_waitcnt lgkmcnt(0)
	s_nop 0
	v_mfma_f32_16x16x32_bf16 v[44:47], v[44:47], v[4:7], v[48:51]
	s_nop 2
	ds_read_b128 v[48:51], v97 offset:13888
	s_waitcnt lgkmcnt(0)
	v_mfma_f32_16x16x32_bf16 v[44:47], v[48:51], v[8:11], v[44:47]
	s_cbranch_vccnz .LBB0_930
	v_add_u32_e32 v48, 0xfffff9e1, v1
	v_cmp_lt_i32_e32 vcc, -1, v48
	v_add_u32_e32 v48, 0xfffff9d1, v1
	s_nop 3
	v_cndmask_b32_e32 v44, v194, v44, vcc
	v_cmp_lt_i32_e32 vcc, -1, v48
	v_add_u32_e32 v48, 0xfffff9c1, v1
	s_nop 0
	v_cndmask_b32_e32 v45, v194, v45, vcc
	v_cmp_lt_i32_e32 vcc, -1, v48
	v_add_u32_e32 v48, 0xfffff9b1, v1
	s_nop 0
	v_cndmask_b32_e32 v46, v194, v46, vcc
	v_cmp_lt_i32_e32 vcc, -1, v48
	s_nop 1
	v_cndmask_b32_e32 v47, v194, v47, vcc
.LBB0_930:
	ds_read_b128 v[48:51], v97 offset:16128
	v_add_u32_e32 v59, 0x700, v2
	v_cvt_f32_i32_e32 v59, v59
	s_and_b64 vcc, exec, s[0:1]
	v_mul_f32_e32 v60, v160, v59
	v_pk_fma_f32 v[62:63], v[160:161], v[248:249], v[60:61] op_sel_hi:[1,1,0]
	v_pk_fma_f32 v[60:61], v[164:165], v[250:251], v[60:61] op_sel_hi:[1,1,0]
	s_waitcnt lgkmcnt(0)
	s_nop 0
	v_mfma_f32_16x16x32_bf16 v[48:51], v[48:51], v[4:7], v[60:63]
	s_nop 2
	ds_read_b128 v[60:63], v97 offset:16192
	s_waitcnt lgkmcnt(0)
	v_mfma_f32_16x16x32_bf16 v[48:51], v[60:63], v[8:11], v[48:51]
	s_cbranch_vccnz .LBB0_932
	v_add_u32_e32 v59, 0xfffff8e1, v1
	v_cmp_lt_i32_e32 vcc, -1, v59
	v_add_u32_e32 v59, 0xfffff8d1, v1
	s_nop 3
	v_cndmask_b32_e32 v48, v194, v48, vcc
	v_cmp_lt_i32_e32 vcc, -1, v59
	v_add_u32_e32 v59, 0xfffff8c1, v1
	s_nop 0
	v_cndmask_b32_e32 v49, v194, v49, vcc
	v_cmp_lt_i32_e32 vcc, -1, v59
	v_add_u32_e32 v59, 0xfffff8b1, v1
	s_nop 0
	v_cndmask_b32_e32 v50, v194, v50, vcc
	v_cmp_lt_i32_e32 vcc, -1, v59
	s_nop 1
	v_cndmask_b32_e32 v51, v194, v51, vcc

; #define LAS __attribute__((address_space(3)))
; __device__ __forceinline__ float bf2f(bf16_t h) { return __uint_as_float((unsigned)h << 16); }
; __device__ __forceinline__ float sigm(float x) { return __builtin_amdgcn_rcpf(1.f + __expf(-x)); }
; #define MFMA16(a, b, c) __builtin_amdgcn_mfma_f32_16x16x32_bf16(a, b, c, 0, 0, 0)
; __device__ __forceinline__ void nsa_phase(LAS unsigned char* lds, const Args& a, const bf16_t* z, const bf16_t* KC, const bf16_t* VCT, const bf16_t* VST, const bf16_t* VWT, bf16_t* A2, int ldo, bool merged) {
;     ...
;             for (int br = 0; br < 3; ++br) gate[qs][br] = sigm(bf2f(zr[ZGT + hq * 3 + br]) + gbias[hq * 3 + br]);
;     ...
;             for (int tl = 0; tl < 4; ++tl) {
;                 if (tl <= tlmax) {
; #pragma unroll
;                     for (int s = 0; s < 4; ++s) {
;                         const LAS unsigned char* kp = lds + kcl_off + (tl * 64 + s * 16) * 144;
;                         const bf16x8 k0 = *(const LAS bf16x8*)kp, k1 = *(const LAS bf16x8*)(kp + 64);
;                         const float cb = slope * (float)((tl * 1024 + s * 256 + 64 * g4 + 31) - tq[qs]);
;                         f32x4 zz;
; #pragma unroll
;                         for (int i = 0; i < 4; ++i) zz[i] = fmaf(slope, 16.f * (float)i, cb);
;                         zz = MFMA16(k0, Qf[qs][0], zz);
;                         zz = MFMA16(k1, Qf[qs][1], zz);
;                         if (!((64 * (tl + 1) - 1) <= (4 * qt - 2))) {
; #pragma unroll
;                             for (int i = 0; i < 4; ++i) {
;                                 const int dist = (tq[qs] - 31 - 64 * g4) - (tl * 1024 + s * 256 + 16 * i);
;                                 const bool ok = (dist >= 0) && !(tl == 3 && s == 3 && i == 3 && g4 == 3);
;                                 zz[i] = ok ? zz[i] : -1e30f;
;                             }
;                         }
; #pragma unroll
;                         for (int i = 0; i < 4; ++i) mx = fmaxf(mx, zz[i]);
;                         sc[tl][s] = zz;
;                         __builtin_amdgcn_sched_barrier(0);
;                     }
.LBB0_934:
	s_waitcnt vmcnt(5)
	v_lshlrev_b32_e32 v59, 16, v58
	v_add_f32_e32 v59, v52, v59
	v_mul_f32_e32 v59, 0xbfb8aa3b, v59
	v_exp_f32_e32 v59, v59
	v_and_b32_e32 v58, 0xffff0000, v58
	v_add_f32_e32 v58, v53, v58
	s_waitcnt vmcnt(4)
	v_lshlrev_b32_e32 v57, 16, v57
	v_add_f32_e32 v59, 1.0, v59
	v_rcp_f32_e32 v172, v59
	s_waitcnt vmcnt(1)
	v_lshlrev_b32_e32 v59, 16, v56
	v_add_f32_e32 v52, v52, v59
	v_and_b32_e32 v56, 0xffff0000, v56
	v_mul_f32_e32 v52, 0xbfb8aa3b, v52
	v_add_f32_e32 v53, v53, v56
	s_waitcnt vmcnt(0)
	v_lshlrev_b32_e32 v55, 16, v55
	v_add_f32_e32 v57, v54, v57
	v_exp_f32_e32 v52, v52
	v_mul_f32_e32 v53, 0xbfb8aa3b, v53
	v_add_f32_e32 v54, v54, v55
	v_mul_f32_e32 v58, 0xbfb8aa3b, v58
	v_mul_f32_e32 v57, 0xbfb8aa3b, v57
	v_exp_f32_e32 v53, v53
	v_mul_f32_e32 v54, 0xbfb8aa3b, v54
	v_exp_f32_e32 v58, v58
	v_exp_f32_e32 v57, v57
	v_exp_f32_e32 v54, v54
	v_add_f32_e32 v52, 1.0, v52
	v_rcp_f32_e32 v174, v52
	v_add_f32_e32 v52, 1.0, v53
	v_add_f32_e32 v58, 1.0, v58
	v_add_f32_e32 v57, 1.0, v57
	v_rcp_f32_e32 v200, v52
	v_add_f32_e32 v52, 1.0, v54
	v_rcp_f32_e32 v199, v58
	v_rcp_f32_e32 v198, v57
	v_rcp_f32_e32 v171, v52
	s_cmp_gt_u32 s63, 31
	s_cselect_b64 s[12:13], -1, 0
	s_cmp_lt_u32 s63, 32
	v_mov_b32_e32 v55, 0xf149f2ca
	s_cbranch_scc1 .LBB0_944
	ds_read_b128 v[52:55], v97 offset:18432
	v_add_u32_e32 v56, 0x800, v2
	v_cvt_f32_i32_e32 v60, v56
	ds_read_b128 v[56:59], v97 offset:18496
	v_mov_b32_e32 v161, v160
	s_cmp_lt_u32 s63, 49
	v_mul_f32_e32 v60, v160, v60
	v_pk_fma_f32 v[62:63], v[160:161], v[248:249], v[60:61] op_sel_hi:[1,1,0]
	v_pk_fma_f32 v[60:61], v[164:165], v[250:251], v[60:61] op_sel_hi:[1,1,0]
	s_cselect_b64 s[8:9], -1, 0
	s_cmp_gt_u32 s63, 48
	s_waitcnt lgkmcnt(1)
	v_mfma_f32_16x16x32_bf16 v[52:55], v[52:55], v[4:7], v[60:63]
	s_waitcnt lgkmcnt(0)
	v_mfma_f32_16x16x32_bf16 v[52:55], v[56:59], v[8:11], v[52:55]
	s_cbranch_scc1 .LBB0_937
	v_add_u32_e32 v56, 0xfffff7e1, v1
	v_cmp_lt_i32_e32 vcc, -1, v56
	v_add_u32_e32 v56, 0xfffff7d1, v1
	s_nop 3
	v_cndmask_b32_e32 v52, v194, v52, vcc
	v_cmp_lt_i32_e32 vcc, -1, v56
	v_add_u32_e32 v56, 0xfffff7c1, v1
	s_nop 0
	v_cndmask_b32_e32 v53, v194, v53, vcc
	v_cmp_lt_i32_e32 vcc, -1, v56
	v_add_u32_e32 v56, 0xfffff7b1, v1
	s_nop 0
	v_cndmask_b32_e32 v54, v194, v54, vcc
	v_cmp_lt_i32_e32 vcc, -1, v56
	s_nop 1
	v_cndmask_b32_e32 v55, v194, v55, vcc
.LBB0_937:
	ds_read_b128 v[56:59], v97 offset:20736
	v_add_u32_e32 v60, 0x900, v2
	v_cvt_f32_i32_e32 v64, v60
	ds_read_b128 v[60:63], v97 offset:20800
	s_andn2_b64 vcc, exec, s[8:9]
	v_mul_f32_e32 v64, v160, v64
	v_pk_fma_f32 v[66:67], v[160:161], v[248:249], v[64:65] op_sel_hi:[1,1,0]
	v_pk_fma_f32 v[64:65], v[164:165], v[250:251], v[64:65] op_sel_hi:[1,1,0]
	s_waitcnt lgkmcnt(1)
	s_nop 0
	v_mfma_f32_16x16x32_bf16 v[56:59], v[56:59], v[4:7], v[64:67]
	s_waitcnt lgkmcnt(0)
	v_mfma_f32_16x16x32_bf16 v[56:59], v[60:63], v[8:11], v[56:59]
	s_nop 0
	v_cndmask_b32_e64 v64, 0, 1, s[8:9]
	v_cmp_ne_u32_e64 s[0:1], 1, v64
	s_cbranch_vccnz .LBB0_939
	v_add_u32_e32 v60, 0xfffff6e1, v1
	v_cmp_lt_i32_e32 vcc, -1, v60
	v_add_u32_e32 v60, 0xfffff6d1, v1
	s_nop 0
	v_cndmask_b32_e32 v56, v194, v56, vcc
	v_cmp_lt_i32_e32 vcc, -1, v60
	v_add_u32_e32 v60, 0xfffff6c1, v1
	s_nop 0
	v_cndmask_b32_e32 v57, v194, v57, vcc
	v_cmp_lt_i32_e32 vcc, -1, v60
	v_add_u32_e32 v60, 0xfffff6b1, v1
	s_nop 0
	v_cndmask_b32_e32 v58, v194, v58, vcc
	v_cmp_lt_i32_e32 vcc, -1, v60
	s_nop 1
	v_cndmask_b32_e32 v59, v194, v59, vcc
.LBB0_939:
	ds_read_b128 v[60:63], v97 offset:23040
	v_add_u32_e32 v64, 0xa00, v2
	v_cvt_f32_i32_e32 v64, v64
	v_mov_b32_e32 v161, v160
	s_and_b64 vcc, exec, s[0:1]
	v_mul_f32_e32 v64, v160, v64
	v_pk_fma_f32 v[66:67], v[160:161], v[248:249], v[64:65] op_sel_hi:[1,1,0]
	v_pk_fma_f32 v[64:65], v[164:165], v[250:251], v[64:65] op_sel_hi:[1,1,0]
	s_waitcnt lgkmcnt(0)
	s_nop 0
	v_mfma_f32_16x16x32_bf16 v[60:63], v[60:63], v[4:7], v[64:67]
	s_nop 2
	ds_read_b128 v[64:67], v97 offset:23104
	s_waitcnt lgkmcnt(0)
	v_mfma_f32_16x16x32_bf16 v[60:63], v[64:67], v[8:11], v[60:63]
	s_cbranch_vccnz .LBB0_941
	v_add_u32_e32 v64, 0xfffff5e1, v1
	v_cmp_lt_i32_e32 vcc, -1, v64
	v_add_u32_e32 v64, 0xfffff5d1, v1
	s_nop 3
	v_cndmask_b32_e32 v60, v194, v60, vcc
	v_cmp_lt_i32_e32 vcc, -1, v64
	v_add_u32_e32 v64, 0xfffff5c1, v1
	s_nop 0
	v_cndmask_b32_e32 v61, v194, v61, vcc
	v_cmp_lt_i32_e32 vcc, -1, v64
	v_add_u32_e32 v64, 0xfffff5b1, v1
	s_nop 0
	v_cndmask_b32_e32 v62, v194, v62, vcc
	v_cmp_lt_i32_e32 vcc, -1, v64
	s_nop 1
	v_cndmask_b32_e32 v63, v194, v63, vcc
.LBB0_941:
	ds_read_b128 v[64:67], v97 offset:25344
	v_add_u32_e32 v68, 0xb00, v2
	v_cvt_f32_i32_e32 v68, v68
	s_and_b64 vcc, exec, s[0:1]
	v_mul_f32_e32 v68, v160, v68
	v_pk_fma_f32 v[70:71], v[160:161], v[248:249], v[68:69] op_sel_hi:[1,1,0]
	v_pk_fma_f32 v[68:69], v[164:165], v[250:251], v[68:69] op_sel_hi:[1,1,0]
	s_waitcnt lgkmcnt(0)
	s_nop 0
	v_mfma_f32_16x16x32_bf16 v[64:67], v[64:67], v[4:7], v[68:71]
	s_nop 2
	ds_read_b128 v[68:71], v97 offset:25408
	s_waitcnt lgkmcnt(0)
	v_mfma_f32_16x16x32_bf16 v[72:75], v[68:71], v[8:11], v[64:67]
	s_cbranch_vccnz .LBB0_943
	s_nop 1
	v_add_u32_e32 v64, 0xfffff4e1, v1
	v_cmp_lt_i32_e32 vcc, -1, v64
	v_add_u32_e32 v64, 0xfffff4d1, v1
	s_nop 1
	v_cndmask_b32_e32 v72, v194, v72, vcc
	v_cmp_lt_i32_e32 vcc, -1, v64
	v_add_u32_e32 v64, 0xfffff4c1, v1
	s_nop 0
	v_cndmask_b32_e32 v73, v194, v73, vcc
	v_cmp_lt_i32_e32 vcc, -1, v64
	v_add_u32_e32 v64, 0xfffff4b1, v1
	s_nop 0
	v_cndmask_b32_e32 v74, v194, v74, vcc
	v_cmp_lt_i32_e32 vcc, -1, v64
	s_nop 1
	v_cndmask_b32_e32 v75, v194, v75, vcc

; #define LAS __attribute__((address_space(3)))
; #define MFMA16(a, b, c) __builtin_amdgcn_mfma_f32_16x16x32_bf16(a, b, c, 0, 0, 0)
; __device__ __forceinline__ void nsa_phase(LAS unsigned char* lds, const Args& a, const bf16_t* z, const bf16_t* KC, const bf16_t* VCT, const bf16_t* VST, const bf16_t* VWT, bf16_t* A2, int ldo, bool merged) {
;     ...
;             for (int tl = 0; tl < 4; ++tl) {
;                 if (tl <= tlmax) {
; #pragma unroll
;                     for (int s = 0; s < 4; ++s) {
;                         const LAS unsigned char* kp = lds + kcl_off + (tl * 64 + s * 16) * 144;
;                         const bf16x8 k0 = *(const LAS bf16x8*)kp, k1 = *(const LAS bf16x8*)(kp + 64);
;                         const float cb = slope * (float)((tl * 1024 + s * 256 + 64 * g4 + 31) - tq[qs]);
;                         f32x4 zz;
; #pragma unroll
;                         for (int i = 0; i < 4; ++i) zz[i] = fmaf(slope, 16.f * (float)i, cb);
;                         zz = MFMA16(k0, Qf[qs][0], zz);
;                         zz = MFMA16(k1, Qf[qs][1], zz);
;                         if (!((64 * (tl + 1) - 1) <= (4 * qt - 2))) {
; #pragma unroll
;                             for (int i = 0; i < 4; ++i) {
;                                 const int dist = (tq[qs] - 31 - 64 * g4) - (tl * 1024 + s * 256 + 16 * i);
;                                 const bool ok = (dist >= 0) && !(tl == 3 && s == 3 && i == 3 && g4 == 3);
;                                 zz[i] = ok ? zz[i] : -1e30f;
;                             }
;                         }
; #pragma unroll
;                         for (int i = 0; i < 4; ++i) mx = fmaxf(mx, zz[i]);
.LBB0_945:
	s_and_b32 s8, s63, 48
	s_cmp_eq_u32 s8, 48
	s_cselect_b64 s[0:1], -1, 0
	s_cmp_lg_u32 s8, 48
	s_cselect_b64 s[18:19], -1, 0
	v_cmp_ne_u32_e64 s[14:15], 3, v136
	v_mov_b32_e32 v115, 0xf149f2ca
	s_and_b64 vcc, exec, s[18:19]
	s_cbranch_vccnz .LBB0_947
	ds_read_b128 v[64:67], v97 offset:27648
	v_add_u32_e32 v68, 0xc00, v2
	v_cvt_f32_i32_e32 v76, v68
	ds_read_b128 v[68:71], v97 offset:27712
	v_mov_b32_e32 v161, v160
	v_mul_f32_e32 v76, v160, v76
	v_pk_fma_f32 v[78:79], v[160:161], v[248:249], v[76:77] op_sel_hi:[1,1,0]
	v_pk_fma_f32 v[76:77], v[164:165], v[250:251], v[76:77] op_sel_hi:[1,1,0]
	s_waitcnt lgkmcnt(1)
	s_nop 0
	v_mfma_f32_16x16x32_bf16 v[64:67], v[64:67], v[4:7], v[76:79]
	s_waitcnt lgkmcnt(0)
	v_mfma_f32_16x16x32_bf16 v[64:67], v[68:71], v[8:11], v[64:67]
	s_nop 0
	v_add_u32_e32 v76, 0xfffff3e1, v1
	v_add_u32_e32 v77, 0xfffff3d1, v1
	v_cmp_lt_i32_e32 vcc, -1, v76
	v_add_u32_e32 v78, 0xfffff3c1, v1
	s_nop 2
	v_cndmask_b32_e32 v100, v194, v64, vcc
	v_cmp_lt_i32_e32 vcc, -1, v77
	v_add_u32_e32 v64, 0xfffff3b1, v1
	s_nop 0
	v_cndmask_b32_e32 v101, v194, v65, vcc
	v_cmp_lt_i32_e32 vcc, -1, v78
	v_max3_f32 v3, v3, v100, v101
	s_nop 0
	v_cndmask_b32_e32 v102, v194, v66, vcc
	v_cmp_lt_i32_e32 vcc, -1, v64
	s_nop 1
	v_cndmask_b32_e32 v103, v194, v67, vcc
	v_max3_f32 v3, v3, v102, v103
	ds_read_b128 v[64:67], v97 offset:29952
	v_add_u32_e32 v68, 0xd00, v2
	v_cvt_f32_i32_e32 v76, v68
	ds_read_b128 v[68:71], v97 offset:30016
	v_mul_f32_e32 v76, v160, v76
	v_pk_fma_f32 v[78:79], v[160:161], v[248:249], v[76:77] op_sel_hi:[1,1,0]
	v_pk_fma_f32 v[76:77], v[164:165], v[250:251], v[76:77] op_sel_hi:[1,1,0]
	s_waitcnt lgkmcnt(1)
	s_nop 0
	v_mfma_f32_16x16x32_bf16 v[64:67], v[64:67], v[4:7], v[76:79]
	s_waitcnt lgkmcnt(0)
	v_mfma_f32_16x16x32_bf16 v[64:67], v[68:71], v[8:11], v[64:67]
	s_nop 0
	v_add_u32_e32 v76, 0xfffff2e1, v1
	v_add_u32_e32 v77, 0xfffff2d1, v1
	v_cmp_lt_i32_e32 vcc, -1, v76
	v_add_u32_e32 v78, 0xfffff2c1, v1
	s_nop 2
	v_cndmask_b32_e32 v106, v194, v64, vcc
	v_cmp_lt_i32_e32 vcc, -1, v77
	v_add_u32_e32 v64, 0xfffff2b1, v1
	s_nop 0
	v_cndmask_b32_e32 v107, v194, v65, vcc
	v_cmp_lt_i32_e32 vcc, -1, v78
	v_max3_f32 v3, v3, v106, v107
	s_nop 0
	v_cndmask_b32_e32 v108, v194, v66, vcc
	v_cmp_lt_i32_e32 vcc, -1, v64
	s_nop 1
	v_cndmask_b32_e32 v109, v194, v67, vcc
	v_max3_f32 v3, v3, v108, v109
	ds_read_b128 v[64:67], v97 offset:32256
	v_add_u32_e32 v68, 0xe00, v2
	v_cvt_f32_i32_e32 v76, v68
	ds_read_b128 v[68:71], v97 offset:32320
	v_mul_f32_e32 v76, v160, v76
	v_pk_fma_f32 v[78:79], v[160:161], v[248:249], v[76:77] op_sel_hi:[1,1,0]
	v_pk_fma_f32 v[76:77], v[164:165], v[250:251], v[76:77] op_sel_hi:[1,1,0]
	s_waitcnt lgkmcnt(1)
	s_nop 0
	v_mfma_f32_16x16x32_bf16 v[64:67], v[64:67], v[4:7], v[76:79]
	s_waitcnt lgkmcnt(0)
	v_mfma_f32_16x16x32_bf16 v[64:67], v[68:71], v[8:11], v[64:67]
	s_nop 0
	v_add_u32_e32 v76, 0xfffff1e1, v1
	v_add_u32_e32 v77, 0xfffff1d1, v1
	v_cmp_lt_i32_e32 vcc, -1, v76
	v_add_u32_e32 v78, 0xfffff1c1, v1
	s_nop 2
	v_cndmask_b32_e32 v110, v194, v64, vcc
	v_cmp_lt_i32_e32 vcc, -1, v77
	v_add_u32_e32 v64, 0xfffff1b1, v1
	s_nop 0
	v_cndmask_b32_e32 v111, v194, v65, vcc
	v_cmp_lt_i32_e32 vcc, -1, v78
	v_max3_f32 v3, v3, v110, v111
	s_nop 0
	v_cndmask_b32_e32 v113, v194, v66, vcc
	v_cmp_lt_i32_e32 vcc, -1, v64
	s_nop 1
	v_cndmask_b32_e32 v114, v194, v67, vcc
	v_max3_f32 v3, v3, v113, v114
	ds_read_b128 v[64:67], v97 offset:34560
	ds_read_b128 v[68:71], v97 offset:34624
	v_add_u32_e32 v2, 0xf00, v2
	v_cvt_f32_i32_e32 v2, v2
	v_mul_f32_e32 v2, v160, v2
	v_pk_fma_f32 v[78:79], v[160:161], v[248:249], v[2:3] op_sel_hi:[1,1,0]
	v_pk_fma_f32 v[76:77], v[164:165], v[250:251], v[2:3] op_sel_hi:[1,1,0]
	v_add_u32_e32 v2, 0xfffff0e1, v1
	v_cmp_lt_i32_e32 vcc, -1, v2
	s_waitcnt lgkmcnt(1)
	v_mfma_f32_16x16x32_bf16 v[64:67], v[64:67], v[4:7], v[76:79]
	s_waitcnt lgkmcnt(0)
	v_mfma_f32_16x16x32_bf16 v[64:67], v[68:71], v[8:11], v[64:67]
	s_nop 0
	v_add_u32_e32 v76, 0xfffff0d1, v1
	v_add_u32_e32 v77, 0xfffff0c1, v1
	v_add_u32_e32 v1, 0xfffff0b1, v1
	s_nop 3
	v_cndmask_b32_e32 v115, v194, v64, vcc
	v_cmp_lt_i32_e32 vcc, -1, v76
	s_nop 1
	v_cndmask_b32_e32 v118, v194, v65, vcc
	v_cmp_lt_i32_e32 vcc, -1, v77
	s_nop 1
	v_cndmask_b32_e32 v120, v194, v66, vcc
	v_cmp_lt_i32_e32 vcc, -1, v1
	s_and_b64 vcc, vcc, s[14:15]
	v_max3_f32 v1, v3, v115, v118
	v_cndmask_b32_e32 v121, v194, v67, vcc
	v_max3_f32 v3, v1, v120, v121
	s_branch .LBB0_948

; #define LAS __attribute__((address_space(3)))
; #define MFMA16(a, b, c) __builtin_amdgcn_mfma_f32_16x16x32_bf16(a, b, c, 0, 0, 0)
; __device__ __forceinline__ void nsa_phase(LAS unsigned char* lds, const Args& a, const bf16_t* z, const bf16_t* KC, const bf16_t* VCT, const bf16_t* VST, const bf16_t* VWT, bf16_t* A2, int ldo, bool merged) {
;     ...
;             for (int tl = 0; tl < 4; ++tl) {
;                 if (tl <= tlmax) {
; #pragma unroll
;                     for (int s = 0; s < 4; ++s) {
;                         const LAS unsigned char* kp = lds + kcl_off + (tl * 64 + s * 16) * 144;
;                         const bf16x8 k0 = *(const LAS bf16x8*)kp, k1 = *(const LAS bf16x8*)(kp + 64);
;                         const float cb = slope * (float)((tl * 1024 + s * 256 + 64 * g4 + 31) - tq[qs]);
;                         f32x4 zz;
; #pragma unroll
;                         for (int i = 0; i < 4; ++i) zz[i] = fmaf(slope, 16.f * (float)i, cb);
;                         zz = MFMA16(k0, Qf[qs][0], zz);
;                         zz = MFMA16(k1, Qf[qs][1], zz);
;                         if (!((64 * (tl + 1) - 1) <= (4 * qt - 2))) {
; #pragma unroll
;                             for (int i = 0; i < 4; ++i) {
;                                 const int dist = (tq[qs] - 31 - 64 * g4) - (tl * 1024 + s * 256 + 16 * i);
;                                 const bool ok = (dist >= 0) && !(tl == 3 && s == 3 && i == 3 && g4 == 3);
;                                 zz[i] = ok ? zz[i] : -1e30f;
;                             }
;                         }
; #pragma unroll
;                         for (int i = 0; i < 4; ++i) mx = fmaxf(mx, zz[i]);
;                         sc[tl][s] = zz;
;                         __builtin_amdgcn_sched_barrier(0);
;                     }
.LBB0_975:
	ds_read_b128 v[36:39], v97
	v_add_u32_e32 v139, s22, v96
	v_sub_u32_e32 v1, v117, v139
	v_cvt_f32_i32_e32 v2, v1
	v_mov_b32_e32 v161, v160
	s_and_b64 vcc, exec, s[16:17]
	v_mul_f32_e32 v2, v160, v2
	v_pk_fma_f32 v[42:43], v[160:161], v[248:249], v[2:3] op_sel_hi:[1,1,0]
	v_pk_fma_f32 v[40:41], v[164:165], v[250:251], v[2:3] op_sel_hi:[1,1,0]
	v_sub_u32_e32 v2, v139, v116
	s_waitcnt lgkmcnt(0)
	v_mfma_f32_16x16x32_bf16 v[36:39], v[36:39], v[12:15], v[40:43]
	s_nop 2
	ds_read_b128 v[40:43], v97 offset:64
	s_waitcnt lgkmcnt(0)
	v_mfma_f32_16x16x32_bf16 v[36:39], v[40:43], v[16:19], v[36:39]
	s_cbranch_vccnz .LBB0_977
	v_subrev_u32_e32 v3, 31, v2
	v_cmp_lt_i32_e32 vcc, -1, v3
	v_subrev_u32_e32 v3, 47, v2
	s_nop 3
	v_cndmask_b32_e32 v36, v194, v36, vcc
	v_cmp_lt_i32_e32 vcc, -1, v3
	v_subrev_u32_e32 v3, 63, v2
	s_nop 0
	v_cndmask_b32_e32 v37, v194, v37, vcc
	v_cmp_lt_i32_e32 vcc, -1, v3
	v_add_u32_e32 v3, 0xffffffb1, v2
	s_nop 0
	v_cndmask_b32_e32 v38, v194, v38, vcc
	v_cmp_lt_i32_e32 vcc, -1, v3
	s_nop 1
	v_cndmask_b32_e32 v39, v194, v39, vcc
.LBB0_977:
	ds_read_b128 v[40:43], v97 offset:2304
	v_add_u32_e32 v3, 0x100, v1
	v_cvt_f32_i32_e32 v3, v3
	s_and_b64 vcc, exec, s[16:17]
	v_mul_f32_e32 v44, v160, v3
	v_pk_fma_f32 v[46:47], v[160:161], v[248:249], v[44:45] op_sel_hi:[1,1,0]
	v_pk_fma_f32 v[44:45], v[164:165], v[250:251], v[44:45] op_sel_hi:[1,1,0]
	s_waitcnt lgkmcnt(0)
	s_nop 0
	v_mfma_f32_16x16x32_bf16 v[40:43], v[40:43], v[12:15], v[44:47]
	s_nop 2
	ds_read_b128 v[44:47], v97 offset:2368
	s_waitcnt lgkmcnt(0)
	v_mfma_f32_16x16x32_bf16 v[40:43], v[44:47], v[16:19], v[40:43]
	s_cbranch_vccnz .LBB0_979
	v_add_u32_e32 v3, 0xfffffee1, v2
	v_cmp_lt_i32_e32 vcc, -1, v3
	v_add_u32_e32 v3, 0xfffffed1, v2
	s_nop 3
	v_cndmask_b32_e32 v40, v194, v40, vcc
	v_cmp_lt_i32_e32 vcc, -1, v3
	v_add_u32_e32 v3, 0xfffffec1, v2
	s_nop 0
	v_cndmask_b32_e32 v41, v194, v41, vcc
	v_cmp_lt_i32_e32 vcc, -1, v3
	v_add_u32_e32 v3, 0xfffffeb1, v2
	s_nop 0
	v_cndmask_b32_e32 v42, v194, v42, vcc
	v_cmp_lt_i32_e32 vcc, -1, v3
	s_nop 1
	v_cndmask_b32_e32 v43, v194, v43, vcc
.LBB0_979:
	ds_read_b128 v[44:47], v97 offset:4608
	v_add_u32_e32 v3, 0x200, v1
	v_cvt_f32_i32_e32 v3, v3
	v_mov_b32_e32 v161, v160
	s_and_b64 vcc, exec, s[16:17]
	v_mul_f32_e32 v48, v160, v3
	v_pk_fma_f32 v[50:51], v[160:161], v[248:249], v[48:49] op_sel_hi:[1,1,0]
	v_pk_fma_f32 v[48:49], v[164:165], v[250:251], v[48:49] op_sel_hi:[1,1,0]
	s_waitcnt lgkmcnt(0)
	s_nop 0
	v_mfma_f32_16x16x32_bf16 v[44:47], v[44:47], v[12:15], v[48:51]
	s_nop 2
	ds_read_b128 v[48:51], v97 offset:4672
	s_waitcnt lgkmcnt(0)
	v_mfma_f32_16x16x32_bf16 v[44:47], v[48:51], v[16:19], v[44:47]
	s_cbranch_vccnz .LBB0_981
	v_add_u32_e32 v3, 0xfffffde1, v2
	v_cmp_lt_i32_e32 vcc, -1, v3
	v_add_u32_e32 v3, 0xfffffdd1, v2
	s_nop 3
	v_cndmask_b32_e32 v44, v194, v44, vcc
	v_cmp_lt_i32_e32 vcc, -1, v3
	v_add_u32_e32 v3, 0xfffffdc1, v2
	s_nop 0
	v_cndmask_b32_e32 v45, v194, v45, vcc
	v_cmp_lt_i32_e32 vcc, -1, v3
	v_add_u32_e32 v3, 0xfffffdb1, v2
	s_nop 0
	v_cndmask_b32_e32 v46, v194, v46, vcc
	v_cmp_lt_i32_e32 vcc, -1, v3
	s_nop 1
	v_cndmask_b32_e32 v47, v194, v47, vcc
.LBB0_981:
	ds_read_b128 v[48:51], v97 offset:6912
	v_add_u32_e32 v3, 0x300, v1
	v_cvt_f32_i32_e32 v3, v3
	s_and_b64 vcc, exec, s[16:17]
	v_mul_f32_e32 v52, v160, v3
	v_pk_fma_f32 v[54:55], v[160:161], v[248:249], v[52:53] op_sel_hi:[1,1,0]
	v_pk_fma_f32 v[52:53], v[164:165], v[250:251], v[52:53] op_sel_hi:[1,1,0]
	s_waitcnt lgkmcnt(0)
	s_nop 0
	v_mfma_f32_16x16x32_bf16 v[48:51], v[48:51], v[12:15], v[52:55]
	s_nop 2
	ds_read_b128 v[52:55], v97 offset:6976
	s_waitcnt lgkmcnt(0)
	v_mfma_f32_16x16x32_bf16 v[48:51], v[52:55], v[16:19], v[48:51]
	s_cbranch_vccnz .LBB0_983
	v_add_u32_e32 v3, 0xfffffce1, v2
	v_cmp_lt_i32_e32 vcc, -1, v3
	v_add_u32_e32 v3, 0xfffffcd1, v2
	s_nop 3
	v_cndmask_b32_e32 v48, v194, v48, vcc
	v_cmp_lt_i32_e32 vcc, -1, v3
	v_add_u32_e32 v3, 0xfffffcc1, v2
	s_nop 0
	v_cndmask_b32_e32 v49, v194, v49, vcc
	v_cmp_lt_i32_e32 vcc, -1, v3
	v_add_u32_e32 v3, 0xfffffcb1, v2
	s_nop 0
	v_cndmask_b32_e32 v50, v194, v50, vcc
	v_cmp_lt_i32_e32 vcc, -1, v3
	s_nop 1
	v_cndmask_b32_e32 v51, v194, v51, vcc
; #define LAS __attribute__((address_space(3)))
; #define MFMA16(a, b, c) __builtin_amdgcn_mfma_f32_16x16x32_bf16(a, b, c, 0, 0, 0)
; __device__ __forceinline__ void nsa_phase(LAS unsigned char* lds, const Args& a, const bf16_t* z, const bf16_t* KC, const bf16_t* VCT, const bf16_t* VST, const bf16_t* VWT, bf16_t* A2, int ldo, bool merged) {
;     ...
;             for (int tl = 0; tl < 4; ++tl) {
;                 if (tl <= tlmax) {
; #pragma unroll
;                     for (int s = 0; s < 4; ++s) {
;                         const LAS unsigned char* kp = lds + kcl_off + (tl * 64 + s * 16) * 144;
;                         const bf16x8 k0 = *(const LAS bf16x8*)kp, k1 = *(const LAS bf16x8*)(kp + 64);
;                         const float cb = slope * (float)((tl * 1024 + s * 256 + 64 * g4 + 31) - tq[qs]);
;                         f32x4 zz;
; #pragma unroll
;                         for (int i = 0; i < 4; ++i) zz[i] = fmaf(slope, 16.f * (float)i, cb);
;                         zz = MFMA16(k0, Qf[qs][0], zz);
;                         zz = MFMA16(k1, Qf[qs][1], zz);
;                         if (!((64 * (tl + 1) - 1) <= (4 * qt - 2))) {
; #pragma unroll
;                             for (int i = 0; i < 4; ++i) {
;                                 const int dist = (tq[qs] - 31 - 64 * g4) - (tl * 1024 + s * 256 + 16 * i);
;                                 const bool ok = (dist >= 0) && !(tl == 3 && s == 3 && i == 3 && g4 == 3);
;                                 zz[i] = ok ? zz[i] : -1e30f;
;                             }
;                         }
; #pragma unroll
;                         for (int i = 0; i < 4; ++i) mx = fmaxf(mx, zz[i]);
;                         sc[tl][s] = zz;
;                         __builtin_amdgcn_sched_barrier(0);
;                     }
.LBB0_983:
	v_mov_b32_e32 v55, 0xf149f2ca
	v_max3_f32 v3, v36, v55, v37
	v_max3_f32 v3, v3, v38, v39
	v_max3_f32 v3, v3, v40, v41
	v_max3_f32 v3, v3, v42, v43
	v_max3_f32 v3, v3, v44, v45
	v_max3_f32 v3, v3, v46, v47
	v_max3_f32 v3, v3, v48, v49
	v_max3_f32 v3, v3, v50, v51
	s_and_b64 vcc, exec, s[10:11]
	s_cbranch_vccnz .LBB0_1000
	ds_read_b128 v[52:55], v97 offset:9216
	v_add_u32_e32 v56, 0x400, v1
	v_cvt_f32_i32_e32 v60, v56
	ds_read_b128 v[56:59], v97 offset:9280
	v_mov_b32_e32 v161, v160
	s_cmp_lt_u32 s63, 33
	v_mul_f32_e32 v60, v160, v60
	v_pk_fma_f32 v[62:63], v[160:161], v[248:249], v[60:61] op_sel_hi:[1,1,0]
	v_pk_fma_f32 v[60:61], v[164:165], v[250:251], v[60:61] op_sel_hi:[1,1,0]
	s_cselect_b64 s[16:17], -1, 0
	s_cmp_gt_u32 s63, 32
	s_waitcnt lgkmcnt(1)
	v_mfma_f32_16x16x32_bf16 v[52:55], v[52:55], v[12:15], v[60:63]
	s_waitcnt lgkmcnt(0)
	v_mfma_f32_16x16x32_bf16 v[52:55], v[56:59], v[16:19], v[52:55]
	s_cbranch_scc1 .LBB0_986
	v_add_u32_e32 v56, 0xfffffbe1, v2
	v_cmp_lt_i32_e32 vcc, -1, v56
	v_add_u32_e32 v56, 0xfffffbd1, v2
	s_nop 3
	v_cndmask_b32_e32 v52, v194, v52, vcc
	v_cmp_lt_i32_e32 vcc, -1, v56
	v_add_u32_e32 v56, 0xfffffbc1, v2
	s_nop 0
	v_cndmask_b32_e32 v53, v194, v53, vcc
	v_cmp_lt_i32_e32 vcc, -1, v56
	v_add_u32_e32 v56, 0xfffffbb1, v2
	s_nop 0
	v_cndmask_b32_e32 v54, v194, v54, vcc
	v_cmp_lt_i32_e32 vcc, -1, v56
	s_nop 1
	v_cndmask_b32_e32 v55, v194, v55, vcc
.LBB0_986:
	ds_read_b128 v[56:59], v97 offset:11520
	v_add_u32_e32 v60, 0x500, v1
	v_cvt_f32_i32_e32 v64, v60
	ds_read_b128 v[60:63], v97 offset:11584
	s_andn2_b64 vcc, exec, s[16:17]
	v_mul_f32_e32 v64, v160, v64
	v_pk_fma_f32 v[66:67], v[160:161], v[248:249], v[64:65] op_sel_hi:[1,1,0]
	v_pk_fma_f32 v[64:65], v[164:165], v[250:251], v[64:65] op_sel_hi:[1,1,0]
	s_waitcnt lgkmcnt(1)
	s_nop 0
	v_mfma_f32_16x16x32_bf16 v[56:59], v[56:59], v[12:15], v[64:67]
	s_waitcnt lgkmcnt(0)
	v_mfma_f32_16x16x32_bf16 v[56:59], v[60:63], v[16:19], v[56:59]
	s_nop 0
	v_cndmask_b32_e64 v64, 0, 1, s[16:17]
	v_cmp_ne_u32_e64 s[0:1], 1, v64
	s_cbranch_vccnz .LBB0_988
	v_add_u32_e32 v60, 0xfffffae1, v2
	v_cmp_lt_i32_e32 vcc, -1, v60
	v_add_u32_e32 v60, 0xfffffad1, v2
	s_nop 0
	v_cndmask_b32_e32 v56, v194, v56, vcc
	v_cmp_lt_i32_e32 vcc, -1, v60
	v_add_u32_e32 v60, 0xfffffac1, v2
	s_nop 0
	v_cndmask_b32_e32 v57, v194, v57, vcc
	v_cmp_lt_i32_e32 vcc, -1, v60
	v_add_u32_e32 v60, 0xfffffab1, v2
	s_nop 0
	v_cndmask_b32_e32 v58, v194, v58, vcc
	v_cmp_lt_i32_e32 vcc, -1, v60
	s_nop 1
	v_cndmask_b32_e32 v59, v194, v59, vcc
.LBB0_988:
	ds_read_b128 v[60:63], v97 offset:13824
	v_add_u32_e32 v64, 0x600, v1
	v_cvt_f32_i32_e32 v64, v64
	v_mov_b32_e32 v161, v160
	s_and_b64 vcc, exec, s[0:1]
	v_mul_f32_e32 v64, v160, v64
	v_pk_fma_f32 v[66:67], v[160:161], v[248:249], v[64:65] op_sel_hi:[1,1,0]
	v_pk_fma_f32 v[64:65], v[164:165], v[250:251], v[64:65] op_sel_hi:[1,1,0]
	s_waitcnt lgkmcnt(0)
	s_nop 0
	v_mfma_f32_16x16x32_bf16 v[60:63], v[60:63], v[12:15], v[64:67]
	s_nop 2
	ds_read_b128 v[64:67], v97 offset:13888
	s_waitcnt lgkmcnt(0)
	v_mfma_f32_16x16x32_bf16 v[60:63], v[64:67], v[16:19], v[60:63]
	s_cbranch_vccnz .LBB0_990
	v_add_u32_e32 v64, 0xfffff9e1, v2
	v_cmp_lt_i32_e32 vcc, -1, v64
	v_add_u32_e32 v64, 0xfffff9d1, v2
	s_nop 3
	v_cndmask_b32_e32 v60, v194, v60, vcc
	v_cmp_lt_i32_e32 vcc, -1, v64
	v_add_u32_e32 v64, 0xfffff9c1, v2
	s_nop 0
	v_cndmask_b32_e32 v61, v194, v61, vcc
	v_cmp_lt_i32_e32 vcc, -1, v64
	v_add_u32_e32 v64, 0xfffff9b1, v2
	s_nop 0
	v_cndmask_b32_e32 v62, v194, v62, vcc
	v_cmp_lt_i32_e32 vcc, -1, v64
	s_nop 1
	v_cndmask_b32_e32 v63, v194, v63, vcc
.LBB0_990:
	ds_read_b128 v[64:67], v97 offset:16128
	v_add_u32_e32 v68, 0x700, v1
	v_cvt_f32_i32_e32 v68, v68
	s_and_b64 vcc, exec, s[0:1]
	v_mul_f32_e32 v68, v160, v68
	v_pk_fma_f32 v[70:71], v[160:161], v[248:249], v[68:69] op_sel_hi:[1,1,0]
	v_pk_fma_f32 v[68:69], v[164:165], v[250:251], v[68:69] op_sel_hi:[1,1,0]
	s_waitcnt lgkmcnt(0)
	s_nop 0
	v_mfma_f32_16x16x32_bf16 v[64:67], v[64:67], v[12:15], v[68:71]
	s_nop 2
	ds_read_b128 v[68:71], v97 offset:16192
	s_waitcnt lgkmcnt(0)
	v_mfma_f32_16x16x32_bf16 v[64:67], v[68:71], v[16:19], v[64:67]
	s_cbranch_vccnz .LBB0_992
	v_add_u32_e32 v68, 0xfffff8e1, v2
	v_cmp_lt_i32_e32 vcc, -1, v68
	v_add_u32_e32 v68, 0xfffff8d1, v2
	s_nop 3
	v_cndmask_b32_e32 v64, v194, v64, vcc
	v_cmp_lt_i32_e32 vcc, -1, v68
	v_add_u32_e32 v68, 0xfffff8c1, v2
	s_nop 0
	v_cndmask_b32_e32 v65, v194, v65, vcc
	v_cmp_lt_i32_e32 vcc, -1, v68
	v_add_u32_e32 v68, 0xfffff8b1, v2
	s_nop 0
	v_cndmask_b32_e32 v66, v194, v66, vcc
	v_cmp_lt_i32_e32 vcc, -1, v68
	s_nop 1
	v_cndmask_b32_e32 v67, v194, v67, vcc

; #define LAS __attribute__((address_space(3)))
; #define MFMA16(a, b, c) __builtin_amdgcn_mfma_f32_16x16x32_bf16(a, b, c, 0, 0, 0)
; __device__ __forceinline__ void nsa_phase(LAS unsigned char* lds, const Args& a, const bf16_t* z, const bf16_t* KC, const bf16_t* VCT, const bf16_t* VST, const bf16_t* VWT, bf16_t* A2, int ldo, bool merged) {
;     ...
;             for (int tl = 0; tl < 4; ++tl) {
;                 if (tl <= tlmax) {
; #pragma unroll
;                     for (int s = 0; s < 4; ++s) {
;                         const LAS unsigned char* kp = lds + kcl_off + (tl * 64 + s * 16) * 144;
;                         const bf16x8 k0 = *(const LAS bf16x8*)kp, k1 = *(const LAS bf16x8*)(kp + 64);
;                         const float cb = slope * (float)((tl * 1024 + s * 256 + 64 * g4 + 31) - tq[qs]);
;                         f32x4 zz;
; #pragma unroll
;                         for (int i = 0; i < 4; ++i) zz[i] = fmaf(slope, 16.f * (float)i, cb);
;                         zz = MFMA16(k0, Qf[qs][0], zz);
;                         zz = MFMA16(k1, Qf[qs][1], zz);
;                         if (!((64 * (tl + 1) - 1) <= (4 * qt - 2))) {
; #pragma unroll
;                             for (int i = 0; i < 4; ++i) {
;                                 const int dist = (tq[qs] - 31 - 64 * g4) - (tl * 1024 + s * 256 + 16 * i);
;                                 const bool ok = (dist >= 0) && !(tl == 3 && s == 3 && i == 3 && g4 == 3);
;                                 zz[i] = ok ? zz[i] : -1e30f;
;                             }
;                         }
; #pragma unroll
;                         for (int i = 0; i < 4; ++i) mx = fmaxf(mx, zz[i]);
;                         sc[tl][s] = zz;
;                         __builtin_amdgcn_sched_barrier(0);
;                     }
.LBB0_1001:
	ds_read_b128 v[68:71], v97 offset:18432
	v_add_u32_e32 v72, 0x800, v1
	v_cvt_f32_i32_e32 v76, v72
	ds_read_b128 v[72:75], v97 offset:18496
	v_mov_b32_e32 v161, v160
	s_cmp_lt_u32 s63, 49
	v_mul_f32_e32 v76, v160, v76
	v_pk_fma_f32 v[78:79], v[160:161], v[248:249], v[76:77] op_sel_hi:[1,1,0]
	v_pk_fma_f32 v[76:77], v[164:165], v[250:251], v[76:77] op_sel_hi:[1,1,0]
	s_cselect_b64 s[16:17], -1, 0
	s_cmp_gt_u32 s63, 48
	s_waitcnt lgkmcnt(1)
	v_mfma_f32_16x16x32_bf16 v[68:71], v[68:71], v[12:15], v[76:79]
	s_waitcnt lgkmcnt(0)
	v_mfma_f32_16x16x32_bf16 v[68:71], v[72:75], v[16:19], v[68:71]
	s_cbranch_scc1 .LBB0_1003
	v_add_u32_e32 v72, 0xfffff7e1, v2
	v_cmp_lt_i32_e32 vcc, -1, v72
	v_add_u32_e32 v72, 0xfffff7d1, v2
	s_nop 3
	v_cndmask_b32_e32 v68, v194, v68, vcc
	v_cmp_lt_i32_e32 vcc, -1, v72
	v_add_u32_e32 v72, 0xfffff7c1, v2
	s_nop 0
	v_cndmask_b32_e32 v69, v194, v69, vcc
	v_cmp_lt_i32_e32 vcc, -1, v72
	v_add_u32_e32 v72, 0xfffff7b1, v2
	s_nop 0
	v_cndmask_b32_e32 v70, v194, v70, vcc
	v_cmp_lt_i32_e32 vcc, -1, v72
	s_nop 1
	v_cndmask_b32_e32 v71, v194, v71, vcc
.LBB0_1003:
	ds_read_b128 v[72:75], v97 offset:20736
	v_add_u32_e32 v76, 0x900, v1
	v_cvt_f32_i32_e32 v80, v76
	ds_read_b128 v[76:79], v97 offset:20800
	s_andn2_b64 vcc, exec, s[16:17]
	v_mul_f32_e32 v80, v160, v80
	v_pk_fma_f32 v[82:83], v[160:161], v[248:249], v[80:81] op_sel_hi:[1,1,0]
	v_pk_fma_f32 v[80:81], v[164:165], v[250:251], v[80:81] op_sel_hi:[1,1,0]
	s_waitcnt lgkmcnt(1)
	s_nop 0
	v_mfma_f32_16x16x32_bf16 v[72:75], v[72:75], v[12:15], v[80:83]
	s_waitcnt lgkmcnt(0)
	v_mfma_f32_16x16x32_bf16 v[72:75], v[76:79], v[16:19], v[72:75]
	s_nop 0
	v_cndmask_b32_e64 v80, 0, 1, s[16:17]
	v_cmp_ne_u32_e64 s[0:1], 1, v80
	s_cbranch_vccnz .LBB0_1005
	v_add_u32_e32 v76, 0xfffff6e1, v2
	v_cmp_lt_i32_e32 vcc, -1, v76
	v_add_u32_e32 v76, 0xfffff6d1, v2
	s_nop 0
	v_cndmask_b32_e32 v72, v194, v72, vcc
	v_cmp_lt_i32_e32 vcc, -1, v76
	v_add_u32_e32 v76, 0xfffff6c1, v2
	s_nop 0
	v_cndmask_b32_e32 v73, v194, v73, vcc
	v_cmp_lt_i32_e32 vcc, -1, v76
	v_add_u32_e32 v76, 0xfffff6b1, v2
	s_nop 0
	v_cndmask_b32_e32 v74, v194, v74, vcc
	v_cmp_lt_i32_e32 vcc, -1, v76
	s_nop 1
	v_cndmask_b32_e32 v75, v194, v75, vcc
.LBB0_1005:
	ds_read_b128 v[76:79], v97 offset:23040
	v_add_u32_e32 v80, 0xa00, v1
	v_cvt_f32_i32_e32 v80, v80
	v_mov_b32_e32 v161, v160
	s_and_b64 vcc, exec, s[0:1]
	v_mul_f32_e32 v80, v160, v80
	v_pk_fma_f32 v[82:83], v[160:161], v[248:249], v[80:81] op_sel_hi:[1,1,0]
	v_pk_fma_f32 v[80:81], v[164:165], v[250:251], v[80:81] op_sel_hi:[1,1,0]
	s_waitcnt lgkmcnt(0)
	s_nop 0
	v_mfma_f32_16x16x32_bf16 v[76:79], v[76:79], v[12:15], v[80:83]
	s_nop 2
	ds_read_b128 v[80:83], v97 offset:23104
	s_waitcnt lgkmcnt(0)
	v_mfma_f32_16x16x32_bf16 v[76:79], v[80:83], v[16:19], v[76:79]
	s_cbranch_vccnz .LBB0_1007
	v_add_u32_e32 v80, 0xfffff5e1, v2
	v_cmp_lt_i32_e32 vcc, -1, v80
	v_add_u32_e32 v80, 0xfffff5d1, v2
	s_nop 3
	v_cndmask_b32_e32 v76, v194, v76, vcc
	v_cmp_lt_i32_e32 vcc, -1, v80
	v_add_u32_e32 v80, 0xfffff5c1, v2
	s_nop 0
	v_cndmask_b32_e32 v77, v194, v77, vcc
	v_cmp_lt_i32_e32 vcc, -1, v80
	v_add_u32_e32 v80, 0xfffff5b1, v2
	s_nop 0
	v_cndmask_b32_e32 v78, v194, v78, vcc
	v_cmp_lt_i32_e32 vcc, -1, v80
	s_nop 1
	v_cndmask_b32_e32 v79, v194, v79, vcc
.LBB0_1007:
	ds_read_b128 v[80:83], v97 offset:25344
	v_add_u32_e32 v84, 0xb00, v1
	v_cvt_f32_i32_e32 v84, v84
	s_and_b64 vcc, exec, s[0:1]
	v_mul_f32_e32 v84, v160, v84
	v_pk_fma_f32 v[86:87], v[160:161], v[248:249], v[84:85] op_sel_hi:[1,1,0]
	v_pk_fma_f32 v[84:85], v[164:165], v[250:251], v[84:85] op_sel_hi:[1,1,0]
	s_waitcnt lgkmcnt(0)
	s_nop 0
	v_mfma_f32_16x16x32_bf16 v[80:83], v[80:83], v[12:15], v[84:87]
	s_nop 2
	ds_read_b128 v[84:87], v97 offset:25408
	s_waitcnt lgkmcnt(0)
	v_mfma_f32_16x16x32_bf16 v[84:87], v[84:87], v[16:19], v[80:83]
	s_cbranch_vccnz .LBB0_1009
	s_nop 1
	v_add_u32_e32 v80, 0xfffff4e1, v2
	v_cmp_lt_i32_e32 vcc, -1, v80
	v_add_u32_e32 v80, 0xfffff4d1, v2
	s_nop 1
	v_cndmask_b32_e32 v84, v194, v84, vcc
	v_cmp_lt_i32_e32 vcc, -1, v80
	v_add_u32_e32 v80, 0xfffff4c1, v2
	s_nop 0
	v_cndmask_b32_e32 v85, v194, v85, vcc
	v_cmp_lt_i32_e32 vcc, -1, v80
	v_add_u32_e32 v80, 0xfffff4b1, v2
	s_nop 0
	v_cndmask_b32_e32 v86, v194, v86, vcc
	v_cmp_lt_i32_e32 vcc, -1, v80
	s_nop 1
	v_cndmask_b32_e32 v87, v194, v87, vcc

; #define LAS __attribute__((address_space(3)))
; #define MFMA16(a, b, c) __builtin_amdgcn_mfma_f32_16x16x32_bf16(a, b, c, 0, 0, 0)
; __device__ __forceinline__ void nsa_phase(LAS unsigned char* lds, const Args& a, const bf16_t* z, const bf16_t* KC, const bf16_t* VCT, const bf16_t* VST, const bf16_t* VWT, bf16_t* A2, int ldo, bool merged) {
;     ...
;             for (int tl = 0; tl < 4; ++tl) {
;                 if (tl <= tlmax) {
; #pragma unroll
;                     for (int s = 0; s < 4; ++s) {
;                         const LAS unsigned char* kp = lds + kcl_off + (tl * 64 + s * 16) * 144;
;                         const bf16x8 k0 = *(const LAS bf16x8*)kp, k1 = *(const LAS bf16x8*)(kp + 64);
;                         const float cb = slope * (float)((tl * 1024 + s * 256 + 64 * g4 + 31) - tq[qs]);
;                         f32x4 zz;
; #pragma unroll
;                         for (int i = 0; i < 4; ++i) zz[i] = fmaf(slope, 16.f * (float)i, cb);
;                         zz = MFMA16(k0, Qf[qs][0], zz);
;                         zz = MFMA16(k1, Qf[qs][1], zz);
;                         if (!((64 * (tl + 1) - 1) <= (4 * qt - 2))) {
; #pragma unroll
;                             for (int i = 0; i < 4; ++i) {
;                                 const int dist = (tq[qs] - 31 - 64 * g4) - (tl * 1024 + s * 256 + 16 * i);
;                                 const bool ok = (dist >= 0) && !(tl == 3 && s == 3 && i == 3 && g4 == 3);
;                                 zz[i] = ok ? zz[i] : -1e30f;
;                             }
;                         }
; #pragma unroll
;                         for (int i = 0; i < 4; ++i) mx = fmaxf(mx, zz[i]);
.LBB0_1010:
	ds_read_b128 v[80:83], v97 offset:27648
	v_add_u32_e32 v88, 0xc00, v1
	v_cvt_f32_i32_e32 v92, v88
	ds_read_b128 v[88:91], v97 offset:27712
	v_mov_b32_e32 v161, v160
	v_mul_f32_e32 v92, v160, v92
	v_pk_fma_f32 v[94:95], v[160:161], v[248:249], v[92:93] op_sel_hi:[1,1,0]
	v_pk_fma_f32 v[92:93], v[164:165], v[250:251], v[92:93] op_sel_hi:[1,1,0]
	s_waitcnt lgkmcnt(1)
	s_nop 0
	v_mfma_f32_16x16x32_bf16 v[80:83], v[80:83], v[12:15], v[92:95]
	s_waitcnt lgkmcnt(0)
	v_mfma_f32_16x16x32_bf16 v[80:83], v[88:91], v[16:19], v[80:83]
	s_nop 0
	v_add_u32_e32 v92, 0xfffff3e1, v2
	v_add_u32_e32 v93, 0xfffff3d1, v2
	v_cmp_lt_i32_e32 vcc, -1, v92
	v_add_u32_e32 v94, 0xfffff3c1, v2
	s_nop 2
	v_cndmask_b32_e32 v119, v194, v80, vcc
	v_cmp_lt_i32_e32 vcc, -1, v93
	v_add_u32_e32 v80, 0xfffff3b1, v2
	s_nop 0
	v_cndmask_b32_e32 v120, v194, v81, vcc
	v_cmp_lt_i32_e32 vcc, -1, v94
	v_max3_f32 v3, v3, v119, v120
	s_nop 0
	v_cndmask_b32_e32 v121, v194, v82, vcc
	v_cmp_lt_i32_e32 vcc, -1, v80
	s_nop 1
	v_cndmask_b32_e32 v122, v194, v83, vcc
	v_max3_f32 v3, v3, v121, v122
	ds_read_b128 v[80:83], v97 offset:29952
	v_add_u32_e32 v88, 0xd00, v1
	v_cvt_f32_i32_e32 v92, v88
	ds_read_b128 v[88:91], v97 offset:30016
	v_mul_f32_e32 v92, v160, v92
	v_pk_fma_f32 v[94:95], v[160:161], v[248:249], v[92:93] op_sel_hi:[1,1,0]
	v_pk_fma_f32 v[92:93], v[164:165], v[250:251], v[92:93] op_sel_hi:[1,1,0]
	s_waitcnt lgkmcnt(1)
	s_nop 0
	v_mfma_f32_16x16x32_bf16 v[80:83], v[80:83], v[12:15], v[92:95]
	s_waitcnt lgkmcnt(0)
	v_mfma_f32_16x16x32_bf16 v[80:83], v[88:91], v[16:19], v[80:83]
	s_nop 0
	v_add_u32_e32 v92, 0xfffff2e1, v2
	v_add_u32_e32 v93, 0xfffff2d1, v2
	v_cmp_lt_i32_e32 vcc, -1, v92
	v_add_u32_e32 v94, 0xfffff2c1, v2
	s_nop 2
	v_cndmask_b32_e32 v123, v194, v80, vcc
	v_cmp_lt_i32_e32 vcc, -1, v93
	v_add_u32_e32 v80, 0xfffff2b1, v2
	s_nop 0
	v_cndmask_b32_e32 v124, v194, v81, vcc
	v_cmp_lt_i32_e32 vcc, -1, v94
	v_max3_f32 v3, v3, v123, v124
	s_nop 0
	v_cndmask_b32_e32 v125, v194, v82, vcc
	v_cmp_lt_i32_e32 vcc, -1, v80
	s_nop 1
	v_cndmask_b32_e32 v126, v194, v83, vcc
	v_max3_f32 v3, v3, v125, v126
	ds_read_b128 v[80:83], v97 offset:32256
	v_add_u32_e32 v88, 0xe00, v1
	v_cvt_f32_i32_e32 v92, v88
	ds_read_b128 v[88:91], v97 offset:32320
	v_mul_f32_e32 v92, v160, v92
	v_pk_fma_f32 v[94:95], v[160:161], v[248:249], v[92:93] op_sel_hi:[1,1,0]
	v_pk_fma_f32 v[92:93], v[164:165], v[250:251], v[92:93] op_sel_hi:[1,1,0]
	s_waitcnt lgkmcnt(1)
	s_nop 0
	v_mfma_f32_16x16x32_bf16 v[80:83], v[80:83], v[12:15], v[92:95]
	s_waitcnt lgkmcnt(0)
	v_mfma_f32_16x16x32_bf16 v[80:83], v[88:91], v[16:19], v[80:83]
	s_nop 0
	v_add_u32_e32 v92, 0xfffff1e1, v2
	v_add_u32_e32 v93, 0xfffff1d1, v2
	v_cmp_lt_i32_e32 vcc, -1, v92
	v_add_u32_e32 v94, 0xfffff1c1, v2
	s_nop 2
	v_cndmask_b32_e32 v127, v194, v80, vcc
	v_cmp_lt_i32_e32 vcc, -1, v93
	v_add_u32_e32 v80, 0xfffff1b1, v2
	s_nop 0
	v_cndmask_b32_e32 v128, v194, v81, vcc
	v_cmp_lt_i32_e32 vcc, -1, v94
	v_max3_f32 v3, v3, v127, v128
	s_nop 0
	v_cndmask_b32_e32 v129, v194, v82, vcc
	v_cmp_lt_i32_e32 vcc, -1, v80
	s_nop 1
	v_cndmask_b32_e32 v137, v194, v83, vcc
	v_max3_f32 v3, v3, v129, v137
	ds_read_b128 v[80:83], v97 offset:34560
	ds_read_b128 v[88:91], v97 offset:34624
	v_add_u32_e32 v1, 0xf00, v1
	v_cvt_f32_i32_e32 v1, v1
	v_mul_f32_e32 v92, v160, v1
	v_pk_fma_f32 v[94:95], v[160:161], v[248:249], v[92:93] op_sel_hi:[1,1,0]
	v_pk_fma_f32 v[92:93], v[164:165], v[250:251], v[92:93] op_sel_hi:[1,1,0]
	v_add_u32_e32 v1, 0xfffff0e1, v2
	v_cmp_lt_i32_e32 vcc, -1, v1
	s_waitcnt lgkmcnt(1)
	v_mfma_f32_16x16x32_bf16 v[80:83], v[80:83], v[12:15], v[92:95]
	v_add_u32_e32 v1, 0xfffff0b1, v2
	s_waitcnt lgkmcnt(0)
	v_mfma_f32_16x16x32_bf16 v[80:83], v[88:91], v[16:19], v[80:83]
	v_add_u32_e32 v92, 0xfffff0d1, v2
	v_add_u32_e32 v93, 0xfffff0c1, v2
	s_nop 5
	v_cndmask_b32_e32 v140, v194, v80, vcc
	v_cmp_lt_i32_e32 vcc, -1, v92
	s_nop 1
	v_cndmask_b32_e32 v141, v194, v81, vcc
	v_cmp_lt_i32_e32 vcc, -1, v93
	s_nop 1
	v_cndmask_b32_e32 v142, v194, v82, vcc
	v_cmp_lt_i32_e32 vcc, -1, v1
	s_and_b64 vcc, vcc, s[14:15]
	v_max3_f32 v1, v3, v140, v141
	v_cndmask_b32_e32 v143, v194, v83, vcc
	v_max3_f32 v3, v1, v142, v143

; #define LAS __attribute__((address_space(3)))
; #define MFMA16(a, b, c) __builtin_amdgcn_mfma_f32_16x16x32_bf16(a, b, c, 0, 0, 0)
; template <int MODE> ...
;     ...
;     for (int qs = 0; qs < 2; ++qs) cb[qs] = slope * (float)(key0 + 4 * g4 - tq[qs]) + ((MODE == 1 && !selb[qs]) ? -1e30f : 0.f);
;     __builtin_amdgcn_s_setprio(1);
; #pragma unroll
;     for (int s = 0; s < 4; ++s) {
;         const LAS unsigned char* kp = KT + (s * 16) * 144;
;         const bf16x8 k0 = *(const LAS bf16x8*)kp, k1 = *(const LAS bf16x8*)(kp + 64);
; #pragma unroll
;         for (int qs = 0; qs < 2; ++qs) {
;             f32x4 zz;
; #pragma unroll
;             for (int i = 0; i < 4; ++i) zz[i] = fmaf(slope, (float)(s * 16 + i), cb[qs]);
;             zz = MFMA16(k0, Qf[qs][0], zz);
;             sc[s][qs] = MFMA16(k1, Qf[qs][1], zz);
;         }
;         __builtin_amdgcn_sched_barrier(0);
;     }
; __device__ __forceinline__ void nsa_phase(LAS unsigned char* lds, const Args& a, const bf16_t* z, const bf16_t* KC, const bf16_t* VCT, const bf16_t* VST, const bf16_t* VWT, bf16_t* A2, int ldo, bool merged) {
;     ...
;                 const bool selb[2] = {(bool)((msk[0] >> jc) & 1ull), (bool)((msk[1] >> jc) & 1ull)};
;                 flash_tile<1>(lds, kt_off, vt_off, Qf, O, mrun, lrun, slope, tq, jc * 64, selb, l15, g4, jc < cur);
.LBB0_1104:
	v_lshrrev_b64 v[92:93], s9, v[124:125]
	v_and_b32_e32 v94, 1, v92
	v_lshrrev_b64 v[92:93], s9, v[128:129]
	s_lshl_b32 s6, s9, 6
	v_mov_b32_e32 v147, v203
	v_mov_b32_e32 v93, v1
	v_add_u32_e32 v148, s6, v141
	v_add_u32_e32 v149, 0, v93
	v_sub_u32_e32 v93, v148, v138
	v_cmp_eq_u32_e32 vcc, 1, v94
	v_sub_u32_e32 v94, v148, v139
	v_cvt_f32_i32_e32 v93, v93
	v_cvt_f32_i32_e32 v94, v94
	v_and_b32_e32 v92, 1, v92
	v_cndmask_b32_e64 v150, v194, 0, vcc
	v_cmp_eq_u32_e32 vcc, 1, v92
	s_cmp_lt_i32 s9, s63
	v_fmac_f32_e32 v150, v160, v93
	v_cndmask_b32_e64 v154, v194, 0, vcc
	v_fmac_f32_e32 v154, v160, v94
	s_nop 0
	ds_read_b128 v[92:95], v149
	v_fma_f32 v96, 0, v160, v150
	v_add_f32_e32 v97, v160, v150
	v_pk_fma_f32 v[98:99], v[162:163], v[228:229], v[150:151] op_sel_hi:[1,1,0]
	v_fma_f32 v100, 0, v160, v154
	v_add_f32_e32 v101, v160, v154
	v_pk_fma_f32 v[102:103], v[162:163], v[228:229], v[154:155] op_sel_hi:[1,1,0]
	s_waitcnt lgkmcnt(0)
	v_mfma_f32_16x16x32_bf16 v[96:99], v[92:95], v[4:7], v[96:99]
	v_mfma_f32_16x16x32_bf16 v[92:95], v[92:95], v[12:15], v[100:103]
	s_nop 2
	ds_read_b128 v[100:103], v149 offset:64
	s_waitcnt lgkmcnt(0)
	v_mfma_f32_16x16x32_bf16 v[104:107], v[100:103], v[8:11], v[96:99]
	v_mfma_f32_16x16x32_bf16 v[92:95], v[100:103], v[16:19], v[92:95]
	s_nop 1
	ds_read_b128 v[96:99], v149 offset:2304
	v_mov_b32_e32 v161, v160
	v_pk_fma_f32 v[100:101], v[164:165], v[232:233], v[150:151] op_sel_hi:[1,1,0]
	v_pk_fma_f32 v[102:103], v[160:161], v[236:237], v[150:151] op_sel_hi:[1,1,0]
	v_pk_fma_f32 v[108:109], v[164:165], v[232:233], v[154:155] op_sel_hi:[1,1,0]
	v_pk_fma_f32 v[110:111], v[160:161], v[236:237], v[154:155] op_sel_hi:[1,1,0]
	s_waitcnt lgkmcnt(0)
	v_mfma_f32_16x16x32_bf16 v[100:103], v[96:99], v[4:7], v[100:103]
	v_mfma_f32_16x16x32_bf16 v[96:99], v[96:99], v[12:15], v[108:111]
	s_nop 2
	ds_read_b128 v[108:111], v149 offset:2368
	s_waitcnt lgkmcnt(0)
	v_mfma_f32_16x16x32_bf16 v[112:115], v[108:111], v[8:11], v[100:103]
	v_mfma_f32_16x16x32_bf16 v[96:99], v[108:111], v[16:19], v[96:99]
	s_nop 1
	ds_read_b128 v[100:103], v149 offset:4608
	ds_read_b128 v[120:123], v149 offset:4672
	v_pk_fma_f32 v[110:111], v[160:161], v[238:239], v[150:151] op_sel_hi:[1,1,0]
	v_pk_fma_f32 v[108:109], v[164:165], v[240:241], v[150:151] op_sel_hi:[1,1,0]
	v_pk_fma_f32 v[118:119], v[160:161], v[238:239], v[154:155] op_sel_hi:[1,1,0]
	v_pk_fma_f32 v[116:117], v[164:165], v[240:241], v[154:155] op_sel_hi:[1,1,0]
	s_waitcnt lgkmcnt(1)
	v_mfma_f32_16x16x32_bf16 v[108:111], v[100:103], v[4:7], v[108:111]
	v_mfma_f32_16x16x32_bf16 v[100:103], v[100:103], v[12:15], v[116:119]
	s_waitcnt lgkmcnt(0)
	v_mfma_f32_16x16x32_bf16 v[116:119], v[120:123], v[8:11], v[108:111]
	v_mfma_f32_16x16x32_bf16 v[100:103], v[120:123], v[16:19], v[100:103]
	s_nop 3
	ds_read_b128 v[108:111], v149 offset:6912
	v_pk_fma_f32 v[122:123], v[160:161], v[242:243], v[150:151] op_sel_hi:[1,1,0]
	v_pk_fma_f32 v[120:121], v[164:165], v[244:245], v[150:151] op_sel_hi:[1,1,0]
	v_pk_fma_f32 v[152:153], v[160:161], v[242:243], v[154:155] op_sel_hi:[1,1,0]
	v_pk_fma_f32 v[150:151], v[164:165], v[244:245], v[154:155] op_sel_hi:[1,1,0]
	s_waitcnt lgkmcnt(0)
	v_mfma_f32_16x16x32_bf16 v[120:123], v[108:111], v[4:7], v[120:123]
	v_mfma_f32_16x16x32_bf16 v[108:111], v[108:111], v[12:15], v[150:153]
	s_nop 2
	ds_read_b128 v[150:153], v149 offset:6976
	s_waitcnt lgkmcnt(0)
	v_mfma_f32_16x16x32_bf16 v[120:123], v[150:153], v[8:11], v[120:123]
	v_mfma_f32_16x16x32_bf16 v[108:111], v[150:153], v[16:19], v[108:111]
	s_nop 0
	s_cbranch_scc1 .LBB0_1106
; template <int MODE> ...
;     ...
;     if (!full) {
; #pragma unroll
;         for (int qs = 0; qs < 2; ++qs)
; #pragma unroll
;             for (int s = 0; s < 4; ++s)
; #pragma unroll
;                 for (int i = 0; i < 4; ++i) {
;                     const int dist = (tq[qs] - key0 - 4 * g4) - (s * 16 + i);
;                     const bool ok = (MODE == 1) ? (dist >= 0) : (dist >= 0 && dist < 512);
;                     sc[s][qs][i] = ok ? sc[s][qs][i] : -1e30f;
;                 }
	v_sub_u32_e32 v149, v138, v148
	v_cmp_lt_i32_e32 vcc, -1, v149
	v_or_b32_e32 v149, 1, v148
	v_sub_u32_e32 v150, v138, v149
	v_cndmask_b32_e32 v104, v194, v104, vcc
	v_cmp_lt_i32_e32 vcc, -1, v150
	v_or_b32_e32 v150, 2, v148
	v_sub_u32_e32 v151, v138, v150
	v_cndmask_b32_e32 v105, v194, v105, vcc
	v_cmp_lt_i32_e32 vcc, -1, v151
	v_or_b32_e32 v151, 3, v148
	v_sub_u32_e32 v152, v138, v151
	v_cndmask_b32_e32 v106, v194, v106, vcc
	v_cmp_lt_i32_e32 vcc, -1, v152
	v_add_u32_e32 v152, 16, v148
	v_sub_u32_e32 v153, v138, v152
	v_cndmask_b32_e32 v107, v194, v107, vcc
	v_cmp_lt_i32_e32 vcc, -1, v153
	v_add_u32_e32 v153, 17, v148
	v_sub_u32_e32 v154, v138, v153
	v_cndmask_b32_e32 v112, v194, v112, vcc
	v_cmp_lt_i32_e32 vcc, -1, v154
	v_add_u32_e32 v154, 18, v148
	v_sub_u32_e32 v155, v138, v154
	v_cndmask_b32_e32 v113, v194, v113, vcc
	v_cmp_lt_i32_e32 vcc, -1, v155
	v_add_u32_e32 v155, 19, v148
	v_sub_u32_e32 v161, v138, v155
	v_cndmask_b32_e32 v114, v194, v114, vcc
	v_cmp_lt_i32_e32 vcc, -1, v161
	v_add_u32_e32 v161, 32, v148
	v_sub_u32_e32 v176, v138, v161
	v_cndmask_b32_e32 v115, v194, v115, vcc
	v_cmp_lt_i32_e32 vcc, -1, v176
	v_add_u32_e32 v176, 33, v148
	v_sub_u32_e32 v177, v138, v176
	v_cndmask_b32_e32 v116, v194, v116, vcc
	v_cmp_lt_i32_e32 vcc, -1, v177
	v_add_u32_e32 v177, 34, v148
	v_sub_u32_e32 v178, v138, v177
	v_cndmask_b32_e32 v117, v194, v117, vcc
	v_cmp_lt_i32_e32 vcc, -1, v178
	v_add_u32_e32 v178, 35, v148
	v_sub_u32_e32 v179, v138, v178
	v_cndmask_b32_e32 v118, v194, v118, vcc
	v_cmp_lt_i32_e32 vcc, -1, v179
	v_add_u32_e32 v179, 48, v148
	v_sub_u32_e32 v180, v138, v179
	v_cndmask_b32_e32 v119, v194, v119, vcc
	v_cmp_lt_i32_e32 vcc, -1, v180
	v_add_u32_e32 v180, 49, v148
	v_sub_u32_e32 v181, v138, v180
	v_cndmask_b32_e32 v120, v194, v120, vcc
	v_cmp_lt_i32_e32 vcc, -1, v181
	v_add_u32_e32 v181, 50, v148
	v_sub_u32_e32 v182, v138, v181
	v_cndmask_b32_e32 v121, v194, v121, vcc
	v_cmp_lt_i32_e32 vcc, -1, v182
	v_add_u32_e32 v182, 51, v148
	v_sub_u32_e32 v183, v138, v182
	v_cndmask_b32_e32 v122, v194, v122, vcc
	v_cmp_lt_i32_e32 vcc, -1, v183
	v_sub_u32_e32 v148, v139, v148
	s_nop 0
	v_cndmask_b32_e32 v123, v194, v123, vcc
	v_cmp_lt_i32_e32 vcc, -1, v148
	v_sub_u32_e32 v148, v139, v149
	s_nop 0
	v_cndmask_b32_e32 v92, v194, v92, vcc
	v_cmp_lt_i32_e32 vcc, -1, v148
	v_sub_u32_e32 v148, v139, v150
	s_nop 0
	v_cndmask_b32_e32 v93, v194, v93, vcc
	v_cmp_lt_i32_e32 vcc, -1, v148
	v_sub_u32_e32 v148, v139, v151
	s_nop 0
	v_cndmask_b32_e32 v94, v194, v94, vcc
	v_cmp_lt_i32_e32 vcc, -1, v148
	v_sub_u32_e32 v148, v139, v152
	s_nop 0
	v_cndmask_b32_e32 v95, v194, v95, vcc
	v_cmp_lt_i32_e32 vcc, -1, v148
	v_sub_u32_e32 v148, v139, v153
	s_nop 0
	v_cndmask_b32_e32 v96, v194, v96, vcc
	v_cmp_lt_i32_e32 vcc, -1, v148
	v_sub_u32_e32 v148, v139, v154
	s_nop 0
	v_cndmask_b32_e32 v97, v194, v97, vcc
	v_cmp_lt_i32_e32 vcc, -1, v148
	v_sub_u32_e32 v148, v139, v155
	s_nop 0
	v_cndmask_b32_e32 v98, v194, v98, vcc
	v_cmp_lt_i32_e32 vcc, -1, v148
	v_sub_u32_e32 v148, v139, v161
	s_nop 0
	v_cndmask_b32_e32 v99, v194, v99, vcc
	v_cmp_lt_i32_e32 vcc, -1, v148
	v_sub_u32_e32 v148, v139, v176
	s_nop 0
	v_cndmask_b32_e32 v100, v194, v100, vcc
	v_cmp_lt_i32_e32 vcc, -1, v148
	v_sub_u32_e32 v148, v139, v177
	s_nop 0
	v_cndmask_b32_e32 v101, v194, v101, vcc
	v_cmp_lt_i32_e32 vcc, -1, v148
	v_sub_u32_e32 v148, v139, v178
	s_nop 0
	v_cndmask_b32_e32 v102, v194, v102, vcc
	v_cmp_lt_i32_e32 vcc, -1, v148
	v_sub_u32_e32 v148, v139, v179
	s_nop 0
	v_cndmask_b32_e32 v103, v194, v103, vcc
	v_cmp_lt_i32_e32 vcc, -1, v148
	v_sub_u32_e32 v148, v139, v180
	s_nop 0
	v_cndmask_b32_e32 v108, v194, v108, vcc
	v_cmp_lt_i32_e32 vcc, -1, v148
	v_sub_u32_e32 v148, v139, v181
	s_nop 0
	v_cndmask_b32_e32 v109, v194, v109, vcc
	v_cmp_lt_i32_e32 vcc, -1, v148
	v_sub_u32_e32 v148, v139, v182
	s_nop 0
	v_cndmask_b32_e32 v110, v194, v110, vcc
	v_cmp_lt_i32_e32 vcc, -1, v148
	s_nop 1
	v_cndmask_b32_e32 v111, v194, v111, vcc

; #define LAS __attribute__((address_space(3)))
; #define MFMA16(a, b, c) __builtin_amdgcn_mfma_f32_16x16x32_bf16(a, b, c, 0, 0, 0)
; template <int MODE> ...
;     ...
;     for (int qs = 0; qs < 2; ++qs) cb[qs] = slope * (float)(key0 + 4 * g4 - tq[qs]) + ((MODE == 1 && !selb[qs]) ? -1e30f : 0.f);
;     __builtin_amdgcn_s_setprio(1);
; #pragma unroll
;     for (int s = 0; s < 4; ++s) {
;         const LAS unsigned char* kp = KT + (s * 16) * 144;
;         const bf16x8 k0 = *(const LAS bf16x8*)kp, k1 = *(const LAS bf16x8*)(kp + 64);
; #pragma unroll
;         for (int qs = 0; qs < 2; ++qs) {
;             f32x4 zz;
; #pragma unroll
;             for (int i = 0; i < 4; ++i) zz[i] = fmaf(slope, (float)(s * 16 + i), cb[qs]);
;             zz = MFMA16(k0, Qf[qs][0], zz);
;             sc[s][qs] = MFMA16(k1, Qf[qs][1], zz);
;         }
;         __builtin_amdgcn_sched_barrier(0);
;     }
;     __builtin_amdgcn_s_setprio(0);
;     if (!full) {
; #pragma unroll
;         for (int qs = 0; qs < 2; ++qs)
; #pragma unroll
;             for (int s = 0; s < 4; ++s)
; #pragma unroll
;                 for (int i = 0; i < 4; ++i) {
;                     const int dist = (tq[qs] - key0 - 4 * g4) - (s * 16 + i);
;                     const bool ok = (MODE == 1) ? (dist >= 0) : (dist >= 0 && dist < 512);
;                     sc[s][qs][i] = ok ? sc[s][qs][i] : -1e30f;
;                 }
;     }
.LBB0_1118:
	v_add_u32_e32 v125, s79, v204
	v_cvt_f32_i32_e32 v126, v125
	v_add_u32_e32 v125, -16, v125
	v_cvt_f32_i32_e32 v125, v125
	s_cmp_gt_i32 s77, s69
	s_cselect_b64 s[6:7], -1, 0
	v_mov_b32_e32 v124, v1
	v_mov_b32_e32 v209, v203
	s_and_b64 s[0:1], s[0:1], s[6:7]
	v_fma_f32 v210, v160, v126, 0
	v_add_u32_e32 v215, 0, v124
	v_fma_f32 v214, v160, v125, 0
	s_nop 0
	ds_read_b128 v[124:127], v215
	v_fma_f32 v128, 0, v160, v210
	v_add_f32_e32 v129, v160, v210
	v_pk_fma_f32 v[130:131], v[162:163], v[228:229], v[210:211] op_sel_hi:[1,1,0]
	v_fma_f32 v132, 0, v160, v214
	v_add_f32_e32 v133, v160, v214
	v_pk_fma_f32 v[134:135], v[162:163], v[228:229], v[214:215] op_sel_hi:[1,1,0]
	s_waitcnt lgkmcnt(0)
	v_mfma_f32_16x16x32_bf16 v[128:131], v[124:127], v[4:7], v[128:131]
	v_mfma_f32_16x16x32_bf16 v[124:127], v[124:127], v[12:15], v[132:135]
	s_nop 2
	ds_read_b128 v[132:135], v215 offset:64
	s_waitcnt lgkmcnt(0)
	v_mfma_f32_16x16x32_bf16 v[136:139], v[132:135], v[8:11], v[128:131]
	v_mfma_f32_16x16x32_bf16 v[124:127], v[132:135], v[16:19], v[124:127]
	s_nop 1
	ds_read_b128 v[128:131], v215 offset:2304
	v_mov_b32_e32 v161, v160
	v_pk_fma_f32 v[132:133], v[164:165], v[232:233], v[210:211] op_sel_hi:[1,1,0]
	v_pk_fma_f32 v[134:135], v[160:161], v[236:237], v[210:211] op_sel_hi:[1,1,0]
	v_pk_fma_f32 v[140:141], v[164:165], v[232:233], v[214:215] op_sel_hi:[1,1,0]
	v_pk_fma_f32 v[142:143], v[160:161], v[236:237], v[214:215] op_sel_hi:[1,1,0]
	s_waitcnt lgkmcnt(0)
	v_mfma_f32_16x16x32_bf16 v[132:135], v[128:131], v[4:7], v[132:135]
	v_mfma_f32_16x16x32_bf16 v[128:131], v[128:131], v[12:15], v[140:143]
	s_nop 2
	ds_read_b128 v[140:143], v215 offset:2368
	s_waitcnt lgkmcnt(0)
	v_mfma_f32_16x16x32_bf16 v[144:147], v[140:143], v[8:11], v[132:135]
	v_mfma_f32_16x16x32_bf16 v[128:131], v[140:143], v[16:19], v[128:131]
	s_nop 1
	ds_read_b128 v[132:135], v215 offset:4608
	ds_read_b128 v[152:155], v215 offset:4672
	v_pk_fma_f32 v[142:143], v[160:161], v[238:239], v[210:211] op_sel_hi:[1,1,0]
	v_pk_fma_f32 v[140:141], v[164:165], v[240:241], v[210:211] op_sel_hi:[1,1,0]
	v_pk_fma_f32 v[150:151], v[160:161], v[238:239], v[214:215] op_sel_hi:[1,1,0]
	v_pk_fma_f32 v[148:149], v[164:165], v[240:241], v[214:215] op_sel_hi:[1,1,0]
	s_waitcnt lgkmcnt(1)
	v_mfma_f32_16x16x32_bf16 v[140:143], v[132:135], v[4:7], v[140:143]
	v_mfma_f32_16x16x32_bf16 v[132:135], v[132:135], v[12:15], v[148:151]
	s_waitcnt lgkmcnt(0)
	v_mfma_f32_16x16x32_bf16 v[148:151], v[152:155], v[8:11], v[140:143]
	v_mfma_f32_16x16x32_bf16 v[132:135], v[152:155], v[16:19], v[132:135]
	s_nop 3
	ds_read_b128 v[140:143], v215 offset:6912
	v_pk_fma_f32 v[154:155], v[160:161], v[242:243], v[210:211] op_sel_hi:[1,1,0]
	v_pk_fma_f32 v[152:153], v[164:165], v[244:245], v[210:211] op_sel_hi:[1,1,0]
	v_pk_fma_f32 v[212:213], v[160:161], v[242:243], v[214:215] op_sel_hi:[1,1,0]
	v_pk_fma_f32 v[210:211], v[164:165], v[244:245], v[214:215] op_sel_hi:[1,1,0]
	s_waitcnt lgkmcnt(0)
	v_mfma_f32_16x16x32_bf16 v[152:155], v[140:143], v[4:7], v[152:155]
	v_mfma_f32_16x16x32_bf16 v[140:143], v[140:143], v[12:15], v[210:213]
	s_nop 2
	ds_read_b128 v[210:213], v215 offset:6976
	s_waitcnt lgkmcnt(0)
	v_mfma_f32_16x16x32_bf16 v[152:155], v[210:213], v[8:11], v[152:155]
	v_mfma_f32_16x16x32_bf16 v[140:143], v[210:213], v[16:19], v[140:143]
	s_nop 0
	s_and_b64 vcc, exec, s[0:1]
	s_cbranch_vccnz .LBB0_1115
	v_add_u32_e32 v161, 51, v3
	v_cmp_gt_u32_e32 vcc, s35, v161
	v_add_u32_e32 v161, 50, v3
	v_cmp_gt_u32_e64 s[0:1], s35, v161
	v_add_u32_e32 v161, 49, v3
	v_cmp_gt_u32_e64 s[6:7], s35, v161
	v_add_u32_e32 v161, 48, v3
	v_cmp_gt_u32_e64 s[8:9], s35, v161
	v_add_u32_e32 v161, 35, v3
	v_cmp_gt_u32_e64 s[10:11], s35, v161
	v_add_u32_e32 v161, 34, v3
	v_cmp_gt_u32_e64 s[12:13], s35, v161
	v_add_u32_e32 v161, 33, v3
	v_cmp_gt_u32_e64 s[14:15], s35, v161
	v_add_u32_e32 v161, 32, v3
	v_cmp_gt_u32_e64 s[16:17], s35, v161
	v_add_u32_e32 v161, 19, v3
	v_cmp_gt_u32_e64 s[18:19], s35, v161
	v_add_u32_e32 v161, 18, v3
	v_cmp_gt_u32_e64 s[22:23], s35, v161
	v_add_u32_e32 v161, 17, v3
	v_cmp_gt_u32_e64 s[24:25], s35, v161
	v_add_u32_e32 v161, 16, v3
	v_cmp_gt_u32_e64 s[26:27], s35, v161
	v_add_u32_e32 v161, 3, v3
	v_cmp_gt_u32_e64 s[28:29], s35, v161
	v_add_u32_e32 v161, 2, v3
	v_cndmask_b32_e32 v136, v194, v136, vcc
	v_cndmask_b32_e64 v152, v194, v152, s[28:29]
	v_cmp_gt_u32_e64 s[28:29], s35, v161
	v_add_u32_e32 v161, 1, v3
	v_cndmask_b32_e64 v137, v194, v137, s[0:1]
	v_cndmask_b32_e64 v153, v194, v153, s[28:29]
	v_cmp_gt_u32_e64 s[28:29], s35, v161
	v_add_u32_e32 v161, 0x43, v3
	v_cndmask_b32_e64 v138, v194, v138, s[6:7]
	v_cndmask_b32_e64 v154, v194, v154, s[28:29]
	v_cmp_gt_u32_e64 s[28:29], s35, v3
	v_cndmask_b32_e64 v139, v194, v139, s[8:9]
	v_cndmask_b32_e64 v144, v194, v144, s[10:11]
	v_cndmask_b32_e64 v155, v194, v155, s[28:29]
	v_cmp_gt_u32_e64 s[28:29], s35, v161
	v_add_u32_e32 v161, 0x42, v3
	v_cndmask_b32_e64 v145, v194, v145, s[12:13]
	v_cndmask_b32_e64 v124, v194, v124, s[28:29]
	v_cmp_gt_u32_e64 s[28:29], s35, v161
	v_add_u32_e32 v161, 0x41, v3
	v_cndmask_b32_e64 v146, v194, v146, s[14:15]
	v_cndmask_b32_e64 v125, v194, v125, s[28:29]
	v_cmp_gt_u32_e64 s[28:29], s35, v161
	v_add_u32_e32 v161, 64, v3
	v_cndmask_b32_e64 v147, v194, v147, s[16:17]
	v_cndmask_b32_e64 v126, v194, v126, s[28:29]
	v_cmp_gt_u32_e64 s[28:29], s35, v161
	v_cndmask_b32_e64 v148, v194, v148, s[18:19]
	v_cndmask_b32_e64 v149, v194, v149, s[22:23]
	v_cndmask_b32_e64 v150, v194, v150, s[24:25]
	v_cndmask_b32_e64 v151, v194, v151, s[26:27]
	v_cndmask_b32_e64 v127, v194, v127, s[28:29]
	v_cndmask_b32_e32 v128, v194, v128, vcc
	v_cndmask_b32_e64 v129, v194, v129, s[0:1]
	v_cndmask_b32_e64 v130, v194, v130, s[6:7]
	v_cndmask_b32_e64 v131, v194, v131, s[8:9]
	v_cndmask_b32_e64 v132, v194, v132, s[10:11]
	v_cndmask_b32_e64 v133, v194, v133, s[12:13]
	v_cndmask_b32_e64 v134, v194, v134, s[14:15]
	v_cndmask_b32_e64 v135, v194, v135, s[16:17]
	v_cndmask_b32_e64 v140, v194, v140, s[18:19]
	v_cndmask_b32_e64 v141, v194, v141, s[22:23]
	v_cndmask_b32_e64 v142, v194, v142, s[24:25]
	v_cndmask_b32_e64 v143, v194, v143, s[26:27]
	s_branch .LBB0_1115
